# GEMM mainloops: loop counter/pointer SALU and exit compare moved in front of the loop-back s_barrier (loop-edge edit)
# baseline (speedup 1.0000x reference)
; #define PG8_STAGE(bufoff, gbase, voff) do { _Pragma("unroll") for (int _i = 0; _i < 2; ++_i) \
;         __builtin_amdgcn_global_load_lds((const unsigned*)((const char*)(gbase) + (voff)[_i]), (LAS unsigned*)(lds + (bufoff) + ldsw + _i * 8192), 16, 0, 0); } while (0)
; #define PG8_LDA(dst, b, h) do { _Pragma("unroll") for (int m = 0; m < 4; ++m) _Pragma("unroll") for (int k = 0; k < 2; ++k) dst[m][k] = *(const LAS bf16x8*)(lds + PG8_SA(b, h) + aoff + m * 2048 + k * 1024); } while (0)
; #define PG8_LDB(dst, b, h) do { _Pragma("unroll") for (int n = 0; n < 2; ++n) _Pragma("unroll") for (int k = 0; k < 2; ++k) dst[n][k] = *(const LAS bf16x8*)(lds + PG8_SB(b, h) + boff + n * 2048 + k * 1024); } while (0)
; #define PG8_MMA(ai, bj, At, Bt) do { __builtin_amdgcn_s_setprio(1); _Pragma("unroll") for (int m = 0; m < 4; ++m) _Pragma("unroll") for (int n = 0; n < 2; ++n) _Pragma("unroll") for (int k = 0; k < 2; ++k) \
;         acc[ai][bj][m][n] = __builtin_amdgcn_mfma_f32_16x16x32_bf16(Bt[n][k], At[m][k], acc[ai][bj][m][n], 0, 0, 0); __builtin_amdgcn_s_setprio(0); } while (0)
; #define PG8_WAIT_V(n) asm volatile("s_waitcnt vmcnt(" #n ")" ::: "memory")
; #define PG8_WAIT_L(n) asm volatile("s_waitcnt lgkmcnt(" #n ")" ::: "memory")
; #define PG8_BAR __builtin_amdgcn_s_barrier()
; #define PG8_SCHED __builtin_amdgcn_sched_barrier(0)
; template <class Epi, class Sched>
; __device__ __forceinline__ void gemm_phase(LAS unsigned char* lds, const Gemm g, const Sched& S, const Epi& E, int wid) {
;     ...
;             PG8_LDB(B0, 0, 0); PG8_LDB(B1, 0, 1); PG8_SCHED; PG8_LDA(At, 0, 0); PG8_STAGE(PG8_SA(1, 1), a1 + hstep, voffA);
;             PG8_WAIT_V(8); PG8_WAIT_L(0); PG8_BAR; PG8_MMA(0, 0, At, B0); PG8_MMA(0, 1, At, B1); PG8_BAR; PG8_SCHED;
;             PG8_LDA(At, 0, 1); PG8_STAGE(PG8_SB(0, 0), b2, voffB); PG8_STAGE(PG8_SB(0, 1), b2 + hstep, voffB); PG8_STAGE(PG8_SA(0, 0), a2, voffA);
;             PG8_WAIT_V(8); PG8_WAIT_L(0); PG8_BAR; PG8_MMA(1, 0, At, B0); PG8_MMA(1, 1, At, B1); PG8_BAR; PG8_SCHED;
.LBB0_197:
	ds_read_b128 v[148:151], v145
	ds_read_b128 v[152:155], v145 offset:1024
	ds_read_b128 v[156:159], v145 offset:2048
	ds_read_b128 v[160:163], v145 offset:3072
	ds_read_b128 v[168:171], v146
	ds_read_b128 v[172:175], v146 offset:1024
	ds_read_b128 v[176:179], v146 offset:2048
	ds_read_b128 v[180:183], v146 offset:3072
	s_add_u32 s34, s30, 0xfffc0080
	s_addc_u32 s35, s31, -1
	s_cmp_eq_u32 s57, 12
	s_cselect_b32 s37, s21, s35
	s_cselect_b32 s36, s27, s34
	s_cselect_b32 s35, s19, s56
	s_cselect_b32 s34, s54, s55
	v_lshl_add_u64 v[140:141], s[30:31], 0, v[136:137]
	s_add_i32 m0, s29, 0xc000
	ds_read_b128 v[184:187], v147
	ds_read_b128 v[188:191], v147 offset:1024
	ds_read_b128 v[192:195], v147 offset:2048
	ds_read_b128 v[196:199], v147 offset:3072
	ds_read_b128 v[200:203], v147 offset:4096
	ds_read_b128 v[204:207], v147 offset:5120
	ds_read_b128 v[208:211], v147 offset:6144
	ds_read_b128 v[212:215], v147 offset:7168
	global_load_lds_dwordx4 v[140:141], off
	v_lshl_add_u64 v[140:141], s[30:31], 0, v[138:139]
	s_add_i32 m0, s29, 0xe000
	s_nop 0
	global_load_lds_dwordx4 v[140:141], off
	s_waitcnt vmcnt(8)
	s_waitcnt lgkmcnt(0)
	s_barrier
	s_setprio 1
	s_waitcnt lgkmcnt(0)
	v_mfma_f32_16x16x32_bf16 v[124:127], v[148:151], v[184:187], v[124:127]
	v_mfma_f32_16x16x32_bf16 v[120:123], v[156:159], v[184:187], v[120:123]
	v_mfma_f32_16x16x32_bf16 v[108:111], v[148:151], v[192:195], v[108:111]
	v_mfma_f32_16x16x32_bf16 v[104:107], v[156:159], v[192:195], v[104:107]
	v_mfma_f32_16x16x32_bf16 v[92:95], v[148:151], v[200:203], v[92:95]
	v_mfma_f32_16x16x32_bf16 v[88:91], v[156:159], v[200:203], v[88:91]
	v_mfma_f32_16x16x32_bf16 v[76:79], v[148:151], v[208:211], v[76:79]
	v_mfma_f32_16x16x32_bf16 v[72:75], v[156:159], v[208:211], v[72:75]
	v_mfma_f32_16x16x32_bf16 v[124:127], v[152:155], v[188:191], v[124:127]
	v_mfma_f32_16x16x32_bf16 v[120:123], v[160:163], v[188:191], v[120:123]
	v_mfma_f32_16x16x32_bf16 v[108:111], v[152:155], v[196:199], v[108:111]
	v_mfma_f32_16x16x32_bf16 v[104:107], v[160:163], v[196:199], v[104:107]
	v_mfma_f32_16x16x32_bf16 v[92:95], v[152:155], v[204:207], v[92:95]
	v_mfma_f32_16x16x32_bf16 v[88:91], v[160:163], v[204:207], v[88:91]
	v_mfma_f32_16x16x32_bf16 v[76:79], v[152:155], v[212:215], v[76:79]
	v_mfma_f32_16x16x32_bf16 v[72:75], v[160:163], v[212:215], v[72:75]
	s_setprio 0
	s_setprio 1
	v_mfma_f32_16x16x32_bf16 v[116:119], v[168:171], v[184:187], v[116:119]
	v_mfma_f32_16x16x32_bf16 v[112:115], v[176:179], v[184:187], v[112:115]
	v_mfma_f32_16x16x32_bf16 v[100:103], v[168:171], v[192:195], v[100:103]
	v_mfma_f32_16x16x32_bf16 v[96:99], v[176:179], v[192:195], v[96:99]
	v_mfma_f32_16x16x32_bf16 v[84:87], v[168:171], v[200:203], v[84:87]
	v_mfma_f32_16x16x32_bf16 v[80:83], v[176:179], v[200:203], v[80:83]
	v_mfma_f32_16x16x32_bf16 v[68:71], v[168:171], v[208:211], v[68:71]
	v_mfma_f32_16x16x32_bf16 v[64:67], v[176:179], v[208:211], v[64:67]
	v_mfma_f32_16x16x32_bf16 v[116:119], v[172:175], v[188:191], v[116:119]
	v_mfma_f32_16x16x32_bf16 v[112:115], v[180:183], v[188:191], v[112:115]
	v_mfma_f32_16x16x32_bf16 v[100:103], v[172:175], v[196:199], v[100:103]
	v_mfma_f32_16x16x32_bf16 v[96:99], v[180:183], v[196:199], v[96:99]
	v_mfma_f32_16x16x32_bf16 v[84:87], v[172:175], v[204:207], v[84:87]
	v_mfma_f32_16x16x32_bf16 v[80:83], v[180:183], v[204:207], v[80:83]
	v_mfma_f32_16x16x32_bf16 v[68:71], v[172:175], v[212:215], v[68:71]
	v_mfma_f32_16x16x32_bf16 v[64:67], v[180:183], v[212:215], v[64:67]
	s_setprio 0
	s_barrier
	s_add_i32 s58, s50, s75
	v_lshl_add_u64 v[140:141], s[34:35], 0, v[130:131]
	s_mov_b32 m0, s58
	ds_read_b128 v[184:187], v147 offset:16384
	ds_read_b128 v[188:191], v147 offset:17408
	global_load_lds_dwordx4 v[140:141], off
	s_add_i32 m0, s58, 0x2000
	s_add_u32 s58, s34, 0x40000
	v_lshl_add_u64 v[164:165], s[34:35], 0, v[134:135]
	s_addc_u32 s59, s35, 0
	s_add_i32 s60, s51, s75
	global_load_lds_dwordx4 v[164:165], off
	v_lshl_add_u64 v[216:217], s[58:59], 0, v[130:131]
	s_mov_b32 m0, s60
	v_lshl_add_u64 v[218:219], s[36:37], 0, v[132:133]
	global_load_lds_dwordx4 v[216:217], off
	v_lshl_add_u64 v[216:217], s[58:59], 0, v[134:135]
	s_add_i32 m0, s60, 0x2000
	s_nop 0
	global_load_lds_dwordx4 v[216:217], off
	v_lshl_add_u64 v[216:217], s[36:37], 0, v[128:129]
	s_mov_b32 m0, s29
	s_nop 0
	global_load_lds_dwordx4 v[216:217], off
	s_mov_b32 m0, s41
	s_nop 0
	global_load_lds_dwordx4 v[218:219], off
	s_waitcnt vmcnt(8)
	s_waitcnt lgkmcnt(0)
	s_barrier
	s_setprio 1
	s_waitcnt lgkmcnt(0)
	v_mfma_f32_16x16x32_bf16 v[60:63], v[148:151], v[184:187], v[60:63]
	v_mfma_f32_16x16x32_bf16 v[56:59], v[156:159], v[184:187], v[56:59]
	v_mfma_f32_16x16x32_bf16 v[60:63], v[152:155], v[188:191], v[60:63]
	v_mfma_f32_16x16x32_bf16 v[56:59], v[160:163], v[188:191], v[56:59]
	s_setprio 0
	s_setprio 1
	v_mfma_f32_16x16x32_bf16 v[52:55], v[168:171], v[184:187], v[52:55]
	v_mfma_f32_16x16x32_bf16 v[48:51], v[176:179], v[184:187], v[48:51]
	v_mfma_f32_16x16x32_bf16 v[52:55], v[172:175], v[188:191], v[52:55]
	v_mfma_f32_16x16x32_bf16 v[48:51], v[180:183], v[188:191], v[48:51]
	s_setprio 0
	s_barrier
; #define PG8_STAGE(bufoff, gbase, voff) do { _Pragma("unroll") for (int _i = 0; _i < 2; ++_i) \
;         __builtin_amdgcn_global_load_lds((const unsigned*)((const char*)(gbase) + (voff)[_i]), (LAS unsigned*)(lds + (bufoff) + ldsw + _i * 8192), 16, 0, 0); } while (0)
; #define PG8_LDA(dst, b, h) do { _Pragma("unroll") for (int m = 0; m < 4; ++m) _Pragma("unroll") for (int k = 0; k < 2; ++k) dst[m][k] = *(const LAS bf16x8*)(lds + PG8_SA(b, h) + aoff + m * 2048 + k * 1024); } while (0)
; #define PG8_LDB(dst, b, h) do { _Pragma("unroll") for (int n = 0; n < 2; ++n) _Pragma("unroll") for (int k = 0; k < 2; ++k) dst[n][k] = *(const LAS bf16x8*)(lds + PG8_SB(b, h) + boff + n * 2048 + k * 1024); } while (0)
; #define PG8_MMA(ai, bj, At, Bt) do { __builtin_amdgcn_s_setprio(1); _Pragma("unroll") for (int m = 0; m < 4; ++m) _Pragma("unroll") for (int n = 0; n < 2; ++n) _Pragma("unroll") for (int k = 0; k < 2; ++k) \
;         acc[ai][bj][m][n] = __builtin_amdgcn_mfma_f32_16x16x32_bf16(Bt[n][k], At[m][k], acc[ai][bj][m][n], 0, 0, 0); __builtin_amdgcn_s_setprio(0); } while (0)
; #define PG8_WAIT_V(n) asm volatile("s_waitcnt vmcnt(" #n ")" ::: "memory")
; #define PG8_WAIT_L(n) asm volatile("s_waitcnt lgkmcnt(" #n ")" ::: "memory")
; #define PG8_BAR __builtin_amdgcn_s_barrier()
; #define PG8_SCHED __builtin_amdgcn_sched_barrier(0)
; template <class Epi, class Sched>
; __device__ __forceinline__ void gemm_phase(LAS unsigned char* lds, const Gemm g, const Sched& S, const Epi& E, int wid) {
;     ...
;             PG8_LDB(B0, 1, 0); PG8_LDB(B1, 1, 1); PG8_SCHED; PG8_LDA(At, 1, 0); PG8_STAGE(PG8_SA(0, 1), a2 + hstep, voffA);
;             PG8_WAIT_V(8); PG8_WAIT_L(0); PG8_BAR; PG8_MMA(0, 0, At, B0); PG8_MMA(0, 1, At, B1); PG8_BAR; PG8_SCHED;
;             PG8_LDA(At, 1, 1); PG8_STAGE(PG8_SB(1, 0), b3, voffB); PG8_STAGE(PG8_SB(1, 1), b3 + hstep, voffB); PG8_STAGE(PG8_SA(1, 0), a3, voffA);
;             PG8_WAIT_V(8); PG8_WAIT_L(0); PG8_BAR; PG8_MMA(1, 0, At, B0); PG8_MMA(1, 1, At, B1); PG8_BAR; PG8_SCHED;
;         }
	s_add_i32 s58, 0, 0x18000
	s_add_i32 s59, 0, 0x1c000
	v_add_u32_e32 v160, s58, v143
	v_add_u32_e32 v180, s59, v143
	ds_read_b128 v[148:151], v160
	ds_read_b128 v[152:155], v160 offset:1024
	ds_read_b128 v[156:159], v160 offset:2048
	ds_read_b128 v[160:163], v160 offset:3072
	ds_read_b128 v[168:171], v180
	ds_read_b128 v[172:175], v180 offset:1024
	ds_read_b128 v[176:179], v180 offset:2048
	ds_read_b128 v[180:183], v180 offset:3072
	s_add_u32 s36, s36, 0x40000
	s_addc_u32 s37, s37, 0
	s_mov_b32 m0, s42
	v_lshl_add_u64 v[220:221], s[36:37], 0, v[128:129]
	ds_read_b128 v[184:187], v147 offset:32768
	ds_read_b128 v[188:191], v147 offset:33792
	ds_read_b128 v[192:195], v147 offset:34816
	ds_read_b128 v[196:199], v147 offset:35840
	ds_read_b128 v[200:203], v147 offset:36864
	ds_read_b128 v[204:207], v147 offset:37888
	ds_read_b128 v[208:211], v147 offset:38912
	ds_read_b128 v[212:215], v147 offset:39936
	global_load_lds_dwordx4 v[220:221], off
	v_lshl_add_u64 v[220:221], s[36:37], 0, v[132:133]
	s_mov_b32 m0, s43
	s_nop 0
	global_load_lds_dwordx4 v[220:221], off
	s_waitcnt vmcnt(8)
	s_waitcnt lgkmcnt(0)
	s_barrier
	s_setprio 1
	s_waitcnt lgkmcnt(0)
	v_mfma_f32_16x16x32_bf16 v[124:127], v[148:151], v[184:187], v[124:127]
	v_mfma_f32_16x16x32_bf16 v[120:123], v[156:159], v[184:187], v[120:123]
	v_mfma_f32_16x16x32_bf16 v[108:111], v[148:151], v[192:195], v[108:111]
	v_mfma_f32_16x16x32_bf16 v[104:107], v[156:159], v[192:195], v[104:107]
	v_mfma_f32_16x16x32_bf16 v[92:95], v[148:151], v[200:203], v[92:95]
	v_mfma_f32_16x16x32_bf16 v[88:91], v[156:159], v[200:203], v[88:91]
	v_mfma_f32_16x16x32_bf16 v[76:79], v[148:151], v[208:211], v[76:79]
	v_mfma_f32_16x16x32_bf16 v[72:75], v[156:159], v[208:211], v[72:75]
	v_mfma_f32_16x16x32_bf16 v[124:127], v[152:155], v[188:191], v[124:127]
	v_mfma_f32_16x16x32_bf16 v[120:123], v[160:163], v[188:191], v[120:123]
	v_mfma_f32_16x16x32_bf16 v[108:111], v[152:155], v[196:199], v[108:111]
	v_mfma_f32_16x16x32_bf16 v[104:107], v[160:163], v[196:199], v[104:107]
	v_mfma_f32_16x16x32_bf16 v[92:95], v[152:155], v[204:207], v[92:95]
	v_mfma_f32_16x16x32_bf16 v[88:91], v[160:163], v[204:207], v[88:91]
	v_mfma_f32_16x16x32_bf16 v[76:79], v[152:155], v[212:215], v[76:79]
	v_mfma_f32_16x16x32_bf16 v[72:75], v[160:163], v[212:215], v[72:75]
	s_setprio 0
	s_setprio 1
	v_mfma_f32_16x16x32_bf16 v[116:119], v[168:171], v[184:187], v[116:119]
	v_mfma_f32_16x16x32_bf16 v[112:115], v[176:179], v[184:187], v[112:115]
	v_mfma_f32_16x16x32_bf16 v[100:103], v[168:171], v[192:195], v[100:103]
	v_mfma_f32_16x16x32_bf16 v[96:99], v[176:179], v[192:195], v[96:99]
	v_mfma_f32_16x16x32_bf16 v[84:87], v[168:171], v[200:203], v[84:87]
	v_mfma_f32_16x16x32_bf16 v[80:83], v[176:179], v[200:203], v[80:83]
	v_mfma_f32_16x16x32_bf16 v[68:71], v[168:171], v[208:211], v[68:71]
	v_mfma_f32_16x16x32_bf16 v[64:67], v[176:179], v[208:211], v[64:67]
	v_mfma_f32_16x16x32_bf16 v[116:119], v[172:175], v[188:191], v[116:119]
	v_mfma_f32_16x16x32_bf16 v[112:115], v[180:183], v[188:191], v[112:115]
	v_mfma_f32_16x16x32_bf16 v[100:103], v[172:175], v[196:199], v[100:103]
	v_mfma_f32_16x16x32_bf16 v[96:99], v[180:183], v[196:199], v[96:99]
	v_mfma_f32_16x16x32_bf16 v[84:87], v[172:175], v[204:207], v[84:87]
	v_mfma_f32_16x16x32_bf16 v[80:83], v[180:183], v[204:207], v[80:83]
	v_mfma_f32_16x16x32_bf16 v[68:71], v[172:175], v[212:215], v[68:71]
	v_mfma_f32_16x16x32_bf16 v[64:67], v[180:183], v[212:215], v[64:67]
	s_setprio 0
	s_barrier
	s_add_i32 s36, s58, s75
	v_lshl_add_u64 v[140:141], v[140:141], 0, s[10:11]
	s_mov_b32 m0, s36
	ds_read_b128 v[184:187], v147 offset:49152
	ds_read_b128 v[188:191], v147 offset:50176
	global_load_lds_dwordx4 v[140:141], off
	s_add_i32 m0, s36, 0x2000
	s_add_u32 s34, s34, 0x40080
	v_lshl_add_u64 v[140:141], v[164:165], 0, s[10:11]
	s_addc_u32 s35, s35, 0
	s_add_i32 s36, s59, s75
	global_load_lds_dwordx4 v[140:141], off
	v_lshl_add_u64 v[140:141], s[34:35], 0, v[130:131]
	s_mov_b32 m0, s36
	s_nop 0
	global_load_lds_dwordx4 v[140:141], off
	v_lshl_add_u64 v[140:141], s[34:35], 0, v[134:135]
	s_add_i32 m0, s36, 0x2000
	s_nop 0
	global_load_lds_dwordx4 v[140:141], off
	v_lshl_add_u64 v[140:141], v[216:217], 0, s[10:11]
	s_mov_b32 m0, s45
	s_nop 0
	global_load_lds_dwordx4 v[140:141], off
	v_lshl_add_u64 v[140:141], v[218:219], 0, s[10:11]
	s_mov_b32 m0, s46
	s_nop 0
	global_load_lds_dwordx4 v[140:141], off
	s_waitcnt vmcnt(8)
	s_waitcnt lgkmcnt(0)
	s_barrier
	s_setprio 1
	s_waitcnt lgkmcnt(0)
	v_mfma_f32_16x16x32_bf16 v[60:63], v[148:151], v[184:187], v[60:63]
	v_mfma_f32_16x16x32_bf16 v[56:59], v[156:159], v[184:187], v[56:59]
	v_mfma_f32_16x16x32_bf16 v[60:63], v[152:155], v[188:191], v[60:63]
	v_mfma_f32_16x16x32_bf16 v[56:59], v[160:163], v[188:191], v[56:59]
	s_setprio 0
	s_setprio 1
	v_mfma_f32_16x16x32_bf16 v[52:55], v[168:171], v[184:187], v[52:55]
	v_mfma_f32_16x16x32_bf16 v[48:51], v[176:179], v[184:187], v[48:51]
	v_mfma_f32_16x16x32_bf16 v[52:55], v[172:175], v[188:191], v[52:55]
	v_mfma_f32_16x16x32_bf16 v[48:51], v[180:183], v[188:191], v[48:51]
	s_setprio 0
	s_add_i32 s57, s57, 2
	s_add_u32 s30, s30, 0x100
	s_addc_u32 s31, s31, 0
	s_add_u32 s55, s55, 0x100
	s_addc_u32 s56, s56, 0
	s_cmp_gt_u32 s57, 13
	s_barrier
	s_cbranch_scc0 .LBB0_197
	s_and_b64 vcc, exec, s[14:15]
	s_cbranch_vccz .LBB0_200
	s_barrier

; #define PG8_STAGE(bufoff, gbase, voff) do { _Pragma("unroll") for (int _i = 0; _i < 2; ++_i) \
;         __builtin_amdgcn_global_load_lds((const unsigned*)((const char*)(gbase) + (voff)[_i]), (LAS unsigned*)(lds + (bufoff) + ldsw + _i * 8192), 16, 0, 0); } while (0)
; #define PG8_LDA(dst, b, h) do { _Pragma("unroll") for (int m = 0; m < 4; ++m) _Pragma("unroll") for (int k = 0; k < 2; ++k) dst[m][k] = *(const LAS bf16x8*)(lds + PG8_SA(b, h) + aoff + m * 2048 + k * 1024); } while (0)
; #define PG8_LDB(dst, b, h) do { _Pragma("unroll") for (int n = 0; n < 2; ++n) _Pragma("unroll") for (int k = 0; k < 2; ++k) dst[n][k] = *(const LAS bf16x8*)(lds + PG8_SB(b, h) + boff + n * 2048 + k * 1024); } while (0)
; #define PG8_MMA(ai, bj, At, Bt) do { __builtin_amdgcn_s_setprio(1); _Pragma("unroll") for (int m = 0; m < 4; ++m) _Pragma("unroll") for (int n = 0; n < 2; ++n) _Pragma("unroll") for (int k = 0; k < 2; ++k) \
;         acc[ai][bj][m][n] = __builtin_amdgcn_mfma_f32_16x16x32_bf16(Bt[n][k], At[m][k], acc[ai][bj][m][n], 0, 0, 0); __builtin_amdgcn_s_setprio(0); } while (0)
; #define PG8_WAIT_V(n) asm volatile("s_waitcnt vmcnt(" #n ")" ::: "memory")
; #define PG8_WAIT_L(n) asm volatile("s_waitcnt lgkmcnt(" #n ")" ::: "memory")
; #define PG8_BAR __builtin_amdgcn_s_barrier()
; #define PG8_SCHED __builtin_amdgcn_sched_barrier(0)
; template <class Epi, class Sched>
; __device__ __forceinline__ void gemm_phase(LAS unsigned char* lds, const Gemm g, const Sched& S, const Epi& E, int wid) {
;     ...
;             PG8_LDB(B0, 0, 0); PG8_LDB(B1, 0, 1); PG8_SCHED; PG8_LDA(At, 0, 0); PG8_STAGE(PG8_SA(1, 1), a1 + hstep, voffA);
;             PG8_WAIT_V(8); PG8_WAIT_L(0); PG8_BAR; PG8_MMA(0, 0, At, B0); PG8_MMA(0, 1, At, B1); PG8_BAR; PG8_SCHED;
;             PG8_LDA(At, 0, 1); PG8_STAGE(PG8_SB(0, 0), b2, voffB); PG8_STAGE(PG8_SB(0, 1), b2 + hstep, voffB); PG8_STAGE(PG8_SA(0, 0), a2, voffA);
;             PG8_WAIT_V(8); PG8_WAIT_L(0); PG8_BAR; PG8_MMA(1, 0, At, B0); PG8_MMA(1, 1, At, B1); PG8_BAR; PG8_SCHED;
.LBB0_475:
	ds_read_b128 v[152:155], v148
	ds_read_b128 v[156:159], v148 offset:1024
	ds_read_b128 v[160:163], v148 offset:2048
	ds_read_b128 v[168:171], v148 offset:3072
	ds_read_b128 v[172:175], v149
	ds_read_b128 v[176:179], v149 offset:1024
	ds_read_b128 v[180:183], v149 offset:2048
	ds_read_b128 v[184:187], v149 offset:3072
	s_add_u32 s26, s24, 0xfffc0080
	s_addc_u32 s27, s25, -1
	s_cmp_eq_u32 s51, 12
	s_cselect_b32 s29, s17, s27
	s_cselect_b32 s28, s23, s26
	s_cselect_b32 s27, s15, s50
	s_cselect_b32 s26, s48, s49
	v_lshl_add_u64 v[164:165], s[24:25], 0, v[138:139]
	s_add_i32 m0, s34, 0xc000
	ds_read_b128 v[188:191], v150
	ds_read_b128 v[192:195], v150 offset:1024
	ds_read_b128 v[196:199], v150 offset:2048
	ds_read_b128 v[200:203], v150 offset:3072
	ds_read_b128 v[204:207], v150 offset:4096
	ds_read_b128 v[208:211], v150 offset:5120
	ds_read_b128 v[212:215], v150 offset:6144
	ds_read_b128 v[216:219], v150 offset:7168
	global_load_lds_dwordx4 v[164:165], off
	v_lshl_add_u64 v[164:165], s[24:25], 0, v[140:141]
	s_add_i32 m0, s34, 0xe000
	s_nop 0
	global_load_lds_dwordx4 v[164:165], off
	s_waitcnt vmcnt(8)
	s_waitcnt lgkmcnt(0)
	s_barrier
	s_setprio 1
	s_waitcnt lgkmcnt(0)
	v_mfma_f32_16x16x32_bf16 v[124:127], v[152:155], v[188:191], v[124:127]
	v_mfma_f32_16x16x32_bf16 v[116:119], v[160:163], v[188:191], v[116:119]
	v_mfma_f32_16x16x32_bf16 v[108:111], v[152:155], v[196:199], v[108:111]
	v_mfma_f32_16x16x32_bf16 v[100:103], v[160:163], v[196:199], v[100:103]
	v_mfma_f32_16x16x32_bf16 v[92:95], v[152:155], v[204:207], v[92:95]
	v_mfma_f32_16x16x32_bf16 v[84:87], v[160:163], v[204:207], v[84:87]
	v_mfma_f32_16x16x32_bf16 v[76:79], v[152:155], v[212:215], v[76:79]
	v_mfma_f32_16x16x32_bf16 v[68:71], v[160:163], v[212:215], v[68:71]
	v_mfma_f32_16x16x32_bf16 v[124:127], v[156:159], v[192:195], v[124:127]
	v_mfma_f32_16x16x32_bf16 v[116:119], v[168:171], v[192:195], v[116:119]
	v_mfma_f32_16x16x32_bf16 v[108:111], v[156:159], v[200:203], v[108:111]
	v_mfma_f32_16x16x32_bf16 v[100:103], v[168:171], v[200:203], v[100:103]
	v_mfma_f32_16x16x32_bf16 v[92:95], v[156:159], v[208:211], v[92:95]
	v_mfma_f32_16x16x32_bf16 v[84:87], v[168:171], v[208:211], v[84:87]
	v_mfma_f32_16x16x32_bf16 v[76:79], v[156:159], v[216:219], v[76:79]
	v_mfma_f32_16x16x32_bf16 v[68:71], v[168:171], v[216:219], v[68:71]
	s_setprio 0
	s_setprio 1
	v_mfma_f32_16x16x32_bf16 v[120:123], v[172:175], v[188:191], v[120:123]
	v_mfma_f32_16x16x32_bf16 v[112:115], v[180:183], v[188:191], v[112:115]
	v_mfma_f32_16x16x32_bf16 v[104:107], v[172:175], v[196:199], v[104:107]
	v_mfma_f32_16x16x32_bf16 v[96:99], v[180:183], v[196:199], v[96:99]
	v_mfma_f32_16x16x32_bf16 v[88:91], v[172:175], v[204:207], v[88:91]
	v_mfma_f32_16x16x32_bf16 v[80:83], v[180:183], v[204:207], v[80:83]
	v_mfma_f32_16x16x32_bf16 v[72:75], v[172:175], v[212:215], v[72:75]
	v_mfma_f32_16x16x32_bf16 v[64:67], v[180:183], v[212:215], v[64:67]
	v_mfma_f32_16x16x32_bf16 v[120:123], v[176:179], v[192:195], v[120:123]
	v_mfma_f32_16x16x32_bf16 v[112:115], v[184:187], v[192:195], v[112:115]
	v_mfma_f32_16x16x32_bf16 v[104:107], v[176:179], v[200:203], v[104:107]
	v_mfma_f32_16x16x32_bf16 v[96:99], v[184:187], v[200:203], v[96:99]
	v_mfma_f32_16x16x32_bf16 v[88:91], v[176:179], v[208:211], v[88:91]
	v_mfma_f32_16x16x32_bf16 v[80:83], v[184:187], v[208:211], v[80:83]
	v_mfma_f32_16x16x32_bf16 v[72:75], v[176:179], v[216:219], v[72:75]
	v_mfma_f32_16x16x32_bf16 v[64:67], v[184:187], v[216:219], v[64:67]
	s_setprio 0
	s_barrier
	s_add_i32 s52, s43, s75
	v_lshl_add_u64 v[164:165], s[26:27], 0, v[130:131]
	s_mov_b32 m0, s52
	ds_read_b128 v[188:191], v150 offset:16384
	ds_read_b128 v[192:195], v150 offset:17408
	ds_read_b128 v[196:199], v150 offset:18432
	ds_read_b128 v[200:203], v150 offset:19456
	ds_read_b128 v[204:207], v150 offset:20480
	ds_read_b128 v[208:211], v150 offset:21504
	ds_read_b128 v[212:215], v150 offset:22528
	ds_read_b128 v[216:219], v150 offset:23552
	global_load_lds_dwordx4 v[164:165], off
	s_add_i32 m0, s52, 0x2000
	s_add_u32 s52, s26, 0x40000
	v_lshl_add_u64 v[220:221], s[26:27], 0, v[134:135]
	s_addc_u32 s53, s27, 0
	s_add_i32 s54, s44, s75
	global_load_lds_dwordx4 v[220:221], off
	v_lshl_add_u64 v[222:223], s[52:53], 0, v[130:131]
	s_mov_b32 m0, s54
	v_lshl_add_u64 v[224:225], s[28:29], 0, v[132:133]
	global_load_lds_dwordx4 v[222:223], off
	v_lshl_add_u64 v[222:223], s[52:53], 0, v[134:135]
	s_add_i32 m0, s54, 0x2000
	s_nop 0
	global_load_lds_dwordx4 v[222:223], off
	v_lshl_add_u64 v[222:223], s[28:29], 0, v[128:129]
	s_mov_b32 m0, s34
	s_nop 0
	global_load_lds_dwordx4 v[222:223], off
	s_mov_b32 m0, s35
	s_nop 0
	global_load_lds_dwordx4 v[224:225], off
	s_waitcnt vmcnt(8)
	s_waitcnt lgkmcnt(0)
	s_barrier
; #define PG8_STAGE(bufoff, gbase, voff) do { _Pragma("unroll") for (int _i = 0; _i < 2; ++_i) \
;         __builtin_amdgcn_global_load_lds((const unsigned*)((const char*)(gbase) + (voff)[_i]), (LAS unsigned*)(lds + (bufoff) + ldsw + _i * 8192), 16, 0, 0); } while (0)
; #define PG8_LDA(dst, b, h) do { _Pragma("unroll") for (int m = 0; m < 4; ++m) _Pragma("unroll") for (int k = 0; k < 2; ++k) dst[m][k] = *(const LAS bf16x8*)(lds + PG8_SA(b, h) + aoff + m * 2048 + k * 1024); } while (0)
; #define PG8_LDB(dst, b, h) do { _Pragma("unroll") for (int n = 0; n < 2; ++n) _Pragma("unroll") for (int k = 0; k < 2; ++k) dst[n][k] = *(const LAS bf16x8*)(lds + PG8_SB(b, h) + boff + n * 2048 + k * 1024); } while (0)
; #define PG8_MMA(ai, bj, At, Bt) do { __builtin_amdgcn_s_setprio(1); _Pragma("unroll") for (int m = 0; m < 4; ++m) _Pragma("unroll") for (int n = 0; n < 2; ++n) _Pragma("unroll") for (int k = 0; k < 2; ++k) \
;         acc[ai][bj][m][n] = __builtin_amdgcn_mfma_f32_16x16x32_bf16(Bt[n][k], At[m][k], acc[ai][bj][m][n], 0, 0, 0); __builtin_amdgcn_s_setprio(0); } while (0)
; #define PG8_WAIT_V(n) asm volatile("s_waitcnt vmcnt(" #n ")" ::: "memory")
; #define PG8_WAIT_L(n) asm volatile("s_waitcnt lgkmcnt(" #n ")" ::: "memory")
; #define PG8_BAR __builtin_amdgcn_s_barrier()
; #define PG8_SCHED __builtin_amdgcn_sched_barrier(0)
; template <class Epi, class Sched>
; __device__ __forceinline__ void gemm_phase(LAS unsigned char* lds, const Gemm g, const Sched& S, const Epi& E, int wid) {
;     ...
;             PG8_WAIT_V(8); PG8_WAIT_L(0); PG8_BAR; PG8_MMA(1, 0, At, B0); PG8_MMA(1, 1, At, B1); PG8_BAR; PG8_SCHED;
;             PG8_LDB(B0, 1, 0); PG8_LDB(B1, 1, 1); PG8_SCHED; PG8_LDA(At, 1, 0); PG8_STAGE(PG8_SA(0, 1), a2 + hstep, voffA);
;             PG8_WAIT_V(8); PG8_WAIT_L(0); PG8_BAR; PG8_MMA(0, 0, At, B0); PG8_MMA(0, 1, At, B1); PG8_BAR; PG8_SCHED;
	s_setprio 1
	s_waitcnt lgkmcnt(0)
	v_mfma_f32_16x16x32_bf16 v[60:63], v[152:155], v[188:191], v[60:63]
	v_mfma_f32_16x16x32_bf16 v[52:55], v[160:163], v[188:191], v[52:55]
	v_mfma_f32_16x16x32_bf16 v[44:47], v[152:155], v[196:199], v[44:47]
	v_mfma_f32_16x16x32_bf16 v[36:39], v[160:163], v[196:199], v[36:39]
	v_mfma_f32_16x16x32_bf16 v[28:31], v[152:155], v[204:207], v[28:31]
	v_mfma_f32_16x16x32_bf16 v[20:23], v[160:163], v[204:207], v[20:23]
	v_mfma_f32_16x16x32_bf16 v[12:15], v[152:155], v[212:215], v[12:15]
	v_mfma_f32_16x16x32_bf16 v[4:7], v[160:163], v[212:215], v[4:7]
	v_mfma_f32_16x16x32_bf16 v[60:63], v[156:159], v[192:195], v[60:63]
	v_mfma_f32_16x16x32_bf16 v[52:55], v[168:171], v[192:195], v[52:55]
	v_mfma_f32_16x16x32_bf16 v[44:47], v[156:159], v[200:203], v[44:47]
	v_mfma_f32_16x16x32_bf16 v[36:39], v[168:171], v[200:203], v[36:39]
	v_mfma_f32_16x16x32_bf16 v[28:31], v[156:159], v[208:211], v[28:31]
	v_mfma_f32_16x16x32_bf16 v[20:23], v[168:171], v[208:211], v[20:23]
	v_mfma_f32_16x16x32_bf16 v[12:15], v[156:159], v[216:219], v[12:15]
	v_mfma_f32_16x16x32_bf16 v[4:7], v[168:171], v[216:219], v[4:7]
	s_setprio 0
	s_setprio 1
	v_mfma_f32_16x16x32_bf16 v[56:59], v[172:175], v[188:191], v[56:59]
	v_mfma_f32_16x16x32_bf16 v[48:51], v[180:183], v[188:191], v[48:51]
	v_mfma_f32_16x16x32_bf16 v[40:43], v[172:175], v[196:199], v[40:43]
	v_mfma_f32_16x16x32_bf16 v[32:35], v[180:183], v[196:199], v[32:35]
	v_mfma_f32_16x16x32_bf16 v[24:27], v[172:175], v[204:207], v[24:27]
	v_mfma_f32_16x16x32_bf16 v[16:19], v[180:183], v[204:207], v[16:19]
	v_mfma_f32_16x16x32_bf16 v[8:11], v[172:175], v[212:215], v[8:11]
	v_mfma_f32_16x16x32_bf16 v[0:3], v[180:183], v[212:215], v[0:3]
	v_mfma_f32_16x16x32_bf16 v[56:59], v[176:179], v[192:195], v[56:59]
	v_mfma_f32_16x16x32_bf16 v[48:51], v[184:187], v[192:195], v[48:51]
	v_mfma_f32_16x16x32_bf16 v[40:43], v[176:179], v[200:203], v[40:43]
	v_mfma_f32_16x16x32_bf16 v[32:35], v[184:187], v[200:203], v[32:35]
	v_mfma_f32_16x16x32_bf16 v[24:27], v[176:179], v[208:211], v[24:27]
	v_mfma_f32_16x16x32_bf16 v[16:19], v[184:187], v[208:211], v[16:19]
	v_mfma_f32_16x16x32_bf16 v[8:11], v[176:179], v[216:219], v[8:11]
	v_mfma_f32_16x16x32_bf16 v[0:3], v[184:187], v[216:219], v[0:3]
	s_setprio 0
	s_barrier
	s_add_i32 s52, 0, 0x18000
	v_add_u32_e32 v151, s52, v147
	s_add_i32 s53, 0, 0x1c000
	ds_read_b128 v[152:155], v151
	ds_read_b128 v[156:159], v151 offset:1024
	ds_read_b128 v[160:163], v151 offset:2048
	ds_read_b128 v[168:171], v151 offset:3072
	v_add_u32_e32 v151, s53, v147
	ds_read_b128 v[172:175], v151
	ds_read_b128 v[176:179], v151 offset:1024
	ds_read_b128 v[180:183], v151 offset:2048
	ds_read_b128 v[184:187], v151 offset:3072
	s_add_u32 s28, s28, 0x40000
	s_addc_u32 s29, s29, 0
	s_mov_b32 m0, s36
	v_lshl_add_u64 v[226:227], s[28:29], 0, v[128:129]
	ds_read_b128 v[188:191], v150 offset:32768
	ds_read_b128 v[192:195], v150 offset:33792
	ds_read_b128 v[196:199], v150 offset:34816
	ds_read_b128 v[200:203], v150 offset:35840
	ds_read_b128 v[204:207], v150 offset:36864
	ds_read_b128 v[208:211], v150 offset:37888
	ds_read_b128 v[212:215], v150 offset:38912
	ds_read_b128 v[216:219], v150 offset:39936
	global_load_lds_dwordx4 v[226:227], off
	v_lshl_add_u64 v[226:227], s[28:29], 0, v[132:133]
	s_mov_b32 m0, s37
	s_nop 0
	global_load_lds_dwordx4 v[226:227], off
	s_waitcnt vmcnt(8)
	s_waitcnt lgkmcnt(0)
	s_barrier
	s_setprio 1
	s_waitcnt lgkmcnt(0)
	v_mfma_f32_16x16x32_bf16 v[124:127], v[152:155], v[188:191], v[124:127]
	v_mfma_f32_16x16x32_bf16 v[116:119], v[160:163], v[188:191], v[116:119]
	v_mfma_f32_16x16x32_bf16 v[108:111], v[152:155], v[196:199], v[108:111]
	v_mfma_f32_16x16x32_bf16 v[100:103], v[160:163], v[196:199], v[100:103]
	v_mfma_f32_16x16x32_bf16 v[92:95], v[152:155], v[204:207], v[92:95]
	v_mfma_f32_16x16x32_bf16 v[84:87], v[160:163], v[204:207], v[84:87]
	v_mfma_f32_16x16x32_bf16 v[76:79], v[152:155], v[212:215], v[76:79]
	v_mfma_f32_16x16x32_bf16 v[68:71], v[160:163], v[212:215], v[68:71]
	v_mfma_f32_16x16x32_bf16 v[124:127], v[156:159], v[192:195], v[124:127]
	v_mfma_f32_16x16x32_bf16 v[116:119], v[168:171], v[192:195], v[116:119]
	v_mfma_f32_16x16x32_bf16 v[108:111], v[156:159], v[200:203], v[108:111]
	v_mfma_f32_16x16x32_bf16 v[100:103], v[168:171], v[200:203], v[100:103]
	v_mfma_f32_16x16x32_bf16 v[92:95], v[156:159], v[208:211], v[92:95]
	v_mfma_f32_16x16x32_bf16 v[84:87], v[168:171], v[208:211], v[84:87]
	v_mfma_f32_16x16x32_bf16 v[76:79], v[156:159], v[216:219], v[76:79]
	v_mfma_f32_16x16x32_bf16 v[68:71], v[168:171], v[216:219], v[68:71]
	s_setprio 0
	s_setprio 1
	v_mfma_f32_16x16x32_bf16 v[120:123], v[172:175], v[188:191], v[120:123]
	v_mfma_f32_16x16x32_bf16 v[112:115], v[180:183], v[188:191], v[112:115]
	v_mfma_f32_16x16x32_bf16 v[104:107], v[172:175], v[196:199], v[104:107]
	v_mfma_f32_16x16x32_bf16 v[96:99], v[180:183], v[196:199], v[96:99]
	v_mfma_f32_16x16x32_bf16 v[88:91], v[172:175], v[204:207], v[88:91]
	v_mfma_f32_16x16x32_bf16 v[80:83], v[180:183], v[204:207], v[80:83]
	v_mfma_f32_16x16x32_bf16 v[72:75], v[172:175], v[212:215], v[72:75]
	v_mfma_f32_16x16x32_bf16 v[64:67], v[180:183], v[212:215], v[64:67]
	v_mfma_f32_16x16x32_bf16 v[120:123], v[176:179], v[192:195], v[120:123]
	v_mfma_f32_16x16x32_bf16 v[112:115], v[184:187], v[192:195], v[112:115]
	v_mfma_f32_16x16x32_bf16 v[104:107], v[176:179], v[200:203], v[104:107]
	v_mfma_f32_16x16x32_bf16 v[96:99], v[184:187], v[200:203], v[96:99]
	v_mfma_f32_16x16x32_bf16 v[88:91], v[176:179], v[208:211], v[88:91]
	v_mfma_f32_16x16x32_bf16 v[80:83], v[184:187], v[208:211], v[80:83]
	v_mfma_f32_16x16x32_bf16 v[72:75], v[176:179], v[216:219], v[72:75]
	v_mfma_f32_16x16x32_bf16 v[64:67], v[184:187], v[216:219], v[64:67]
	s_setprio 0
	s_barrier
; #define PG8_STAGE(bufoff, gbase, voff) do { _Pragma("unroll") for (int _i = 0; _i < 2; ++_i) \
;         __builtin_amdgcn_global_load_lds((const unsigned*)((const char*)(gbase) + (voff)[_i]), (LAS unsigned*)(lds + (bufoff) + ldsw + _i * 8192), 16, 0, 0); } while (0)
; #define PG8_LDA(dst, b, h) do { _Pragma("unroll") for (int m = 0; m < 4; ++m) _Pragma("unroll") for (int k = 0; k < 2; ++k) dst[m][k] = *(const LAS bf16x8*)(lds + PG8_SA(b, h) + aoff + m * 2048 + k * 1024); } while (0)
; #define PG8_MMA(ai, bj, At, Bt) do { __builtin_amdgcn_s_setprio(1); _Pragma("unroll") for (int m = 0; m < 4; ++m) _Pragma("unroll") for (int n = 0; n < 2; ++n) _Pragma("unroll") for (int k = 0; k < 2; ++k) \
;         acc[ai][bj][m][n] = __builtin_amdgcn_mfma_f32_16x16x32_bf16(Bt[n][k], At[m][k], acc[ai][bj][m][n], 0, 0, 0); __builtin_amdgcn_s_setprio(0); } while (0)
; #define PG8_WAIT_V(n) asm volatile("s_waitcnt vmcnt(" #n ")" ::: "memory")
; #define PG8_WAIT_L(n) asm volatile("s_waitcnt lgkmcnt(" #n ")" ::: "memory")
; #define PG8_BAR __builtin_amdgcn_s_barrier()
; #define PG8_SCHED __builtin_amdgcn_sched_barrier(0)
; template <class Epi, class Sched>
; __device__ __forceinline__ void gemm_phase(LAS unsigned char* lds, const Gemm g, const Sched& S, const Epi& E, int wid) {
;     ...
;             PG8_LDA(At, 1, 1); PG8_STAGE(PG8_SB(1, 0), b3, voffB); PG8_STAGE(PG8_SB(1, 1), b3 + hstep, voffB); PG8_STAGE(PG8_SA(1, 0), a3, voffA);
;             PG8_WAIT_V(8); PG8_WAIT_L(0); PG8_BAR; PG8_MMA(1, 0, At, B0); PG8_MMA(1, 1, At, B1); PG8_BAR; PG8_SCHED;
;         }
	s_add_i32 s28, s52, s75
	v_lshl_add_u64 v[164:165], v[164:165], 0, s[10:11]
	s_mov_b32 m0, s28
	ds_read_b128 v[188:191], v150 offset:49152
	ds_read_b128 v[192:195], v150 offset:50176
	ds_read_b128 v[196:199], v150 offset:51200
	ds_read_b128 v[200:203], v150 offset:52224
	ds_read_b128 v[204:207], v150 offset:53248
	ds_read_b128 v[208:211], v150 offset:54272
	ds_read_b128 v[212:215], v150 offset:55296
	ds_read_b128 v[216:219], v150 offset:56320
	global_load_lds_dwordx4 v[164:165], off
	s_add_i32 m0, s28, 0x2000
	s_add_u32 s26, s26, 0x40080
	v_lshl_add_u64 v[164:165], v[220:221], 0, s[10:11]
	s_addc_u32 s27, s27, 0
	s_add_i32 s28, s53, s75
	global_load_lds_dwordx4 v[164:165], off
	v_lshl_add_u64 v[164:165], s[26:27], 0, v[130:131]
	s_mov_b32 m0, s28
	s_nop 0
	global_load_lds_dwordx4 v[164:165], off
	v_lshl_add_u64 v[164:165], s[26:27], 0, v[134:135]
	s_add_i32 m0, s28, 0x2000
	s_nop 0
	global_load_lds_dwordx4 v[164:165], off
	v_lshl_add_u64 v[164:165], v[222:223], 0, s[10:11]
	s_mov_b32 m0, s38
	s_nop 0
	global_load_lds_dwordx4 v[164:165], off
	v_lshl_add_u64 v[164:165], v[224:225], 0, s[10:11]
	s_mov_b32 m0, s39
	s_nop 0
	global_load_lds_dwordx4 v[164:165], off
	s_waitcnt vmcnt(8)
	s_waitcnt lgkmcnt(0)
	s_barrier
	s_setprio 1
	s_waitcnt lgkmcnt(0)
	v_mfma_f32_16x16x32_bf16 v[60:63], v[152:155], v[188:191], v[60:63]
	v_mfma_f32_16x16x32_bf16 v[52:55], v[160:163], v[188:191], v[52:55]
	v_mfma_f32_16x16x32_bf16 v[44:47], v[152:155], v[196:199], v[44:47]
	v_mfma_f32_16x16x32_bf16 v[36:39], v[160:163], v[196:199], v[36:39]
	v_mfma_f32_16x16x32_bf16 v[28:31], v[152:155], v[204:207], v[28:31]
	v_mfma_f32_16x16x32_bf16 v[20:23], v[160:163], v[204:207], v[20:23]
	v_mfma_f32_16x16x32_bf16 v[12:15], v[152:155], v[212:215], v[12:15]
	v_mfma_f32_16x16x32_bf16 v[4:7], v[160:163], v[212:215], v[4:7]
	v_mfma_f32_16x16x32_bf16 v[60:63], v[156:159], v[192:195], v[60:63]
	v_mfma_f32_16x16x32_bf16 v[52:55], v[168:171], v[192:195], v[52:55]
	v_mfma_f32_16x16x32_bf16 v[44:47], v[156:159], v[200:203], v[44:47]
	v_mfma_f32_16x16x32_bf16 v[36:39], v[168:171], v[200:203], v[36:39]
	v_mfma_f32_16x16x32_bf16 v[28:31], v[156:159], v[208:211], v[28:31]
	v_mfma_f32_16x16x32_bf16 v[20:23], v[168:171], v[208:211], v[20:23]
	v_mfma_f32_16x16x32_bf16 v[12:15], v[156:159], v[216:219], v[12:15]
	v_mfma_f32_16x16x32_bf16 v[4:7], v[168:171], v[216:219], v[4:7]
	s_setprio 0
	s_setprio 1
	v_mfma_f32_16x16x32_bf16 v[56:59], v[172:175], v[188:191], v[56:59]
	v_mfma_f32_16x16x32_bf16 v[48:51], v[180:183], v[188:191], v[48:51]
	v_mfma_f32_16x16x32_bf16 v[40:43], v[172:175], v[196:199], v[40:43]
	v_mfma_f32_16x16x32_bf16 v[32:35], v[180:183], v[196:199], v[32:35]
	v_mfma_f32_16x16x32_bf16 v[24:27], v[172:175], v[204:207], v[24:27]
	v_mfma_f32_16x16x32_bf16 v[16:19], v[180:183], v[204:207], v[16:19]
	v_mfma_f32_16x16x32_bf16 v[8:11], v[172:175], v[212:215], v[8:11]
	v_mfma_f32_16x16x32_bf16 v[0:3], v[180:183], v[212:215], v[0:3]
	v_mfma_f32_16x16x32_bf16 v[56:59], v[176:179], v[192:195], v[56:59]
	v_mfma_f32_16x16x32_bf16 v[48:51], v[184:187], v[192:195], v[48:51]
	v_mfma_f32_16x16x32_bf16 v[40:43], v[176:179], v[200:203], v[40:43]
	v_mfma_f32_16x16x32_bf16 v[32:35], v[184:187], v[200:203], v[32:35]
	v_mfma_f32_16x16x32_bf16 v[24:27], v[176:179], v[208:211], v[24:27]
	v_mfma_f32_16x16x32_bf16 v[16:19], v[184:187], v[208:211], v[16:19]
	v_mfma_f32_16x16x32_bf16 v[8:11], v[176:179], v[216:219], v[8:11]
	v_mfma_f32_16x16x32_bf16 v[0:3], v[184:187], v[216:219], v[0:3]
	s_setprio 0
	s_add_i32 s51, s51, 2
	s_add_u32 s24, s24, 0x100
	s_addc_u32 s25, s25, 0
	s_add_u32 s49, s49, 0x100
	s_addc_u32 s50, s50, 0
	s_cmp_gt_u32 s51, 13
	s_barrier
	s_cbranch_scc0 .LBB0_475
	s_and_b64 vcc, exec, s[12:13]
	s_cbranch_vccz .LBB0_478
	s_barrier

; #define PG8_STAGE(bufoff, gbase, voff) do { _Pragma("unroll") for (int _i = 0; _i < 2; ++_i) \
;         __builtin_amdgcn_global_load_lds((const unsigned*)((const char*)(gbase) + (voff)[_i]), (LAS unsigned*)(lds + (bufoff) + ldsw + _i * 8192), 16, 0, 0); } while (0)
; #define PG8_LDA(dst, b, h) do { _Pragma("unroll") for (int m = 0; m < 4; ++m) _Pragma("unroll") for (int k = 0; k < 2; ++k) dst[m][k] = *(const LAS bf16x8*)(lds + PG8_SA(b, h) + aoff + m * 2048 + k * 1024); } while (0)
; #define PG8_LDB(dst, b, h) do { _Pragma("unroll") for (int n = 0; n < 2; ++n) _Pragma("unroll") for (int k = 0; k < 2; ++k) dst[n][k] = *(const LAS bf16x8*)(lds + PG8_SB(b, h) + boff + n * 2048 + k * 1024); } while (0)
; #define PG8_MMA(ai, bj, At, Bt) do { __builtin_amdgcn_s_setprio(1); _Pragma("unroll") for (int m = 0; m < 4; ++m) _Pragma("unroll") for (int n = 0; n < 2; ++n) _Pragma("unroll") for (int k = 0; k < 2; ++k) \
;         acc[ai][bj][m][n] = __builtin_amdgcn_mfma_f32_16x16x32_bf16(Bt[n][k], At[m][k], acc[ai][bj][m][n], 0, 0, 0); __builtin_amdgcn_s_setprio(0); } while (0)
; #define PG8_WAIT_V(n) asm volatile("s_waitcnt vmcnt(" #n ")" ::: "memory")
; #define PG8_WAIT_L(n) asm volatile("s_waitcnt lgkmcnt(" #n ")" ::: "memory")
; #define PG8_BAR __builtin_amdgcn_s_barrier()
; #define PG8_SCHED __builtin_amdgcn_sched_barrier(0)
; template <class Epi, class Sched>
; __device__ __forceinline__ void gemm_phase(LAS unsigned char* lds, const Gemm g, const Sched& S, const Epi& E, int wid) {
;     ...
;             PG8_LDB(B0, 0, 0); PG8_LDB(B1, 0, 1); PG8_SCHED; PG8_LDA(At, 0, 0); PG8_STAGE(PG8_SA(1, 1), a1 + hstep, voffA);
;             PG8_WAIT_V(8); PG8_WAIT_L(0); PG8_BAR; PG8_MMA(0, 0, At, B0); PG8_MMA(0, 1, At, B1); PG8_BAR; PG8_SCHED;
;             PG8_LDA(At, 0, 1); PG8_STAGE(PG8_SB(0, 0), b2, voffB); PG8_STAGE(PG8_SB(0, 1), b2 + hstep, voffB); PG8_STAGE(PG8_SA(0, 0), a2, voffA);
;             PG8_WAIT_V(8); PG8_WAIT_L(0); PG8_BAR; PG8_MMA(1, 0, At, B0); PG8_MMA(1, 1, At, B1); PG8_BAR; PG8_SCHED;
.LBB0_573:
	ds_read_b128 v[128:131], v169
	ds_read_b128 v[132:135], v169 offset:1024
	ds_read_b128 v[152:155], v169 offset:2048
	ds_read_b128 v[156:159], v169 offset:3072
	ds_read_b128 v[160:163], v170
	ds_read_b128 v[174:177], v170 offset:1024
	ds_read_b128 v[178:181], v170 offset:2048
	ds_read_b128 v[182:185], v170 offset:3072
	s_add_u32 s4, s6, 0x100
	s_addc_u32 s5, s7, 0
	s_cmp_eq_u32 s40, 40
	s_cselect_b32 s39, s29, s5
	s_cselect_b32 s38, s28, s4
	s_cselect_b32 s11, s31, s37
	s_cselect_b32 s10, s30, s35
	v_lshl_add_u64 v[218:219], s[6:7], 0, v[144:145]
	s_add_i32 m0, s44, 0xc000
	ds_read_b128 v[186:189], v171
	ds_read_b128 v[190:193], v171 offset:1024
	ds_read_b128 v[194:197], v171 offset:2048
	ds_read_b128 v[198:201], v171 offset:3072
	ds_read_b128 v[202:205], v171 offset:4096
	ds_read_b128 v[206:209], v171 offset:5120
	ds_read_b128 v[210:213], v171 offset:6144
	ds_read_b128 v[214:217], v171 offset:7168
	global_load_lds_dwordx4 v[218:219], off
	v_lshl_add_u64 v[218:219], s[6:7], 0, v[146:147]
	s_add_i32 m0, s44, 0xe000
	s_nop 0
	global_load_lds_dwordx4 v[218:219], off
	s_waitcnt vmcnt(8)
	s_waitcnt lgkmcnt(0)
	s_barrier
	s_setprio 1
	s_waitcnt lgkmcnt(0)
	v_mfma_f32_16x16x32_bf16 v[56:59], v[128:131], v[186:189], v[56:59]
	v_mfma_f32_16x16x32_bf16 v[60:63], v[152:155], v[186:189], v[60:63]
	v_mfma_f32_16x16x32_bf16 v[84:87], v[128:131], v[194:197], v[84:87]
	v_mfma_f32_16x16x32_bf16 v[88:91], v[152:155], v[194:197], v[88:91]
	v_mfma_f32_16x16x32_bf16 v[112:115], v[128:131], v[202:205], v[112:115]
	v_mfma_f32_16x16x32_bf16 v[116:119], v[152:155], v[202:205], v[116:119]
	v_mfma_f32_16x16x32_bf16 v[120:123], v[128:131], v[210:213], v[120:123]
	v_mfma_f32_16x16x32_bf16 v[124:127], v[152:155], v[210:213], v[124:127]
	v_mfma_f32_16x16x32_bf16 v[56:59], v[132:135], v[190:193], v[56:59]
	v_mfma_f32_16x16x32_bf16 v[60:63], v[156:159], v[190:193], v[60:63]
	v_mfma_f32_16x16x32_bf16 v[84:87], v[132:135], v[198:201], v[84:87]
	v_mfma_f32_16x16x32_bf16 v[88:91], v[156:159], v[198:201], v[88:91]
	v_mfma_f32_16x16x32_bf16 v[112:115], v[132:135], v[206:209], v[112:115]
	v_mfma_f32_16x16x32_bf16 v[116:119], v[156:159], v[206:209], v[116:119]
	v_mfma_f32_16x16x32_bf16 v[120:123], v[132:135], v[214:217], v[120:123]
	v_mfma_f32_16x16x32_bf16 v[124:127], v[156:159], v[214:217], v[124:127]
	s_setprio 0
	s_setprio 1
	v_mfma_f32_16x16x32_bf16 v[20:23], v[160:163], v[186:189], v[20:23]
	v_mfma_f32_16x16x32_bf16 v[28:31], v[178:181], v[186:189], v[28:31]
	v_mfma_f32_16x16x32_bf16 v[40:43], v[160:163], v[194:197], v[40:43]
	v_mfma_f32_16x16x32_bf16 v[48:51], v[178:181], v[194:197], v[48:51]
	v_mfma_f32_16x16x32_bf16 v[64:67], v[160:163], v[202:205], v[64:67]
	v_mfma_f32_16x16x32_bf16 v[80:83], v[178:181], v[202:205], v[80:83]
	v_mfma_f32_16x16x32_bf16 v[96:99], v[160:163], v[210:213], v[96:99]
	v_mfma_f32_16x16x32_bf16 v[104:107], v[178:181], v[210:213], v[104:107]
	v_mfma_f32_16x16x32_bf16 v[20:23], v[174:177], v[190:193], v[20:23]
	v_mfma_f32_16x16x32_bf16 v[28:31], v[182:185], v[190:193], v[28:31]
	v_mfma_f32_16x16x32_bf16 v[40:43], v[174:177], v[198:201], v[40:43]
	v_mfma_f32_16x16x32_bf16 v[48:51], v[182:185], v[198:201], v[48:51]
	v_mfma_f32_16x16x32_bf16 v[64:67], v[174:177], v[206:209], v[64:67]
	v_mfma_f32_16x16x32_bf16 v[80:83], v[182:185], v[206:209], v[80:83]
	v_mfma_f32_16x16x32_bf16 v[96:99], v[174:177], v[214:217], v[96:99]
	v_mfma_f32_16x16x32_bf16 v[104:107], v[182:185], v[214:217], v[104:107]
	s_setprio 0
	s_barrier
	s_add_i32 s6, s61, s75
	v_lshl_add_u64 v[218:219], s[10:11], 0, v[138:139]
	s_mov_b32 m0, s6
	ds_read_b128 v[186:189], v171 offset:16384
	ds_read_b128 v[190:193], v171 offset:17408
	ds_read_b128 v[194:197], v171 offset:18432
	ds_read_b128 v[198:201], v171 offset:19456
	ds_read_b128 v[202:205], v171 offset:20480
	ds_read_b128 v[206:209], v171 offset:21504
	ds_read_b128 v[210:213], v171 offset:22528
	ds_read_b128 v[214:217], v171 offset:23552
	global_load_lds_dwordx4 v[218:219], off
	s_add_i32 m0, s6, 0x2000
	s_add_u32 s6, s10, 0xb0000
	v_lshl_add_u64 v[220:221], s[10:11], 0, v[142:143]
	s_addc_u32 s7, s11, 0
	s_add_i32 s41, s62, s75
	global_load_lds_dwordx4 v[220:221], off
	v_lshl_add_u64 v[222:223], s[6:7], 0, v[138:139]
	s_mov_b32 m0, s41
	v_lshl_add_u64 v[224:225], s[38:39], 0, v[140:141]
	global_load_lds_dwordx4 v[222:223], off
	v_lshl_add_u64 v[222:223], s[6:7], 0, v[142:143]
	s_add_i32 m0, s41, 0x2000
	s_nop 0
	global_load_lds_dwordx4 v[222:223], off
	v_lshl_add_u64 v[222:223], s[38:39], 0, v[136:137]
	s_mov_b32 m0, s44
	s_nop 0
	global_load_lds_dwordx4 v[222:223], off
	s_mov_b32 m0, s45
	s_nop 0
	global_load_lds_dwordx4 v[224:225], off
	s_waitcnt vmcnt(8)
	s_waitcnt lgkmcnt(0)
	s_barrier
; #define PG8_STAGE(bufoff, gbase, voff) do { _Pragma("unroll") for (int _i = 0; _i < 2; ++_i) \
;         __builtin_amdgcn_global_load_lds((const unsigned*)((const char*)(gbase) + (voff)[_i]), (LAS unsigned*)(lds + (bufoff) + ldsw + _i * 8192), 16, 0, 0); } while (0)
; #define PG8_LDA(dst, b, h) do { _Pragma("unroll") for (int m = 0; m < 4; ++m) _Pragma("unroll") for (int k = 0; k < 2; ++k) dst[m][k] = *(const LAS bf16x8*)(lds + PG8_SA(b, h) + aoff + m * 2048 + k * 1024); } while (0)
; #define PG8_LDB(dst, b, h) do { _Pragma("unroll") for (int n = 0; n < 2; ++n) _Pragma("unroll") for (int k = 0; k < 2; ++k) dst[n][k] = *(const LAS bf16x8*)(lds + PG8_SB(b, h) + boff + n * 2048 + k * 1024); } while (0)
; #define PG8_MMA(ai, bj, At, Bt) do { __builtin_amdgcn_s_setprio(1); _Pragma("unroll") for (int m = 0; m < 4; ++m) _Pragma("unroll") for (int n = 0; n < 2; ++n) _Pragma("unroll") for (int k = 0; k < 2; ++k) \
;         acc[ai][bj][m][n] = __builtin_amdgcn_mfma_f32_16x16x32_bf16(Bt[n][k], At[m][k], acc[ai][bj][m][n], 0, 0, 0); __builtin_amdgcn_s_setprio(0); } while (0)
; #define PG8_WAIT_V(n) asm volatile("s_waitcnt vmcnt(" #n ")" ::: "memory")
; #define PG8_WAIT_L(n) asm volatile("s_waitcnt lgkmcnt(" #n ")" ::: "memory")
; #define PG8_BAR __builtin_amdgcn_s_barrier()
; #define PG8_SCHED __builtin_amdgcn_sched_barrier(0)
; template <class Epi, class Sched>
; __device__ __forceinline__ void gemm_phase(LAS unsigned char* lds, const Gemm g, const Sched& S, const Epi& E, int wid) {
;     ...
;             PG8_WAIT_V(8); PG8_WAIT_L(0); PG8_BAR; PG8_MMA(1, 0, At, B0); PG8_MMA(1, 1, At, B1); PG8_BAR; PG8_SCHED;
;             PG8_LDB(B0, 1, 0); PG8_LDB(B1, 1, 1); PG8_SCHED; PG8_LDA(At, 1, 0); PG8_STAGE(PG8_SA(0, 1), a2 + hstep, voffA);
;             PG8_WAIT_V(8); PG8_WAIT_L(0); PG8_BAR; PG8_MMA(0, 0, At, B0); PG8_MMA(0, 1, At, B1); PG8_BAR; PG8_SCHED;
	s_setprio 1
	s_waitcnt lgkmcnt(0)
	v_mfma_f32_16x16x32_bf16 v[108:111], v[128:131], v[186:189], v[108:111]
	v_mfma_f32_16x16x32_bf16 v[100:103], v[152:155], v[186:189], v[100:103]
	v_mfma_f32_16x16x32_bf16 v[72:75], v[128:131], v[194:197], v[72:75]
	v_mfma_f32_16x16x32_bf16 v[68:71], v[152:155], v[194:197], v[68:71]
	v_mfma_f32_16x16x32_bf16 v[36:39], v[128:131], v[202:205], v[36:39]
	v_mfma_f32_16x16x32_bf16 v[32:35], v[152:155], v[202:205], v[32:35]
	v_mfma_f32_16x16x32_bf16 v[12:15], v[128:131], v[210:213], v[12:15]
	v_mfma_f32_16x16x32_bf16 v[8:11], v[152:155], v[210:213], v[8:11]
	v_mfma_f32_16x16x32_bf16 v[108:111], v[132:135], v[190:193], v[108:111]
	v_mfma_f32_16x16x32_bf16 v[100:103], v[156:159], v[190:193], v[100:103]
	v_mfma_f32_16x16x32_bf16 v[72:75], v[132:135], v[198:201], v[72:75]
	v_mfma_f32_16x16x32_bf16 v[68:71], v[156:159], v[198:201], v[68:71]
	v_mfma_f32_16x16x32_bf16 v[36:39], v[132:135], v[206:209], v[36:39]
	v_mfma_f32_16x16x32_bf16 v[32:35], v[156:159], v[206:209], v[32:35]
	v_mfma_f32_16x16x32_bf16 v[12:15], v[132:135], v[214:217], v[12:15]
	v_mfma_f32_16x16x32_bf16 v[8:11], v[156:159], v[214:217], v[8:11]
	s_setprio 0
	s_setprio 1
	v_mfma_f32_16x16x32_bf16 v[92:95], v[160:163], v[186:189], v[92:95]
	v_mfma_f32_16x16x32_bf16 v[76:79], v[178:181], v[186:189], v[76:79]
	v_mfma_f32_16x16x32_bf16 v[52:55], v[160:163], v[194:197], v[52:55]
	v_mfma_f32_16x16x32_bf16 v[44:47], v[178:181], v[194:197], v[44:47]
	v_mfma_f32_16x16x32_bf16 v[24:27], v[160:163], v[202:205], v[24:27]
	v_mfma_f32_16x16x32_bf16 v[16:19], v[178:181], v[202:205], v[16:19]
	v_mfma_f32_16x16x32_bf16 v[4:7], v[160:163], v[210:213], v[4:7]
	v_mfma_f32_16x16x32_bf16 v[0:3], v[178:181], v[210:213], v[0:3]
	v_mfma_f32_16x16x32_bf16 v[92:95], v[174:177], v[190:193], v[92:95]
	v_mfma_f32_16x16x32_bf16 v[76:79], v[182:185], v[190:193], v[76:79]
	v_mfma_f32_16x16x32_bf16 v[52:55], v[174:177], v[198:201], v[52:55]
	v_mfma_f32_16x16x32_bf16 v[44:47], v[182:185], v[198:201], v[44:47]
	v_mfma_f32_16x16x32_bf16 v[24:27], v[174:177], v[206:209], v[24:27]
	v_mfma_f32_16x16x32_bf16 v[16:19], v[182:185], v[206:209], v[16:19]
	v_mfma_f32_16x16x32_bf16 v[4:7], v[174:177], v[214:217], v[4:7]
	v_mfma_f32_16x16x32_bf16 v[0:3], v[182:185], v[214:217], v[0:3]
	s_setprio 0
	s_barrier
	s_add_i32 s41, 0, 0x18000
	s_add_i32 s69, 0, 0x1c000
	v_add_u32_e32 v156, s41, v168
	v_add_u32_e32 v173, s69, v168
	ds_read_b128 v[128:131], v156
	ds_read_b128 v[132:135], v156 offset:1024
	ds_read_b128 v[152:155], v156 offset:2048
	ds_read_b128 v[156:159], v156 offset:3072
	ds_read_b128 v[160:163], v173
	ds_read_b128 v[174:177], v173 offset:1024
	ds_read_b128 v[178:181], v173 offset:2048
	ds_read_b128 v[182:185], v173 offset:3072
	s_add_u32 s6, s38, 0xb0000
	s_addc_u32 s7, s39, 0
	s_mov_b32 m0, s46
	v_lshl_add_u64 v[226:227], s[6:7], 0, v[136:137]
	ds_read_b128 v[186:189], v171 offset:32768
	ds_read_b128 v[190:193], v171 offset:33792
	ds_read_b128 v[194:197], v171 offset:34816
	ds_read_b128 v[198:201], v171 offset:35840
	ds_read_b128 v[202:205], v171 offset:36864
	ds_read_b128 v[206:209], v171 offset:37888
	ds_read_b128 v[210:213], v171 offset:38912
	ds_read_b128 v[214:217], v171 offset:39936
	global_load_lds_dwordx4 v[226:227], off
	v_lshl_add_u64 v[226:227], s[6:7], 0, v[140:141]
	s_mov_b32 m0, s47
	s_nop 0
	global_load_lds_dwordx4 v[226:227], off
	s_waitcnt vmcnt(8)
	s_waitcnt lgkmcnt(0)
	s_barrier
	s_setprio 1
	s_waitcnt lgkmcnt(0)
	v_mfma_f32_16x16x32_bf16 v[56:59], v[128:131], v[186:189], v[56:59]
	v_mfma_f32_16x16x32_bf16 v[60:63], v[152:155], v[186:189], v[60:63]
	v_mfma_f32_16x16x32_bf16 v[84:87], v[128:131], v[194:197], v[84:87]
	v_mfma_f32_16x16x32_bf16 v[88:91], v[152:155], v[194:197], v[88:91]
	v_mfma_f32_16x16x32_bf16 v[112:115], v[128:131], v[202:205], v[112:115]
	v_mfma_f32_16x16x32_bf16 v[116:119], v[152:155], v[202:205], v[116:119]
	v_mfma_f32_16x16x32_bf16 v[120:123], v[128:131], v[210:213], v[120:123]
	v_mfma_f32_16x16x32_bf16 v[124:127], v[152:155], v[210:213], v[124:127]
	v_mfma_f32_16x16x32_bf16 v[56:59], v[132:135], v[190:193], v[56:59]
	v_mfma_f32_16x16x32_bf16 v[60:63], v[156:159], v[190:193], v[60:63]
	v_mfma_f32_16x16x32_bf16 v[84:87], v[132:135], v[198:201], v[84:87]
	v_mfma_f32_16x16x32_bf16 v[88:91], v[156:159], v[198:201], v[88:91]
	v_mfma_f32_16x16x32_bf16 v[112:115], v[132:135], v[206:209], v[112:115]
	v_mfma_f32_16x16x32_bf16 v[116:119], v[156:159], v[206:209], v[116:119]
	v_mfma_f32_16x16x32_bf16 v[120:123], v[132:135], v[214:217], v[120:123]
	v_mfma_f32_16x16x32_bf16 v[124:127], v[156:159], v[214:217], v[124:127]
	s_setprio 0
	s_setprio 1
	v_mfma_f32_16x16x32_bf16 v[20:23], v[160:163], v[186:189], v[20:23]
	v_mfma_f32_16x16x32_bf16 v[28:31], v[178:181], v[186:189], v[28:31]
	v_mfma_f32_16x16x32_bf16 v[40:43], v[160:163], v[194:197], v[40:43]
	v_mfma_f32_16x16x32_bf16 v[48:51], v[178:181], v[194:197], v[48:51]
	v_mfma_f32_16x16x32_bf16 v[64:67], v[160:163], v[202:205], v[64:67]
	v_mfma_f32_16x16x32_bf16 v[80:83], v[178:181], v[202:205], v[80:83]
	v_mfma_f32_16x16x32_bf16 v[96:99], v[160:163], v[210:213], v[96:99]
	v_mfma_f32_16x16x32_bf16 v[104:107], v[178:181], v[210:213], v[104:107]
	v_mfma_f32_16x16x32_bf16 v[20:23], v[174:177], v[190:193], v[20:23]
	v_mfma_f32_16x16x32_bf16 v[28:31], v[182:185], v[190:193], v[28:31]
	v_mfma_f32_16x16x32_bf16 v[40:43], v[174:177], v[198:201], v[40:43]
	v_mfma_f32_16x16x32_bf16 v[48:51], v[182:185], v[198:201], v[48:51]
	v_mfma_f32_16x16x32_bf16 v[64:67], v[174:177], v[206:209], v[64:67]
	v_mfma_f32_16x16x32_bf16 v[80:83], v[182:185], v[206:209], v[80:83]
	v_mfma_f32_16x16x32_bf16 v[96:99], v[174:177], v[214:217], v[96:99]
	v_mfma_f32_16x16x32_bf16 v[104:107], v[182:185], v[214:217], v[104:107]
	s_setprio 0
	s_barrier
; #define PG8_STAGE(bufoff, gbase, voff) do { _Pragma("unroll") for (int _i = 0; _i < 2; ++_i) \
;         __builtin_amdgcn_global_load_lds((const unsigned*)((const char*)(gbase) + (voff)[_i]), (LAS unsigned*)(lds + (bufoff) + ldsw + _i * 8192), 16, 0, 0); } while (0)
; #define PG8_LDA(dst, b, h) do { _Pragma("unroll") for (int m = 0; m < 4; ++m) _Pragma("unroll") for (int k = 0; k < 2; ++k) dst[m][k] = *(const LAS bf16x8*)(lds + PG8_SA(b, h) + aoff + m * 2048 + k * 1024); } while (0)
; #define PG8_MMA(ai, bj, At, Bt) do { __builtin_amdgcn_s_setprio(1); _Pragma("unroll") for (int m = 0; m < 4; ++m) _Pragma("unroll") for (int n = 0; n < 2; ++n) _Pragma("unroll") for (int k = 0; k < 2; ++k) \
;         acc[ai][bj][m][n] = __builtin_amdgcn_mfma_f32_16x16x32_bf16(Bt[n][k], At[m][k], acc[ai][bj][m][n], 0, 0, 0); __builtin_amdgcn_s_setprio(0); } while (0)
; #define PG8_WAIT_V(n) asm volatile("s_waitcnt vmcnt(" #n ")" ::: "memory")
; #define PG8_WAIT_L(n) asm volatile("s_waitcnt lgkmcnt(" #n ")" ::: "memory")
; #define PG8_BAR __builtin_amdgcn_s_barrier()
; #define PG8_SCHED __builtin_amdgcn_sched_barrier(0)
; template <class Epi, class Sched>
; __device__ __forceinline__ void gemm_phase(LAS unsigned char* lds, const Gemm g, const Sched& S, const Epi& E, int wid) {
;     ...
;             PG8_LDA(At, 1, 1); PG8_STAGE(PG8_SB(1, 0), b3, voffB); PG8_STAGE(PG8_SB(1, 1), b3 + hstep, voffB); PG8_STAGE(PG8_SA(1, 0), a3, voffA);
;             PG8_WAIT_V(8); PG8_WAIT_L(0); PG8_BAR; PG8_MMA(1, 0, At, B0); PG8_MMA(1, 1, At, B1); PG8_BAR; PG8_SCHED;
;         }
	s_add_i32 s6, s41, s75
	v_lshl_add_u64 v[218:219], v[218:219], 0, s[22:23]
	s_mov_b32 m0, s6
	ds_read_b128 v[186:189], v171 offset:49152
	ds_read_b128 v[190:193], v171 offset:50176
	ds_read_b128 v[194:197], v171 offset:51200
	ds_read_b128 v[198:201], v171 offset:52224
	ds_read_b128 v[202:205], v171 offset:53248
	ds_read_b128 v[206:209], v171 offset:54272
	ds_read_b128 v[210:213], v171 offset:55296
	ds_read_b128 v[214:217], v171 offset:56320
	global_load_lds_dwordx4 v[218:219], off
	s_add_i32 m0, s6, 0x2000
	s_add_u32 s6, s10, 0xb0080
	v_lshl_add_u64 v[218:219], v[220:221], 0, s[22:23]
	s_addc_u32 s7, s11, 0
	s_add_i32 s10, s69, s75
	global_load_lds_dwordx4 v[218:219], off
	v_lshl_add_u64 v[218:219], s[6:7], 0, v[138:139]
	s_mov_b32 m0, s10
	s_nop 0
	global_load_lds_dwordx4 v[218:219], off
	v_lshl_add_u64 v[218:219], s[6:7], 0, v[142:143]
	s_add_i32 m0, s10, 0x2000
	s_nop 0
	global_load_lds_dwordx4 v[218:219], off
	v_lshl_add_u64 v[218:219], v[222:223], 0, s[22:23]
	s_mov_b32 m0, s53
	s_nop 0
	global_load_lds_dwordx4 v[218:219], off
	v_lshl_add_u64 v[218:219], v[224:225], 0, s[22:23]
	s_mov_b32 m0, s54
	s_nop 0
	global_load_lds_dwordx4 v[218:219], off
	s_waitcnt vmcnt(8)
	s_waitcnt lgkmcnt(0)
	s_barrier
	s_setprio 1
	s_waitcnt lgkmcnt(0)
	v_mfma_f32_16x16x32_bf16 v[108:111], v[128:131], v[186:189], v[108:111]
	v_mfma_f32_16x16x32_bf16 v[100:103], v[152:155], v[186:189], v[100:103]
	v_mfma_f32_16x16x32_bf16 v[72:75], v[128:131], v[194:197], v[72:75]
	v_mfma_f32_16x16x32_bf16 v[68:71], v[152:155], v[194:197], v[68:71]
	v_mfma_f32_16x16x32_bf16 v[36:39], v[128:131], v[202:205], v[36:39]
	v_mfma_f32_16x16x32_bf16 v[32:35], v[152:155], v[202:205], v[32:35]
	v_mfma_f32_16x16x32_bf16 v[12:15], v[128:131], v[210:213], v[12:15]
	v_mfma_f32_16x16x32_bf16 v[8:11], v[152:155], v[210:213], v[8:11]
	v_mfma_f32_16x16x32_bf16 v[108:111], v[132:135], v[190:193], v[108:111]
	v_mfma_f32_16x16x32_bf16 v[100:103], v[156:159], v[190:193], v[100:103]
	v_mfma_f32_16x16x32_bf16 v[72:75], v[132:135], v[198:201], v[72:75]
	v_mfma_f32_16x16x32_bf16 v[68:71], v[156:159], v[198:201], v[68:71]
	v_mfma_f32_16x16x32_bf16 v[36:39], v[132:135], v[206:209], v[36:39]
	v_mfma_f32_16x16x32_bf16 v[32:35], v[156:159], v[206:209], v[32:35]
	v_mfma_f32_16x16x32_bf16 v[12:15], v[132:135], v[214:217], v[12:15]
	v_mfma_f32_16x16x32_bf16 v[8:11], v[156:159], v[214:217], v[8:11]
	s_setprio 0
	s_setprio 1
	v_mfma_f32_16x16x32_bf16 v[92:95], v[160:163], v[186:189], v[92:95]
	v_mfma_f32_16x16x32_bf16 v[76:79], v[178:181], v[186:189], v[76:79]
	v_mfma_f32_16x16x32_bf16 v[52:55], v[160:163], v[194:197], v[52:55]
	v_mfma_f32_16x16x32_bf16 v[44:47], v[178:181], v[194:197], v[44:47]
	v_mfma_f32_16x16x32_bf16 v[24:27], v[160:163], v[202:205], v[24:27]
	v_mfma_f32_16x16x32_bf16 v[16:19], v[178:181], v[202:205], v[16:19]
	v_mfma_f32_16x16x32_bf16 v[4:7], v[160:163], v[210:213], v[4:7]
	v_mfma_f32_16x16x32_bf16 v[0:3], v[178:181], v[210:213], v[0:3]
	v_mfma_f32_16x16x32_bf16 v[92:95], v[174:177], v[190:193], v[92:95]
	v_mfma_f32_16x16x32_bf16 v[76:79], v[182:185], v[190:193], v[76:79]
	v_mfma_f32_16x16x32_bf16 v[52:55], v[174:177], v[198:201], v[52:55]
	v_mfma_f32_16x16x32_bf16 v[44:47], v[182:185], v[198:201], v[44:47]
	v_mfma_f32_16x16x32_bf16 v[24:27], v[174:177], v[206:209], v[24:27]
	v_mfma_f32_16x16x32_bf16 v[16:19], v[182:185], v[206:209], v[16:19]
	v_mfma_f32_16x16x32_bf16 v[4:7], v[174:177], v[214:217], v[4:7]
	v_mfma_f32_16x16x32_bf16 v[0:3], v[182:185], v[214:217], v[0:3]
	s_setprio 0
	s_add_i32 s40, s40, 2
	s_add_u32 s35, s35, 0x100
	s_addc_u32 s37, s37, 0
	s_cmp_gt_u32 s40, 41
	s_mov_b64 s[6:7], s[4:5]
	s_barrier
	s_cbranch_scc0 .LBB0_573
	s_and_b64 vcc, exec, s[24:25]
	s_cbranch_vccz .LBB0_576
	s_barrier

; #define PG8_STAGE(bufoff, gbase, voff) do { _Pragma("unroll") for (int _i = 0; _i < 2; ++_i) \
;         __builtin_amdgcn_global_load_lds((const unsigned*)((const char*)(gbase) + (voff)[_i]), (LAS unsigned*)(lds + (bufoff) + ldsw + _i * 8192), 16, 0, 0); } while (0)
; #define PG8_LDA(dst, b, h) do { _Pragma("unroll") for (int m = 0; m < 4; ++m) _Pragma("unroll") for (int k = 0; k < 2; ++k) dst[m][k] = *(const LAS bf16x8*)(lds + PG8_SA(b, h) + aoff + m * 2048 + k * 1024); } while (0)
; #define PG8_LDB(dst, b, h) do { _Pragma("unroll") for (int n = 0; n < 2; ++n) _Pragma("unroll") for (int k = 0; k < 2; ++k) dst[n][k] = *(const LAS bf16x8*)(lds + PG8_SB(b, h) + boff + n * 2048 + k * 1024); } while (0)
; #define PG8_MMA(ai, bj, At, Bt) do { __builtin_amdgcn_s_setprio(1); _Pragma("unroll") for (int m = 0; m < 4; ++m) _Pragma("unroll") for (int n = 0; n < 2; ++n) _Pragma("unroll") for (int k = 0; k < 2; ++k) \
;         acc[ai][bj][m][n] = __builtin_amdgcn_mfma_f32_16x16x32_bf16(Bt[n][k], At[m][k], acc[ai][bj][m][n], 0, 0, 0); __builtin_amdgcn_s_setprio(0); } while (0)
; #define PG8_WAIT_V(n) asm volatile("s_waitcnt vmcnt(" #n ")" ::: "memory")
; #define PG8_WAIT_L(n) asm volatile("s_waitcnt lgkmcnt(" #n ")" ::: "memory")
; #define PG8_BAR __builtin_amdgcn_s_barrier()
; #define PG8_SCHED __builtin_amdgcn_sched_barrier(0)
; template <class Epi, class Sched>
; __device__ __forceinline__ void gemm_phase(LAS unsigned char* lds, const Gemm g, const Sched& S, const Epi& E, int wid) {
;     ...
;             PG8_LDB(B0, 0, 0); PG8_LDB(B1, 0, 1); PG8_SCHED; PG8_LDA(At, 0, 0); PG8_STAGE(PG8_SA(1, 1), a1 + hstep, voffA);
;             PG8_WAIT_V(8); PG8_WAIT_L(0); PG8_BAR; PG8_MMA(0, 0, At, B0); PG8_MMA(0, 1, At, B1); PG8_BAR; PG8_SCHED;
;             PG8_LDA(At, 0, 1); PG8_STAGE(PG8_SB(0, 0), b2, voffB); PG8_STAGE(PG8_SB(0, 1), b2 + hstep, voffB); PG8_STAGE(PG8_SA(0, 0), a2, voffA);
;             PG8_WAIT_V(8); PG8_WAIT_L(0); PG8_BAR; PG8_MMA(1, 0, At, B0); PG8_MMA(1, 1, At, B1); PG8_BAR; PG8_SCHED;
.LBB0_743:
	ds_read_b128 v[150:153], v172
	ds_read_b128 v[154:157], v172 offset:1024
	ds_read_b128 v[158:161], v172 offset:2048
	ds_read_b128 v[162:165], v172 offset:3072
	ds_read_b128 v[176:179], v173
	ds_read_b128 v[180:183], v173 offset:1024
	ds_read_b128 v[184:187], v173 offset:2048
	ds_read_b128 v[188:191], v173 offset:3072
	s_add_u32 s4, s6, 0xfffc0080
	s_addc_u32 s5, s7, -1
	s_cmp_eq_u32 s45, 12
	s_cselect_b32 s15, s13, s5
	s_cselect_b32 s14, s37, s4
	s_cselect_b32 s5, s35, s44
	s_cselect_b32 s4, s42, s43
	v_lshl_add_u64 v[224:225], s[6:7], 0, v[142:143]
	s_add_i32 m0, s23, 0xc000
	ds_read_b128 v[192:195], v174
	ds_read_b128 v[196:199], v174 offset:1024
	ds_read_b128 v[200:203], v174 offset:2048
	ds_read_b128 v[204:207], v174 offset:3072
	ds_read_b128 v[208:211], v174 offset:4096
	ds_read_b128 v[212:215], v174 offset:5120
	ds_read_b128 v[216:219], v174 offset:6144
	ds_read_b128 v[220:223], v174 offset:7168
	global_load_lds_dwordx4 v[224:225], off
	v_lshl_add_u64 v[224:225], s[6:7], 0, v[144:145]
	s_add_i32 m0, s23, 0xe000
	s_nop 0
	global_load_lds_dwordx4 v[224:225], off
	s_waitcnt vmcnt(8)
	s_waitcnt lgkmcnt(0)
	s_barrier
	s_setprio 1
	s_waitcnt lgkmcnt(0)
	v_mfma_f32_16x16x32_bf16 v[60:63], v[150:153], v[192:195], v[60:63]
	v_mfma_f32_16x16x32_bf16 v[56:59], v[158:161], v[192:195], v[56:59]
	v_mfma_f32_16x16x32_bf16 v[52:55], v[150:153], v[200:203], v[52:55]
	v_mfma_f32_16x16x32_bf16 v[48:51], v[158:161], v[200:203], v[48:51]
	v_mfma_f32_16x16x32_bf16 v[44:47], v[150:153], v[208:211], v[44:47]
	v_mfma_f32_16x16x32_bf16 v[40:43], v[158:161], v[208:211], v[40:43]
	v_mfma_f32_16x16x32_bf16 v[36:39], v[150:153], v[216:219], v[36:39]
	v_mfma_f32_16x16x32_bf16 v[32:35], v[158:161], v[216:219], v[32:35]
	v_mfma_f32_16x16x32_bf16 v[60:63], v[154:157], v[196:199], v[60:63]
	v_mfma_f32_16x16x32_bf16 v[56:59], v[162:165], v[196:199], v[56:59]
	v_mfma_f32_16x16x32_bf16 v[52:55], v[154:157], v[204:207], v[52:55]
	v_mfma_f32_16x16x32_bf16 v[48:51], v[162:165], v[204:207], v[48:51]
	v_mfma_f32_16x16x32_bf16 v[44:47], v[154:157], v[212:215], v[44:47]
	v_mfma_f32_16x16x32_bf16 v[40:43], v[162:165], v[212:215], v[40:43]
	v_mfma_f32_16x16x32_bf16 v[36:39], v[154:157], v[220:223], v[36:39]
	v_mfma_f32_16x16x32_bf16 v[32:35], v[162:165], v[220:223], v[32:35]
	s_setprio 0
	s_setprio 1
	v_mfma_f32_16x16x32_bf16 v[124:127], v[176:179], v[192:195], v[124:127]
	v_mfma_f32_16x16x32_bf16 v[120:123], v[184:187], v[192:195], v[120:123]
	v_mfma_f32_16x16x32_bf16 v[116:119], v[176:179], v[200:203], v[116:119]
	v_mfma_f32_16x16x32_bf16 v[112:115], v[184:187], v[200:203], v[112:115]
	v_mfma_f32_16x16x32_bf16 v[108:111], v[176:179], v[208:211], v[108:111]
	v_mfma_f32_16x16x32_bf16 v[104:107], v[184:187], v[208:211], v[104:107]
	v_mfma_f32_16x16x32_bf16 v[100:103], v[176:179], v[216:219], v[100:103]
	v_mfma_f32_16x16x32_bf16 v[96:99], v[184:187], v[216:219], v[96:99]
	v_mfma_f32_16x16x32_bf16 v[124:127], v[180:183], v[196:199], v[124:127]
	v_mfma_f32_16x16x32_bf16 v[120:123], v[188:191], v[196:199], v[120:123]
	v_mfma_f32_16x16x32_bf16 v[116:119], v[180:183], v[204:207], v[116:119]
	v_mfma_f32_16x16x32_bf16 v[112:115], v[188:191], v[204:207], v[112:115]
	v_mfma_f32_16x16x32_bf16 v[108:111], v[180:183], v[212:215], v[108:111]
	v_mfma_f32_16x16x32_bf16 v[104:107], v[188:191], v[212:215], v[104:107]
	v_mfma_f32_16x16x32_bf16 v[100:103], v[180:183], v[220:223], v[100:103]
	v_mfma_f32_16x16x32_bf16 v[96:99], v[188:191], v[220:223], v[96:99]
	s_setprio 0
	s_barrier
	s_add_i32 s46, s66, s75
	v_lshl_add_u64 v[224:225], s[4:5], 0, v[130:131]
	s_mov_b32 m0, s46
	ds_read_b128 v[192:195], v174 offset:16384
	ds_read_b128 v[196:199], v174 offset:17408
	ds_read_b128 v[200:203], v174 offset:18432
	ds_read_b128 v[204:207], v174 offset:19456
	ds_read_b128 v[208:211], v174 offset:20480
	ds_read_b128 v[212:215], v174 offset:21504
	ds_read_b128 v[216:219], v174 offset:22528
	ds_read_b128 v[220:223], v174 offset:23552
	global_load_lds_dwordx4 v[224:225], off
	s_add_i32 m0, s46, 0x2000
	s_add_u32 s46, s4, 0x40000
	v_lshl_add_u64 v[226:227], s[4:5], 0, v[134:135]
	s_addc_u32 s47, s5, 0
	s_add_i32 s48, s67, s75
	global_load_lds_dwordx4 v[226:227], off
	v_lshl_add_u64 v[228:229], s[46:47], 0, v[130:131]
	s_mov_b32 m0, s48
	v_lshl_add_u64 v[230:231], s[14:15], 0, v[132:133]
	global_load_lds_dwordx4 v[228:229], off
	v_lshl_add_u64 v[228:229], s[46:47], 0, v[134:135]
	s_add_i32 m0, s48, 0x2000
	s_nop 0
	global_load_lds_dwordx4 v[228:229], off
	v_lshl_add_u64 v[228:229], s[14:15], 0, v[128:129]
	s_mov_b32 m0, s23
	s_nop 0
	global_load_lds_dwordx4 v[228:229], off
	s_mov_b32 m0, s56
	s_nop 0
	global_load_lds_dwordx4 v[230:231], off
	s_waitcnt vmcnt(8)
	s_waitcnt lgkmcnt(0)
	s_barrier
; #define PG8_STAGE(bufoff, gbase, voff) do { _Pragma("unroll") for (int _i = 0; _i < 2; ++_i) \
;         __builtin_amdgcn_global_load_lds((const unsigned*)((const char*)(gbase) + (voff)[_i]), (LAS unsigned*)(lds + (bufoff) + ldsw + _i * 8192), 16, 0, 0); } while (0)
; #define PG8_LDA(dst, b, h) do { _Pragma("unroll") for (int m = 0; m < 4; ++m) _Pragma("unroll") for (int k = 0; k < 2; ++k) dst[m][k] = *(const LAS bf16x8*)(lds + PG8_SA(b, h) + aoff + m * 2048 + k * 1024); } while (0)
; #define PG8_LDB(dst, b, h) do { _Pragma("unroll") for (int n = 0; n < 2; ++n) _Pragma("unroll") for (int k = 0; k < 2; ++k) dst[n][k] = *(const LAS bf16x8*)(lds + PG8_SB(b, h) + boff + n * 2048 + k * 1024); } while (0)
; #define PG8_MMA(ai, bj, At, Bt) do { __builtin_amdgcn_s_setprio(1); _Pragma("unroll") for (int m = 0; m < 4; ++m) _Pragma("unroll") for (int n = 0; n < 2; ++n) _Pragma("unroll") for (int k = 0; k < 2; ++k) \
;         acc[ai][bj][m][n] = __builtin_amdgcn_mfma_f32_16x16x32_bf16(Bt[n][k], At[m][k], acc[ai][bj][m][n], 0, 0, 0); __builtin_amdgcn_s_setprio(0); } while (0)
; #define PG8_WAIT_V(n) asm volatile("s_waitcnt vmcnt(" #n ")" ::: "memory")
; #define PG8_WAIT_L(n) asm volatile("s_waitcnt lgkmcnt(" #n ")" ::: "memory")
; #define PG8_BAR __builtin_amdgcn_s_barrier()
; #define PG8_SCHED __builtin_amdgcn_sched_barrier(0)
; template <class Epi, class Sched>
; __device__ __forceinline__ void gemm_phase(LAS unsigned char* lds, const Gemm g, const Sched& S, const Epi& E, int wid) {
;     ...
;             PG8_WAIT_V(8); PG8_WAIT_L(0); PG8_BAR; PG8_MMA(1, 0, At, B0); PG8_MMA(1, 1, At, B1); PG8_BAR; PG8_SCHED;
;             PG8_LDB(B0, 1, 0); PG8_LDB(B1, 1, 1); PG8_SCHED; PG8_LDA(At, 1, 0); PG8_STAGE(PG8_SA(0, 1), a2 + hstep, voffA);
;             PG8_WAIT_V(8); PG8_WAIT_L(0); PG8_BAR; PG8_MMA(0, 0, At, B0); PG8_MMA(0, 1, At, B1); PG8_BAR; PG8_SCHED;
	s_setprio 1
	s_waitcnt lgkmcnt(0)
	v_mfma_f32_16x16x32_bf16 v[28:31], v[150:153], v[192:195], v[28:31]
	v_mfma_f32_16x16x32_bf16 v[24:27], v[158:161], v[192:195], v[24:27]
	v_mfma_f32_16x16x32_bf16 v[20:23], v[150:153], v[200:203], v[20:23]
	v_mfma_f32_16x16x32_bf16 v[16:19], v[158:161], v[200:203], v[16:19]
	v_mfma_f32_16x16x32_bf16 v[12:15], v[150:153], v[208:211], v[12:15]
	v_mfma_f32_16x16x32_bf16 v[8:11], v[158:161], v[208:211], v[8:11]
	v_mfma_f32_16x16x32_bf16 v[4:7], v[150:153], v[216:219], v[4:7]
	v_mfma_f32_16x16x32_bf16 v[0:3], v[158:161], v[216:219], v[0:3]
	v_mfma_f32_16x16x32_bf16 v[28:31], v[154:157], v[196:199], v[28:31]
	v_mfma_f32_16x16x32_bf16 v[24:27], v[162:165], v[196:199], v[24:27]
	v_mfma_f32_16x16x32_bf16 v[20:23], v[154:157], v[204:207], v[20:23]
	v_mfma_f32_16x16x32_bf16 v[16:19], v[162:165], v[204:207], v[16:19]
	v_mfma_f32_16x16x32_bf16 v[12:15], v[154:157], v[212:215], v[12:15]
	v_mfma_f32_16x16x32_bf16 v[8:11], v[162:165], v[212:215], v[8:11]
	v_mfma_f32_16x16x32_bf16 v[4:7], v[154:157], v[220:223], v[4:7]
	v_mfma_f32_16x16x32_bf16 v[0:3], v[162:165], v[220:223], v[0:3]
	s_setprio 0
	s_setprio 1
	v_mfma_f32_16x16x32_bf16 v[92:95], v[176:179], v[192:195], v[92:95]
	v_mfma_f32_16x16x32_bf16 v[88:91], v[184:187], v[192:195], v[88:91]
	v_mfma_f32_16x16x32_bf16 v[84:87], v[176:179], v[200:203], v[84:87]
	v_mfma_f32_16x16x32_bf16 v[80:83], v[184:187], v[200:203], v[80:83]
	v_mfma_f32_16x16x32_bf16 v[76:79], v[176:179], v[208:211], v[76:79]
	v_mfma_f32_16x16x32_bf16 v[72:75], v[184:187], v[208:211], v[72:75]
	v_mfma_f32_16x16x32_bf16 v[68:71], v[176:179], v[216:219], v[68:71]
	v_mfma_f32_16x16x32_bf16 v[64:67], v[184:187], v[216:219], v[64:67]
	v_mfma_f32_16x16x32_bf16 v[92:95], v[180:183], v[196:199], v[92:95]
	v_mfma_f32_16x16x32_bf16 v[88:91], v[188:191], v[196:199], v[88:91]
	v_mfma_f32_16x16x32_bf16 v[84:87], v[180:183], v[204:207], v[84:87]
	v_mfma_f32_16x16x32_bf16 v[80:83], v[188:191], v[204:207], v[80:83]
	v_mfma_f32_16x16x32_bf16 v[76:79], v[180:183], v[212:215], v[76:79]
	v_mfma_f32_16x16x32_bf16 v[72:75], v[188:191], v[212:215], v[72:75]
	v_mfma_f32_16x16x32_bf16 v[68:71], v[180:183], v[220:223], v[68:71]
	v_mfma_f32_16x16x32_bf16 v[64:67], v[188:191], v[220:223], v[64:67]
	s_setprio 0
	s_barrier
	s_add_i32 s46, 0, 0x18000
	v_add_u32_e32 v136, s46, v170
	s_add_i32 s47, 0, 0x1c000
	ds_read_b128 v[150:153], v136
	ds_read_b128 v[154:157], v136 offset:1024
	ds_read_b128 v[158:161], v136 offset:2048
	ds_read_b128 v[162:165], v136 offset:3072
	v_add_u32_e32 v136, s47, v170
	ds_read_b128 v[176:179], v136
	ds_read_b128 v[180:183], v136 offset:1024
	ds_read_b128 v[184:187], v136 offset:2048
	ds_read_b128 v[188:191], v136 offset:3072
	s_add_u32 s14, s14, 0x40000
	s_addc_u32 s15, s15, 0
	s_mov_b32 m0, s57
	v_lshl_add_u64 v[232:233], s[14:15], 0, v[128:129]
	ds_read_b128 v[192:195], v174 offset:32768
	ds_read_b128 v[196:199], v174 offset:33792
	ds_read_b128 v[200:203], v174 offset:34816
	ds_read_b128 v[204:207], v174 offset:35840
	ds_read_b128 v[208:211], v174 offset:36864
	ds_read_b128 v[212:215], v174 offset:37888
	ds_read_b128 v[216:219], v174 offset:38912
	ds_read_b128 v[220:223], v174 offset:39936
	global_load_lds_dwordx4 v[232:233], off
	v_lshl_add_u64 v[232:233], s[14:15], 0, v[132:133]
	s_mov_b32 m0, s58
	s_nop 0
	global_load_lds_dwordx4 v[232:233], off
	s_waitcnt vmcnt(8)
	s_waitcnt lgkmcnt(0)
	s_barrier
	s_setprio 1
	s_waitcnt lgkmcnt(0)
	v_mfma_f32_16x16x32_bf16 v[60:63], v[150:153], v[192:195], v[60:63]
	v_mfma_f32_16x16x32_bf16 v[56:59], v[158:161], v[192:195], v[56:59]
	v_mfma_f32_16x16x32_bf16 v[52:55], v[150:153], v[200:203], v[52:55]
	v_mfma_f32_16x16x32_bf16 v[48:51], v[158:161], v[200:203], v[48:51]
	v_mfma_f32_16x16x32_bf16 v[44:47], v[150:153], v[208:211], v[44:47]
	v_mfma_f32_16x16x32_bf16 v[40:43], v[158:161], v[208:211], v[40:43]
	v_mfma_f32_16x16x32_bf16 v[36:39], v[150:153], v[216:219], v[36:39]
	v_mfma_f32_16x16x32_bf16 v[32:35], v[158:161], v[216:219], v[32:35]
	v_mfma_f32_16x16x32_bf16 v[60:63], v[154:157], v[196:199], v[60:63]
	v_mfma_f32_16x16x32_bf16 v[56:59], v[162:165], v[196:199], v[56:59]
	v_mfma_f32_16x16x32_bf16 v[52:55], v[154:157], v[204:207], v[52:55]
	v_mfma_f32_16x16x32_bf16 v[48:51], v[162:165], v[204:207], v[48:51]
	v_mfma_f32_16x16x32_bf16 v[44:47], v[154:157], v[212:215], v[44:47]
	v_mfma_f32_16x16x32_bf16 v[40:43], v[162:165], v[212:215], v[40:43]
	v_mfma_f32_16x16x32_bf16 v[36:39], v[154:157], v[220:223], v[36:39]
	v_mfma_f32_16x16x32_bf16 v[32:35], v[162:165], v[220:223], v[32:35]
	s_setprio 0
	s_setprio 1
	v_mfma_f32_16x16x32_bf16 v[124:127], v[176:179], v[192:195], v[124:127]
	v_mfma_f32_16x16x32_bf16 v[120:123], v[184:187], v[192:195], v[120:123]
	v_mfma_f32_16x16x32_bf16 v[116:119], v[176:179], v[200:203], v[116:119]
	v_mfma_f32_16x16x32_bf16 v[112:115], v[184:187], v[200:203], v[112:115]
	v_mfma_f32_16x16x32_bf16 v[108:111], v[176:179], v[208:211], v[108:111]
	v_mfma_f32_16x16x32_bf16 v[104:107], v[184:187], v[208:211], v[104:107]
	v_mfma_f32_16x16x32_bf16 v[100:103], v[176:179], v[216:219], v[100:103]
	v_mfma_f32_16x16x32_bf16 v[96:99], v[184:187], v[216:219], v[96:99]
	v_mfma_f32_16x16x32_bf16 v[124:127], v[180:183], v[196:199], v[124:127]
	v_mfma_f32_16x16x32_bf16 v[120:123], v[188:191], v[196:199], v[120:123]
	v_mfma_f32_16x16x32_bf16 v[116:119], v[180:183], v[204:207], v[116:119]
	v_mfma_f32_16x16x32_bf16 v[112:115], v[188:191], v[204:207], v[112:115]
	v_mfma_f32_16x16x32_bf16 v[108:111], v[180:183], v[212:215], v[108:111]
	v_mfma_f32_16x16x32_bf16 v[104:107], v[188:191], v[212:215], v[104:107]
	v_mfma_f32_16x16x32_bf16 v[100:103], v[180:183], v[220:223], v[100:103]
	v_mfma_f32_16x16x32_bf16 v[96:99], v[188:191], v[220:223], v[96:99]
	s_setprio 0
	s_barrier
; #define PG8_STAGE(bufoff, gbase, voff) do { _Pragma("unroll") for (int _i = 0; _i < 2; ++_i) \
;         __builtin_amdgcn_global_load_lds((const unsigned*)((const char*)(gbase) + (voff)[_i]), (LAS unsigned*)(lds + (bufoff) + ldsw + _i * 8192), 16, 0, 0); } while (0)
; #define PG8_LDA(dst, b, h) do { _Pragma("unroll") for (int m = 0; m < 4; ++m) _Pragma("unroll") for (int k = 0; k < 2; ++k) dst[m][k] = *(const LAS bf16x8*)(lds + PG8_SA(b, h) + aoff + m * 2048 + k * 1024); } while (0)
; #define PG8_MMA(ai, bj, At, Bt) do { __builtin_amdgcn_s_setprio(1); _Pragma("unroll") for (int m = 0; m < 4; ++m) _Pragma("unroll") for (int n = 0; n < 2; ++n) _Pragma("unroll") for (int k = 0; k < 2; ++k) \
;         acc[ai][bj][m][n] = __builtin_amdgcn_mfma_f32_16x16x32_bf16(Bt[n][k], At[m][k], acc[ai][bj][m][n], 0, 0, 0); __builtin_amdgcn_s_setprio(0); } while (0)
; #define PG8_WAIT_V(n) asm volatile("s_waitcnt vmcnt(" #n ")" ::: "memory")
; #define PG8_WAIT_L(n) asm volatile("s_waitcnt lgkmcnt(" #n ")" ::: "memory")
; #define PG8_BAR __builtin_amdgcn_s_barrier()
; #define PG8_SCHED __builtin_amdgcn_sched_barrier(0)
; template <class Epi, class Sched>
; __device__ __forceinline__ void gemm_phase(LAS unsigned char* lds, const Gemm g, const Sched& S, const Epi& E, int wid) {
;     ...
;             PG8_LDA(At, 1, 1); PG8_STAGE(PG8_SB(1, 0), b3, voffB); PG8_STAGE(PG8_SB(1, 1), b3 + hstep, voffB); PG8_STAGE(PG8_SA(1, 0), a3, voffA);
;             PG8_WAIT_V(8); PG8_WAIT_L(0); PG8_BAR; PG8_MMA(1, 0, At, B0); PG8_MMA(1, 1, At, B1); PG8_BAR; PG8_SCHED;
;         }
	s_add_i32 s14, s46, s75
	v_lshl_add_u64 v[224:225], v[224:225], 0, s[20:21]
	s_mov_b32 m0, s14
	ds_read_b128 v[192:195], v174 offset:49152
	ds_read_b128 v[196:199], v174 offset:50176
	ds_read_b128 v[200:203], v174 offset:51200
	ds_read_b128 v[204:207], v174 offset:52224
	ds_read_b128 v[208:211], v174 offset:53248
	ds_read_b128 v[212:215], v174 offset:54272
	ds_read_b128 v[216:219], v174 offset:55296
	ds_read_b128 v[220:223], v174 offset:56320
	global_load_lds_dwordx4 v[224:225], off
	s_add_i32 m0, s14, 0x2000
	s_add_u32 s4, s4, 0x40080
	v_lshl_add_u64 v[224:225], v[226:227], 0, s[20:21]
	s_addc_u32 s5, s5, 0
	s_add_i32 s14, s47, s75
	global_load_lds_dwordx4 v[224:225], off
	v_lshl_add_u64 v[224:225], s[4:5], 0, v[130:131]
	s_mov_b32 m0, s14
	s_nop 0
	global_load_lds_dwordx4 v[224:225], off
	v_lshl_add_u64 v[224:225], s[4:5], 0, v[134:135]
	s_add_i32 m0, s14, 0x2000
	s_nop 0
	global_load_lds_dwordx4 v[224:225], off
	v_lshl_add_u64 v[224:225], v[228:229], 0, s[20:21]
	s_mov_b32 m0, s61
	s_nop 0
	global_load_lds_dwordx4 v[224:225], off
	v_lshl_add_u64 v[224:225], v[230:231], 0, s[20:21]
	s_mov_b32 m0, s62
	s_nop 0
	global_load_lds_dwordx4 v[224:225], off
	s_waitcnt vmcnt(8)
	s_waitcnt lgkmcnt(0)
	s_barrier
	s_setprio 1
	s_waitcnt lgkmcnt(0)
	v_mfma_f32_16x16x32_bf16 v[28:31], v[150:153], v[192:195], v[28:31]
	v_mfma_f32_16x16x32_bf16 v[24:27], v[158:161], v[192:195], v[24:27]
	v_mfma_f32_16x16x32_bf16 v[20:23], v[150:153], v[200:203], v[20:23]
	v_mfma_f32_16x16x32_bf16 v[16:19], v[158:161], v[200:203], v[16:19]
	v_mfma_f32_16x16x32_bf16 v[12:15], v[150:153], v[208:211], v[12:15]
	v_mfma_f32_16x16x32_bf16 v[8:11], v[158:161], v[208:211], v[8:11]
	v_mfma_f32_16x16x32_bf16 v[4:7], v[150:153], v[216:219], v[4:7]
	v_mfma_f32_16x16x32_bf16 v[0:3], v[158:161], v[216:219], v[0:3]
	v_mfma_f32_16x16x32_bf16 v[28:31], v[154:157], v[196:199], v[28:31]
	v_mfma_f32_16x16x32_bf16 v[24:27], v[162:165], v[196:199], v[24:27]
	v_mfma_f32_16x16x32_bf16 v[20:23], v[154:157], v[204:207], v[20:23]
	v_mfma_f32_16x16x32_bf16 v[16:19], v[162:165], v[204:207], v[16:19]
	v_mfma_f32_16x16x32_bf16 v[12:15], v[154:157], v[212:215], v[12:15]
	v_mfma_f32_16x16x32_bf16 v[8:11], v[162:165], v[212:215], v[8:11]
	v_mfma_f32_16x16x32_bf16 v[4:7], v[154:157], v[220:223], v[4:7]
	v_mfma_f32_16x16x32_bf16 v[0:3], v[162:165], v[220:223], v[0:3]
	s_setprio 0
	s_setprio 1
	v_mfma_f32_16x16x32_bf16 v[92:95], v[176:179], v[192:195], v[92:95]
	v_mfma_f32_16x16x32_bf16 v[88:91], v[184:187], v[192:195], v[88:91]
	v_mfma_f32_16x16x32_bf16 v[84:87], v[176:179], v[200:203], v[84:87]
	v_mfma_f32_16x16x32_bf16 v[80:83], v[184:187], v[200:203], v[80:83]
	v_mfma_f32_16x16x32_bf16 v[76:79], v[176:179], v[208:211], v[76:79]
	v_mfma_f32_16x16x32_bf16 v[72:75], v[184:187], v[208:211], v[72:75]
	v_mfma_f32_16x16x32_bf16 v[68:71], v[176:179], v[216:219], v[68:71]
	v_mfma_f32_16x16x32_bf16 v[64:67], v[184:187], v[216:219], v[64:67]
	v_mfma_f32_16x16x32_bf16 v[92:95], v[180:183], v[196:199], v[92:95]
	v_mfma_f32_16x16x32_bf16 v[88:91], v[188:191], v[196:199], v[88:91]
	v_mfma_f32_16x16x32_bf16 v[84:87], v[180:183], v[204:207], v[84:87]
	v_mfma_f32_16x16x32_bf16 v[80:83], v[188:191], v[204:207], v[80:83]
	v_mfma_f32_16x16x32_bf16 v[76:79], v[180:183], v[212:215], v[76:79]
	v_mfma_f32_16x16x32_bf16 v[72:75], v[188:191], v[212:215], v[72:75]
	v_mfma_f32_16x16x32_bf16 v[68:71], v[180:183], v[220:223], v[68:71]
	v_mfma_f32_16x16x32_bf16 v[64:67], v[188:191], v[220:223], v[64:67]
	s_setprio 0
	s_add_i32 s45, s45, 2
	s_add_u32 s6, s6, 0x100
	s_addc_u32 s7, s7, 0
	s_add_u32 s43, s43, 0x100
	s_addc_u32 s44, s44, 0
	s_cmp_gt_u32 s45, 13
	s_barrier
	s_cbranch_scc0 .LBB0_743
	s_and_b64 vcc, exec, s[24:25]
	s_cbranch_vccz .LBB0_746
	s_barrier

; #define PG8_STAGE(bufoff, gbase, voff) do { _Pragma("unroll") for (int _i = 0; _i < 2; ++_i) \
;         __builtin_amdgcn_global_load_lds((const unsigned*)((const char*)(gbase) + (voff)[_i]), (LAS unsigned*)(lds + (bufoff) + ldsw + _i * 8192), 16, 0, 0); } while (0)
; #define PG8_LDA(dst, b, h) do { _Pragma("unroll") for (int m = 0; m < 4; ++m) _Pragma("unroll") for (int k = 0; k < 2; ++k) dst[m][k] = *(const LAS bf16x8*)(lds + PG8_SA(b, h) + aoff + m * 2048 + k * 1024); } while (0)
; #define PG8_LDB(dst, b, h) do { _Pragma("unroll") for (int n = 0; n < 2; ++n) _Pragma("unroll") for (int k = 0; k < 2; ++k) dst[n][k] = *(const LAS bf16x8*)(lds + PG8_SB(b, h) + boff + n * 2048 + k * 1024); } while (0)
; #define PG8_MMA(ai, bj, At, Bt) do { __builtin_amdgcn_s_setprio(1); _Pragma("unroll") for (int m = 0; m < 4; ++m) _Pragma("unroll") for (int n = 0; n < 2; ++n) _Pragma("unroll") for (int k = 0; k < 2; ++k) \
;         acc[ai][bj][m][n] = __builtin_amdgcn_mfma_f32_16x16x32_bf16(Bt[n][k], At[m][k], acc[ai][bj][m][n], 0, 0, 0); __builtin_amdgcn_s_setprio(0); } while (0)
; #define PG8_WAIT_V(n) asm volatile("s_waitcnt vmcnt(" #n ")" ::: "memory")
; #define PG8_WAIT_L(n) asm volatile("s_waitcnt lgkmcnt(" #n ")" ::: "memory")
; #define PG8_BAR __builtin_amdgcn_s_barrier()
; #define PG8_SCHED __builtin_amdgcn_sched_barrier(0)
; template <class Epi, class Sched>
; __device__ __forceinline__ void gemm_phase(LAS unsigned char* lds, const Gemm g, const Sched& S, const Epi& E, int wid) {
;     ...
;             PG8_LDB(B0, 0, 0); PG8_LDB(B1, 0, 1); PG8_SCHED; PG8_LDA(At, 0, 0); PG8_STAGE(PG8_SA(1, 1), a1 + hstep, voffA);
;             PG8_WAIT_V(8); PG8_WAIT_L(0); PG8_BAR; PG8_MMA(0, 0, At, B0); PG8_MMA(0, 1, At, B1); PG8_BAR; PG8_SCHED;
;             PG8_LDA(At, 0, 1); PG8_STAGE(PG8_SB(0, 0), b2, voffB); PG8_STAGE(PG8_SB(0, 1), b2 + hstep, voffB); PG8_STAGE(PG8_SA(0, 0), a2, voffA);
;             PG8_WAIT_V(8); PG8_WAIT_L(0); PG8_BAR; PG8_MMA(1, 0, At, B0); PG8_MMA(1, 1, At, B1); PG8_BAR; PG8_SCHED;
.LBB0_1909:
	v_add_u32_e32 v1, s48, v165
	ds_read_b128 v[132:135], v1
	ds_read_b128 v[136:139], v1 offset:1024
	ds_read_b128 v[140:143], v1 offset:2048
	ds_read_b128 v[176:179], v1 offset:3072
	v_add_u32_e32 v1, s49, v165
	ds_read_b128 v[180:183], v1
	ds_read_b128 v[184:187], v1 offset:1024
	ds_read_b128 v[188:191], v1 offset:2048
	ds_read_b128 v[192:195], v1 offset:3072
	s_add_u32 s36, s4, 0xfffc0080
	s_addc_u32 s37, s5, -1
	s_cmp_eq_u32 s56, 12
	s_cselect_b32 s41, s29, s37
	s_cselect_b32 s40, s39, s36
	s_cselect_b32 s37, s27, s55
	s_cselect_b32 s36, s53, s54
	v_lshl_add_u64 v[2:3], s[4:5], 0, v[156:157]
	s_add_i32 m0, s3, 0xc000
	ds_read_b128 v[196:199], v175
	ds_read_b128 v[200:203], v175 offset:1024
	ds_read_b128 v[204:207], v175 offset:2048
	ds_read_b128 v[208:211], v175 offset:3072
	ds_read_b128 v[212:215], v175 offset:4096
	ds_read_b128 v[216:219], v175 offset:5120
	ds_read_b128 v[220:223], v175 offset:6144
	ds_read_b128 v[224:227], v175 offset:7168
	global_load_lds_dwordx4 v[2:3], off
	v_lshl_add_u64 v[2:3], s[4:5], 0, v[158:159]
	s_add_i32 m0, s3, 0xe000
	s_nop 0
	global_load_lds_dwordx4 v[2:3], off
	s_waitcnt vmcnt(8)
	s_waitcnt lgkmcnt(0)
	s_barrier
	s_setprio 1
	s_waitcnt lgkmcnt(0)
	v_mfma_f32_16x16x32_bf16 v[128:131], v[132:135], v[196:199], v[128:131]
	v_mfma_f32_16x16x32_bf16 v[124:127], v[140:143], v[196:199], v[124:127]
	v_mfma_f32_16x16x32_bf16 v[120:123], v[132:135], v[204:207], v[120:123]
	v_mfma_f32_16x16x32_bf16 v[116:119], v[140:143], v[204:207], v[116:119]
	v_mfma_f32_16x16x32_bf16 v[112:115], v[132:135], v[212:215], v[112:115]
	v_mfma_f32_16x16x32_bf16 v[108:111], v[140:143], v[212:215], v[108:111]
	v_mfma_f32_16x16x32_bf16 v[104:107], v[132:135], v[220:223], v[104:107]
	v_mfma_f32_16x16x32_bf16 v[100:103], v[140:143], v[220:223], v[100:103]
	v_mfma_f32_16x16x32_bf16 v[128:131], v[136:139], v[200:203], v[128:131]
	v_mfma_f32_16x16x32_bf16 v[124:127], v[176:179], v[200:203], v[124:127]
	v_mfma_f32_16x16x32_bf16 v[120:123], v[136:139], v[208:211], v[120:123]
	v_mfma_f32_16x16x32_bf16 v[116:119], v[176:179], v[208:211], v[116:119]
	v_mfma_f32_16x16x32_bf16 v[112:115], v[136:139], v[216:219], v[112:115]
	v_mfma_f32_16x16x32_bf16 v[108:111], v[176:179], v[216:219], v[108:111]
	v_mfma_f32_16x16x32_bf16 v[104:107], v[136:139], v[224:227], v[104:107]
	v_mfma_f32_16x16x32_bf16 v[100:103], v[176:179], v[224:227], v[100:103]
	s_setprio 0
	s_setprio 1
	v_mfma_f32_16x16x32_bf16 v[96:99], v[180:183], v[196:199], v[96:99]
	v_mfma_f32_16x16x32_bf16 v[92:95], v[188:191], v[196:199], v[92:95]
	v_mfma_f32_16x16x32_bf16 v[88:91], v[180:183], v[204:207], v[88:91]
	v_mfma_f32_16x16x32_bf16 v[84:87], v[188:191], v[204:207], v[84:87]
	v_mfma_f32_16x16x32_bf16 v[80:83], v[180:183], v[212:215], v[80:83]
	v_mfma_f32_16x16x32_bf16 v[76:79], v[188:191], v[212:215], v[76:79]
	v_mfma_f32_16x16x32_bf16 v[72:75], v[180:183], v[220:223], v[72:75]
	v_mfma_f32_16x16x32_bf16 v[68:71], v[188:191], v[220:223], v[68:71]
	v_mfma_f32_16x16x32_bf16 v[96:99], v[184:187], v[200:203], v[96:99]
	v_mfma_f32_16x16x32_bf16 v[92:95], v[192:195], v[200:203], v[92:95]
	v_mfma_f32_16x16x32_bf16 v[88:91], v[184:187], v[208:211], v[88:91]
	v_mfma_f32_16x16x32_bf16 v[84:87], v[192:195], v[208:211], v[84:87]
	v_mfma_f32_16x16x32_bf16 v[80:83], v[184:187], v[216:219], v[80:83]
	v_mfma_f32_16x16x32_bf16 v[76:79], v[192:195], v[216:219], v[76:79]
	v_mfma_f32_16x16x32_bf16 v[72:75], v[184:187], v[224:227], v[72:75]
	v_mfma_f32_16x16x32_bf16 v[68:71], v[192:195], v[224:227], v[68:71]
	s_setprio 0
	s_barrier
	s_add_i32 s57, s48, s75
	v_lshl_add_u64 v[228:229], s[36:37], 0, v[146:147]
	s_mov_b32 m0, s57
	ds_read_b128 v[196:199], v175 offset:16384
	ds_read_b128 v[200:203], v175 offset:17408
	ds_read_b128 v[204:207], v175 offset:18432
	ds_read_b128 v[208:211], v175 offset:19456
	ds_read_b128 v[212:215], v175 offset:20480
	ds_read_b128 v[216:219], v175 offset:21504
	ds_read_b128 v[220:223], v175 offset:22528
	ds_read_b128 v[224:227], v175 offset:23552
	global_load_lds_dwordx4 v[228:229], off
	s_add_i32 m0, s57, 0x2000
	s_add_u32 s58, s36, 0x40000
	v_lshl_add_u64 v[230:231], s[36:37], 0, v[150:151]
	s_addc_u32 s59, s37, 0
	s_add_i32 s57, s49, s75
	global_load_lds_dwordx4 v[230:231], off
	v_lshl_add_u64 v[2:3], s[58:59], 0, v[146:147]
	s_mov_b32 m0, s57
	v_lshl_add_u64 v[232:233], s[40:41], 0, v[144:145]
	global_load_lds_dwordx4 v[2:3], off
	v_lshl_add_u64 v[2:3], s[58:59], 0, v[150:151]
	s_add_i32 m0, s57, 0x2000
	v_lshl_add_u64 v[234:235], s[40:41], 0, v[148:149]
	global_load_lds_dwordx4 v[2:3], off
	s_mov_b32 m0, s3
	s_nop 0
	global_load_lds_dwordx4 v[232:233], off
	s_mov_b32 m0, s42
	s_nop 0
	global_load_lds_dwordx4 v[234:235], off
	s_waitcnt vmcnt(8)
	s_waitcnt lgkmcnt(0)
	s_barrier
; #define PG8_STAGE(bufoff, gbase, voff) do { _Pragma("unroll") for (int _i = 0; _i < 2; ++_i) \
;         __builtin_amdgcn_global_load_lds((const unsigned*)((const char*)(gbase) + (voff)[_i]), (LAS unsigned*)(lds + (bufoff) + ldsw + _i * 8192), 16, 0, 0); } while (0)
; #define PG8_LDA(dst, b, h) do { _Pragma("unroll") for (int m = 0; m < 4; ++m) _Pragma("unroll") for (int k = 0; k < 2; ++k) dst[m][k] = *(const LAS bf16x8*)(lds + PG8_SA(b, h) + aoff + m * 2048 + k * 1024); } while (0)
; #define PG8_LDB(dst, b, h) do { _Pragma("unroll") for (int n = 0; n < 2; ++n) _Pragma("unroll") for (int k = 0; k < 2; ++k) dst[n][k] = *(const LAS bf16x8*)(lds + PG8_SB(b, h) + boff + n * 2048 + k * 1024); } while (0)
; #define PG8_MMA(ai, bj, At, Bt) do { __builtin_amdgcn_s_setprio(1); _Pragma("unroll") for (int m = 0; m < 4; ++m) _Pragma("unroll") for (int n = 0; n < 2; ++n) _Pragma("unroll") for (int k = 0; k < 2; ++k) \
;         acc[ai][bj][m][n] = __builtin_amdgcn_mfma_f32_16x16x32_bf16(Bt[n][k], At[m][k], acc[ai][bj][m][n], 0, 0, 0); __builtin_amdgcn_s_setprio(0); } while (0)
; #define PG8_WAIT_V(n) asm volatile("s_waitcnt vmcnt(" #n ")" ::: "memory")
; #define PG8_WAIT_L(n) asm volatile("s_waitcnt lgkmcnt(" #n ")" ::: "memory")
; #define PG8_BAR __builtin_amdgcn_s_barrier()
; #define PG8_SCHED __builtin_amdgcn_sched_barrier(0)
; template <class Epi, class Sched>
; __device__ __forceinline__ void gemm_phase(LAS unsigned char* lds, const Gemm g, const Sched& S, const Epi& E, int wid) {
;     ...
;             PG8_WAIT_V(8); PG8_WAIT_L(0); PG8_BAR; PG8_MMA(1, 0, At, B0); PG8_MMA(1, 1, At, B1); PG8_BAR; PG8_SCHED;
;             PG8_LDB(B0, 1, 0); PG8_LDB(B1, 1, 1); PG8_SCHED; PG8_LDA(At, 1, 0); PG8_STAGE(PG8_SA(0, 1), a2 + hstep, voffA);
;             PG8_WAIT_V(8); PG8_WAIT_L(0); PG8_BAR; PG8_MMA(0, 0, At, B0); PG8_MMA(0, 1, At, B1); PG8_BAR; PG8_SCHED;
	s_setprio 1
	s_waitcnt lgkmcnt(0)
	v_mfma_f32_16x16x32_bf16 v[64:67], v[132:135], v[196:199], v[64:67]
	v_mfma_f32_16x16x32_bf16 v[60:63], v[140:143], v[196:199], v[60:63]
	v_mfma_f32_16x16x32_bf16 v[56:59], v[132:135], v[204:207], v[56:59]
	v_mfma_f32_16x16x32_bf16 v[52:55], v[140:143], v[204:207], v[52:55]
	v_mfma_f32_16x16x32_bf16 v[48:51], v[132:135], v[212:215], v[48:51]
	v_mfma_f32_16x16x32_bf16 v[44:47], v[140:143], v[212:215], v[44:47]
	v_mfma_f32_16x16x32_bf16 v[40:43], v[132:135], v[220:223], v[40:43]
	v_mfma_f32_16x16x32_bf16 v[36:39], v[140:143], v[220:223], v[36:39]
	v_mfma_f32_16x16x32_bf16 v[64:67], v[136:139], v[200:203], v[64:67]
	v_mfma_f32_16x16x32_bf16 v[60:63], v[176:179], v[200:203], v[60:63]
	v_mfma_f32_16x16x32_bf16 v[56:59], v[136:139], v[208:211], v[56:59]
	v_mfma_f32_16x16x32_bf16 v[52:55], v[176:179], v[208:211], v[52:55]
	v_mfma_f32_16x16x32_bf16 v[48:51], v[136:139], v[216:219], v[48:51]
	v_mfma_f32_16x16x32_bf16 v[44:47], v[176:179], v[216:219], v[44:47]
	v_mfma_f32_16x16x32_bf16 v[40:43], v[136:139], v[224:227], v[40:43]
	v_mfma_f32_16x16x32_bf16 v[36:39], v[176:179], v[224:227], v[36:39]
	s_setprio 0
	s_setprio 1
	v_mfma_f32_16x16x32_bf16 v[32:35], v[180:183], v[196:199], v[32:35]
	v_mfma_f32_16x16x32_bf16 v[28:31], v[188:191], v[196:199], v[28:31]
	v_mfma_f32_16x16x32_bf16 v[24:27], v[180:183], v[204:207], v[24:27]
	v_mfma_f32_16x16x32_bf16 v[20:23], v[188:191], v[204:207], v[20:23]
	v_mfma_f32_16x16x32_bf16 v[16:19], v[180:183], v[212:215], v[16:19]
	v_mfma_f32_16x16x32_bf16 v[12:15], v[188:191], v[212:215], v[12:15]
	v_mfma_f32_16x16x32_bf16 v[8:11], v[180:183], v[220:223], v[8:11]
	v_mfma_f32_16x16x32_bf16 v[2:5], v[188:191], v[220:223], v[4:7]
	v_mfma_f32_16x16x32_bf16 v[32:35], v[184:187], v[200:203], v[32:35]
	v_mfma_f32_16x16x32_bf16 v[28:31], v[192:195], v[200:203], v[28:31]
	v_mfma_f32_16x16x32_bf16 v[24:27], v[184:187], v[208:211], v[24:27]
	v_mfma_f32_16x16x32_bf16 v[20:23], v[192:195], v[208:211], v[20:23]
	v_mfma_f32_16x16x32_bf16 v[16:19], v[184:187], v[216:219], v[16:19]
	v_mfma_f32_16x16x32_bf16 v[12:15], v[192:195], v[216:219], v[12:15]
	v_mfma_f32_16x16x32_bf16 v[8:11], v[184:187], v[224:227], v[8:11]
	v_mfma_f32_16x16x32_bf16 v[2:5], v[192:195], v[224:227], v[2:5]
	s_setprio 0
	s_barrier
	s_add_i32 s57, 0, 0x18000
	v_add_u32_e32 v1, s57, v165
	s_add_i32 s58, 0, 0x1c000
	ds_read_b128 v[132:135], v1
	ds_read_b128 v[136:139], v1 offset:1024
	ds_read_b128 v[140:143], v1 offset:2048
	ds_read_b128 v[176:179], v1 offset:3072
	v_add_u32_e32 v1, s58, v165
	ds_read_b128 v[180:183], v1
	ds_read_b128 v[184:187], v1 offset:1024
	ds_read_b128 v[188:191], v1 offset:2048
	ds_read_b128 v[192:195], v1 offset:3072
	s_add_u32 s40, s40, 0x40000
	s_addc_u32 s41, s41, 0
	s_mov_b32 m0, s43
	v_lshl_add_u64 v[6:7], s[40:41], 0, v[144:145]
	ds_read_b128 v[196:199], v175 offset:32768
	ds_read_b128 v[200:203], v175 offset:33792
	ds_read_b128 v[204:207], v175 offset:34816
	ds_read_b128 v[208:211], v175 offset:35840
	ds_read_b128 v[212:215], v175 offset:36864
	ds_read_b128 v[216:219], v175 offset:37888
	ds_read_b128 v[220:223], v175 offset:38912
	ds_read_b128 v[224:227], v175 offset:39936
	global_load_lds_dwordx4 v[6:7], off
	v_lshl_add_u64 v[6:7], s[40:41], 0, v[148:149]
	s_mov_b32 m0, s44
	s_nop 0
	global_load_lds_dwordx4 v[6:7], off
	s_waitcnt vmcnt(8)
	s_waitcnt lgkmcnt(0)
	s_barrier
	s_setprio 1
	s_waitcnt lgkmcnt(0)
	v_mfma_f32_16x16x32_bf16 v[128:131], v[132:135], v[196:199], v[128:131]
	v_mfma_f32_16x16x32_bf16 v[124:127], v[140:143], v[196:199], v[124:127]
	v_mfma_f32_16x16x32_bf16 v[120:123], v[132:135], v[204:207], v[120:123]
	v_mfma_f32_16x16x32_bf16 v[116:119], v[140:143], v[204:207], v[116:119]
	v_mfma_f32_16x16x32_bf16 v[112:115], v[132:135], v[212:215], v[112:115]
	v_mfma_f32_16x16x32_bf16 v[108:111], v[140:143], v[212:215], v[108:111]
	v_mfma_f32_16x16x32_bf16 v[104:107], v[132:135], v[220:223], v[104:107]
	v_mfma_f32_16x16x32_bf16 v[100:103], v[140:143], v[220:223], v[100:103]
	v_mfma_f32_16x16x32_bf16 v[128:131], v[136:139], v[200:203], v[128:131]
	v_mfma_f32_16x16x32_bf16 v[124:127], v[176:179], v[200:203], v[124:127]
	v_mfma_f32_16x16x32_bf16 v[120:123], v[136:139], v[208:211], v[120:123]
	v_mfma_f32_16x16x32_bf16 v[116:119], v[176:179], v[208:211], v[116:119]
	v_mfma_f32_16x16x32_bf16 v[112:115], v[136:139], v[216:219], v[112:115]
	v_mfma_f32_16x16x32_bf16 v[108:111], v[176:179], v[216:219], v[108:111]
	v_mfma_f32_16x16x32_bf16 v[104:107], v[136:139], v[224:227], v[104:107]
	v_mfma_f32_16x16x32_bf16 v[100:103], v[176:179], v[224:227], v[100:103]
	s_setprio 0
	s_setprio 1
	v_mfma_f32_16x16x32_bf16 v[96:99], v[180:183], v[196:199], v[96:99]
	v_mfma_f32_16x16x32_bf16 v[92:95], v[188:191], v[196:199], v[92:95]
	v_mfma_f32_16x16x32_bf16 v[88:91], v[180:183], v[204:207], v[88:91]
	v_mfma_f32_16x16x32_bf16 v[84:87], v[188:191], v[204:207], v[84:87]
	v_mfma_f32_16x16x32_bf16 v[80:83], v[180:183], v[212:215], v[80:83]
	v_mfma_f32_16x16x32_bf16 v[76:79], v[188:191], v[212:215], v[76:79]
	v_mfma_f32_16x16x32_bf16 v[72:75], v[180:183], v[220:223], v[72:75]
	v_mfma_f32_16x16x32_bf16 v[68:71], v[188:191], v[220:223], v[68:71]
	v_mfma_f32_16x16x32_bf16 v[96:99], v[184:187], v[200:203], v[96:99]
	v_mfma_f32_16x16x32_bf16 v[92:95], v[192:195], v[200:203], v[92:95]
	v_mfma_f32_16x16x32_bf16 v[88:91], v[184:187], v[208:211], v[88:91]
	v_mfma_f32_16x16x32_bf16 v[84:87], v[192:195], v[208:211], v[84:87]
	v_mfma_f32_16x16x32_bf16 v[80:83], v[184:187], v[216:219], v[80:83]
	v_mfma_f32_16x16x32_bf16 v[76:79], v[192:195], v[216:219], v[76:79]
	v_mfma_f32_16x16x32_bf16 v[72:75], v[184:187], v[224:227], v[72:75]
	v_mfma_f32_16x16x32_bf16 v[68:71], v[192:195], v[224:227], v[68:71]
	s_setprio 0
	s_barrier
; #define PG8_STAGE(bufoff, gbase, voff) do { _Pragma("unroll") for (int _i = 0; _i < 2; ++_i) \
;         __builtin_amdgcn_global_load_lds((const unsigned*)((const char*)(gbase) + (voff)[_i]), (LAS unsigned*)(lds + (bufoff) + ldsw + _i * 8192), 16, 0, 0); } while (0)
; #define PG8_LDA(dst, b, h) do { _Pragma("unroll") for (int m = 0; m < 4; ++m) _Pragma("unroll") for (int k = 0; k < 2; ++k) dst[m][k] = *(const LAS bf16x8*)(lds + PG8_SA(b, h) + aoff + m * 2048 + k * 1024); } while (0)
; #define PG8_MMA(ai, bj, At, Bt) do { __builtin_amdgcn_s_setprio(1); _Pragma("unroll") for (int m = 0; m < 4; ++m) _Pragma("unroll") for (int n = 0; n < 2; ++n) _Pragma("unroll") for (int k = 0; k < 2; ++k) \
;         acc[ai][bj][m][n] = __builtin_amdgcn_mfma_f32_16x16x32_bf16(Bt[n][k], At[m][k], acc[ai][bj][m][n], 0, 0, 0); __builtin_amdgcn_s_setprio(0); } while (0)
; #define PG8_WAIT_V(n) asm volatile("s_waitcnt vmcnt(" #n ")" ::: "memory")
; #define PG8_WAIT_L(n) asm volatile("s_waitcnt lgkmcnt(" #n ")" ::: "memory")
; #define PG8_BAR __builtin_amdgcn_s_barrier()
; #define PG8_SCHED __builtin_amdgcn_sched_barrier(0)
; template <class Epi, class Sched>
; __device__ __forceinline__ void gemm_phase(LAS unsigned char* lds, const Gemm g, const Sched& S, const Epi& E, int wid) {
;     ...
;             PG8_LDA(At, 1, 1); PG8_STAGE(PG8_SB(1, 0), b3, voffB); PG8_STAGE(PG8_SB(1, 1), b3 + hstep, voffB); PG8_STAGE(PG8_SA(1, 0), a3, voffA);
;             PG8_WAIT_V(8); PG8_WAIT_L(0); PG8_BAR; PG8_MMA(1, 0, At, B0); PG8_MMA(1, 1, At, B1); PG8_BAR; PG8_SCHED;
;         }
	s_add_i32 s40, s57, s75
	v_lshl_add_u64 v[6:7], v[228:229], 0, s[22:23]
	s_mov_b32 m0, s40
	ds_read_b128 v[196:199], v175 offset:49152
	ds_read_b128 v[200:203], v175 offset:50176
	ds_read_b128 v[204:207], v175 offset:51200
	ds_read_b128 v[208:211], v175 offset:52224
	ds_read_b128 v[212:215], v175 offset:53248
	ds_read_b128 v[216:219], v175 offset:54272
	ds_read_b128 v[220:223], v175 offset:55296
	ds_read_b128 v[224:227], v175 offset:56320
	global_load_lds_dwordx4 v[6:7], off
	s_add_i32 m0, s40, 0x2000
	s_add_u32 s36, s36, 0x40080
	v_lshl_add_u64 v[6:7], v[230:231], 0, s[22:23]
	s_addc_u32 s37, s37, 0
	s_add_i32 s40, s58, s75
	global_load_lds_dwordx4 v[6:7], off
	v_lshl_add_u64 v[6:7], s[36:37], 0, v[146:147]
	s_mov_b32 m0, s40
	s_nop 0
	global_load_lds_dwordx4 v[6:7], off
	v_lshl_add_u64 v[6:7], s[36:37], 0, v[150:151]
	s_add_i32 m0, s40, 0x2000
	s_nop 0
	global_load_lds_dwordx4 v[6:7], off
	v_lshl_add_u64 v[6:7], v[232:233], 0, s[22:23]
	s_mov_b32 m0, s45
	s_nop 0
	global_load_lds_dwordx4 v[6:7], off
	v_lshl_add_u64 v[6:7], v[234:235], 0, s[22:23]
	s_mov_b32 m0, s46
	s_nop 0
	global_load_lds_dwordx4 v[6:7], off
	s_waitcnt vmcnt(8)
	s_waitcnt lgkmcnt(0)
	s_barrier
	s_setprio 1
	s_waitcnt lgkmcnt(0)
	v_mfma_f32_16x16x32_bf16 v[64:67], v[132:135], v[196:199], v[64:67]
	v_mfma_f32_16x16x32_bf16 v[60:63], v[140:143], v[196:199], v[60:63]
	v_mfma_f32_16x16x32_bf16 v[56:59], v[132:135], v[204:207], v[56:59]
	v_mfma_f32_16x16x32_bf16 v[52:55], v[140:143], v[204:207], v[52:55]
	v_mfma_f32_16x16x32_bf16 v[48:51], v[132:135], v[212:215], v[48:51]
	v_mfma_f32_16x16x32_bf16 v[44:47], v[140:143], v[212:215], v[44:47]
	v_mfma_f32_16x16x32_bf16 v[40:43], v[132:135], v[220:223], v[40:43]
	v_mfma_f32_16x16x32_bf16 v[36:39], v[140:143], v[220:223], v[36:39]
	v_mfma_f32_16x16x32_bf16 v[64:67], v[136:139], v[200:203], v[64:67]
	v_mfma_f32_16x16x32_bf16 v[60:63], v[176:179], v[200:203], v[60:63]
	v_mfma_f32_16x16x32_bf16 v[56:59], v[136:139], v[208:211], v[56:59]
	v_mfma_f32_16x16x32_bf16 v[52:55], v[176:179], v[208:211], v[52:55]
	v_mfma_f32_16x16x32_bf16 v[48:51], v[136:139], v[216:219], v[48:51]
	v_mfma_f32_16x16x32_bf16 v[44:47], v[176:179], v[216:219], v[44:47]
	v_mfma_f32_16x16x32_bf16 v[40:43], v[136:139], v[224:227], v[40:43]
	v_mfma_f32_16x16x32_bf16 v[36:39], v[176:179], v[224:227], v[36:39]
	s_setprio 0
	s_setprio 1
	v_mfma_f32_16x16x32_bf16 v[32:35], v[180:183], v[196:199], v[32:35]
	v_mfma_f32_16x16x32_bf16 v[28:31], v[188:191], v[196:199], v[28:31]
	v_mfma_f32_16x16x32_bf16 v[24:27], v[180:183], v[204:207], v[24:27]
	v_mfma_f32_16x16x32_bf16 v[20:23], v[188:191], v[204:207], v[20:23]
	v_mfma_f32_16x16x32_bf16 v[16:19], v[180:183], v[212:215], v[16:19]
	v_mfma_f32_16x16x32_bf16 v[12:15], v[188:191], v[212:215], v[12:15]
	v_mfma_f32_16x16x32_bf16 v[6:9], v[180:183], v[220:223], v[8:11]
	v_mfma_f32_16x16x32_bf16 v[2:5], v[188:191], v[220:223], v[2:5]
	v_mfma_f32_16x16x32_bf16 v[32:35], v[184:187], v[200:203], v[32:35]
	v_mfma_f32_16x16x32_bf16 v[28:31], v[192:195], v[200:203], v[28:31]
	v_mfma_f32_16x16x32_bf16 v[24:27], v[184:187], v[208:211], v[24:27]
	v_mfma_f32_16x16x32_bf16 v[20:23], v[192:195], v[208:211], v[20:23]
	v_mfma_f32_16x16x32_bf16 v[16:19], v[184:187], v[216:219], v[16:19]
	v_mfma_f32_16x16x32_bf16 v[12:15], v[192:195], v[216:219], v[12:15]
	v_mfma_f32_16x16x32_bf16 v[8:11], v[184:187], v[224:227], v[6:9]
	v_mfma_f32_16x16x32_bf16 v[4:7], v[192:195], v[224:227], v[2:5]
	s_setprio 0
	s_add_i32 s56, s56, 2
	s_add_u32 s4, s4, 0x100
	s_addc_u32 s5, s5, 0
	s_add_u32 s54, s54, 0x100
	s_addc_u32 s55, s55, 0
	s_cmp_gt_u32 s56, 13
	s_barrier
	s_cbranch_scc0 .LBB0_1909
	s_and_b64 vcc, exec, s[24:25]
	s_cbranch_vccz .LBB0_1912
	s_barrier

; #define PG8_STAGE(bufoff, gbase, voff) do { _Pragma("unroll") for (int _i = 0; _i < 2; ++_i) \
;         __builtin_amdgcn_global_load_lds((const unsigned*)((const char*)(gbase) + (voff)[_i]), (LAS unsigned*)(lds + (bufoff) + ldsw + _i * 8192), 16, 0, 0); } while (0)
; #define PG8_LDA(dst, b, h) do { _Pragma("unroll") for (int m = 0; m < 4; ++m) _Pragma("unroll") for (int k = 0; k < 2; ++k) dst[m][k] = *(const LAS bf16x8*)(lds + PG8_SA(b, h) + aoff + m * 2048 + k * 1024); } while (0)
; #define PG8_LDB(dst, b, h) do { _Pragma("unroll") for (int n = 0; n < 2; ++n) _Pragma("unroll") for (int k = 0; k < 2; ++k) dst[n][k] = *(const LAS bf16x8*)(lds + PG8_SB(b, h) + boff + n * 2048 + k * 1024); } while (0)
; #define PG8_MMA(ai, bj, At, Bt) do { __builtin_amdgcn_s_setprio(1); _Pragma("unroll") for (int m = 0; m < 4; ++m) _Pragma("unroll") for (int n = 0; n < 2; ++n) _Pragma("unroll") for (int k = 0; k < 2; ++k) \
;         acc[ai][bj][m][n] = __builtin_amdgcn_mfma_f32_16x16x32_bf16(Bt[n][k], At[m][k], acc[ai][bj][m][n], 0, 0, 0); __builtin_amdgcn_s_setprio(0); } while (0)
; #define PG8_WAIT_V(n) asm volatile("s_waitcnt vmcnt(" #n ")" ::: "memory")
; #define PG8_WAIT_L(n) asm volatile("s_waitcnt lgkmcnt(" #n ")" ::: "memory")
; #define PG8_BAR __builtin_amdgcn_s_barrier()
; #define PG8_SCHED __builtin_amdgcn_sched_barrier(0)
; template <class Epi, class Sched>
; __device__ __forceinline__ void gemm_phase(LAS unsigned char* lds, const Gemm g, const Sched& S, const Epi& E, int wid) {
;     ...
;             PG8_LDB(B0, 0, 0); PG8_LDB(B1, 0, 1); PG8_SCHED; PG8_LDA(At, 0, 0); PG8_STAGE(PG8_SA(1, 1), a1 + hstep, voffA);
;             PG8_WAIT_V(8); PG8_WAIT_L(0); PG8_BAR; PG8_MMA(0, 0, At, B0); PG8_MMA(0, 1, At, B1); PG8_BAR; PG8_SCHED;
;             PG8_LDA(At, 0, 1); PG8_STAGE(PG8_SB(0, 0), b2, voffB); PG8_STAGE(PG8_SB(0, 1), b2 + hstep, voffB); PG8_STAGE(PG8_SA(0, 0), a2, voffA);
;             PG8_WAIT_V(8); PG8_WAIT_L(0); PG8_BAR; PG8_MMA(1, 0, At, B0); PG8_MMA(1, 1, At, B1); PG8_BAR; PG8_SCHED;
.LBB0_2014:
	ds_read_b128 v[128:131], v169
	ds_read_b128 v[132:135], v169 offset:1024
	ds_read_b128 v[152:155], v169 offset:2048
	ds_read_b128 v[156:159], v169 offset:3072
	ds_read_b128 v[160:163], v170
	ds_read_b128 v[174:177], v170 offset:1024
	ds_read_b128 v[178:181], v170 offset:2048
	ds_read_b128 v[182:185], v170 offset:3072
	s_add_u32 s4, s6, 0xfffc0080
	s_addc_u32 s5, s7, -1
	s_cmp_eq_u32 s44, 12
	s_cselect_b32 s11, s31, s5
	s_cselect_b32 s10, s39, s4
	s_cselect_b32 s5, s29, s43
	s_cselect_b32 s4, s41, s42
	v_lshl_add_u64 v[218:219], s[6:7], 0, v[144:145]
	s_add_i32 m0, s3, 0xc000
	ds_read_b128 v[186:189], v171
	ds_read_b128 v[190:193], v171 offset:1024
	ds_read_b128 v[194:197], v171 offset:2048
	ds_read_b128 v[198:201], v171 offset:3072
	ds_read_b128 v[202:205], v171 offset:4096
	ds_read_b128 v[206:209], v171 offset:5120
	ds_read_b128 v[210:213], v171 offset:6144
	ds_read_b128 v[214:217], v171 offset:7168
	global_load_lds_dwordx4 v[218:219], off
	v_lshl_add_u64 v[218:219], s[6:7], 0, v[146:147]
	s_add_i32 m0, s3, 0xe000
	s_nop 0
	global_load_lds_dwordx4 v[218:219], off
	s_waitcnt vmcnt(8)
	s_waitcnt lgkmcnt(0)
	s_barrier
	s_setprio 1
	s_waitcnt lgkmcnt(0)
	v_mfma_f32_16x16x32_bf16 v[56:59], v[128:131], v[186:189], v[56:59]
	v_mfma_f32_16x16x32_bf16 v[64:67], v[152:155], v[186:189], v[64:67]
	v_mfma_f32_16x16x32_bf16 v[84:87], v[128:131], v[194:197], v[84:87]
	v_mfma_f32_16x16x32_bf16 v[92:95], v[152:155], v[194:197], v[92:95]
	v_mfma_f32_16x16x32_bf16 v[112:115], v[128:131], v[202:205], v[112:115]
	v_mfma_f32_16x16x32_bf16 v[116:119], v[152:155], v[202:205], v[116:119]
	v_mfma_f32_16x16x32_bf16 v[120:123], v[128:131], v[210:213], v[120:123]
	v_mfma_f32_16x16x32_bf16 v[124:127], v[152:155], v[210:213], v[124:127]
	v_mfma_f32_16x16x32_bf16 v[56:59], v[132:135], v[190:193], v[56:59]
	v_mfma_f32_16x16x32_bf16 v[64:67], v[156:159], v[190:193], v[64:67]
	v_mfma_f32_16x16x32_bf16 v[84:87], v[132:135], v[198:201], v[84:87]
	v_mfma_f32_16x16x32_bf16 v[92:95], v[156:159], v[198:201], v[92:95]
	v_mfma_f32_16x16x32_bf16 v[112:115], v[132:135], v[206:209], v[112:115]
	v_mfma_f32_16x16x32_bf16 v[116:119], v[156:159], v[206:209], v[116:119]
	v_mfma_f32_16x16x32_bf16 v[120:123], v[132:135], v[214:217], v[120:123]
	v_mfma_f32_16x16x32_bf16 v[124:127], v[156:159], v[214:217], v[124:127]
	s_setprio 0
	s_setprio 1
	v_mfma_f32_16x16x32_bf16 v[20:23], v[160:163], v[186:189], v[20:23]
	v_mfma_f32_16x16x32_bf16 v[28:31], v[178:181], v[186:189], v[28:31]
	v_mfma_f32_16x16x32_bf16 v[36:39], v[160:163], v[194:197], v[36:39]
	v_mfma_f32_16x16x32_bf16 v[48:51], v[178:181], v[194:197], v[48:51]
	v_mfma_f32_16x16x32_bf16 v[60:63], v[160:163], v[202:205], v[60:63]
	v_mfma_f32_16x16x32_bf16 v[80:83], v[178:181], v[202:205], v[80:83]
	v_mfma_f32_16x16x32_bf16 v[96:99], v[160:163], v[210:213], v[96:99]
	v_mfma_f32_16x16x32_bf16 v[104:107], v[178:181], v[210:213], v[104:107]
	v_mfma_f32_16x16x32_bf16 v[20:23], v[174:177], v[190:193], v[20:23]
	v_mfma_f32_16x16x32_bf16 v[28:31], v[182:185], v[190:193], v[28:31]
	v_mfma_f32_16x16x32_bf16 v[36:39], v[174:177], v[198:201], v[36:39]
	v_mfma_f32_16x16x32_bf16 v[48:51], v[182:185], v[198:201], v[48:51]
	v_mfma_f32_16x16x32_bf16 v[60:63], v[174:177], v[206:209], v[60:63]
	v_mfma_f32_16x16x32_bf16 v[80:83], v[182:185], v[206:209], v[80:83]
	v_mfma_f32_16x16x32_bf16 v[96:99], v[174:177], v[214:217], v[96:99]
	v_mfma_f32_16x16x32_bf16 v[104:107], v[182:185], v[214:217], v[104:107]
	s_setprio 0
	s_barrier
	s_add_i32 s45, s62, s75
	v_lshl_add_u64 v[218:219], s[4:5], 0, v[138:139]
	s_mov_b32 m0, s45
	ds_read_b128 v[186:189], v171 offset:16384
	ds_read_b128 v[190:193], v171 offset:17408
	ds_read_b128 v[194:197], v171 offset:18432
	ds_read_b128 v[198:201], v171 offset:19456
	ds_read_b128 v[202:205], v171 offset:20480
	ds_read_b128 v[206:209], v171 offset:21504
	ds_read_b128 v[210:213], v171 offset:22528
	ds_read_b128 v[214:217], v171 offset:23552
	global_load_lds_dwordx4 v[218:219], off
	s_add_i32 m0, s45, 0x2000
	s_add_u32 s68, s4, 0x40000
	v_lshl_add_u64 v[220:221], s[4:5], 0, v[142:143]
	s_addc_u32 s69, s5, 0
	s_add_i32 s45, s63, s75
	global_load_lds_dwordx4 v[220:221], off
	v_lshl_add_u64 v[222:223], s[68:69], 0, v[138:139]
	s_mov_b32 m0, s45
	v_lshl_add_u64 v[224:225], s[10:11], 0, v[140:141]
	global_load_lds_dwordx4 v[222:223], off
	v_lshl_add_u64 v[222:223], s[68:69], 0, v[142:143]
	s_add_i32 m0, s45, 0x2000
	s_nop 0
	global_load_lds_dwordx4 v[222:223], off
	v_lshl_add_u64 v[222:223], s[10:11], 0, v[136:137]
	s_mov_b32 m0, s3
	s_nop 0
	global_load_lds_dwordx4 v[222:223], off
	s_mov_b32 m0, s46
	s_nop 0
	global_load_lds_dwordx4 v[224:225], off
	s_waitcnt vmcnt(8)
	s_waitcnt lgkmcnt(0)
	s_barrier
; #define PG8_STAGE(bufoff, gbase, voff) do { _Pragma("unroll") for (int _i = 0; _i < 2; ++_i) \
;         __builtin_amdgcn_global_load_lds((const unsigned*)((const char*)(gbase) + (voff)[_i]), (LAS unsigned*)(lds + (bufoff) + ldsw + _i * 8192), 16, 0, 0); } while (0)
; #define PG8_LDA(dst, b, h) do { _Pragma("unroll") for (int m = 0; m < 4; ++m) _Pragma("unroll") for (int k = 0; k < 2; ++k) dst[m][k] = *(const LAS bf16x8*)(lds + PG8_SA(b, h) + aoff + m * 2048 + k * 1024); } while (0)
; #define PG8_LDB(dst, b, h) do { _Pragma("unroll") for (int n = 0; n < 2; ++n) _Pragma("unroll") for (int k = 0; k < 2; ++k) dst[n][k] = *(const LAS bf16x8*)(lds + PG8_SB(b, h) + boff + n * 2048 + k * 1024); } while (0)
; #define PG8_MMA(ai, bj, At, Bt) do { __builtin_amdgcn_s_setprio(1); _Pragma("unroll") for (int m = 0; m < 4; ++m) _Pragma("unroll") for (int n = 0; n < 2; ++n) _Pragma("unroll") for (int k = 0; k < 2; ++k) \
;         acc[ai][bj][m][n] = __builtin_amdgcn_mfma_f32_16x16x32_bf16(Bt[n][k], At[m][k], acc[ai][bj][m][n], 0, 0, 0); __builtin_amdgcn_s_setprio(0); } while (0)
; #define PG8_WAIT_V(n) asm volatile("s_waitcnt vmcnt(" #n ")" ::: "memory")
; #define PG8_WAIT_L(n) asm volatile("s_waitcnt lgkmcnt(" #n ")" ::: "memory")
; #define PG8_BAR __builtin_amdgcn_s_barrier()
; #define PG8_SCHED __builtin_amdgcn_sched_barrier(0)
; template <class Epi, class Sched>
; __device__ __forceinline__ void gemm_phase(LAS unsigned char* lds, const Gemm g, const Sched& S, const Epi& E, int wid) {
;     ...
;             PG8_WAIT_V(8); PG8_WAIT_L(0); PG8_BAR; PG8_MMA(1, 0, At, B0); PG8_MMA(1, 1, At, B1); PG8_BAR; PG8_SCHED;
;             PG8_LDB(B0, 1, 0); PG8_LDB(B1, 1, 1); PG8_SCHED; PG8_LDA(At, 1, 0); PG8_STAGE(PG8_SA(0, 1), a2 + hstep, voffA);
;             PG8_WAIT_V(8); PG8_WAIT_L(0); PG8_BAR; PG8_MMA(0, 0, At, B0); PG8_MMA(0, 1, At, B1); PG8_BAR; PG8_SCHED;
	s_setprio 1
	s_waitcnt lgkmcnt(0)
	v_mfma_f32_16x16x32_bf16 v[108:111], v[128:131], v[186:189], v[108:111]
	v_mfma_f32_16x16x32_bf16 v[100:103], v[152:155], v[186:189], v[100:103]
	v_mfma_f32_16x16x32_bf16 v[72:75], v[128:131], v[194:197], v[72:75]
	v_mfma_f32_16x16x32_bf16 v[68:71], v[152:155], v[194:197], v[68:71]
	v_mfma_f32_16x16x32_bf16 v[40:43], v[128:131], v[202:205], v[40:43]
	v_mfma_f32_16x16x32_bf16 v[32:35], v[152:155], v[202:205], v[32:35]
	v_mfma_f32_16x16x32_bf16 v[12:15], v[128:131], v[210:213], v[12:15]
	v_mfma_f32_16x16x32_bf16 v[8:11], v[152:155], v[210:213], v[8:11]
	v_mfma_f32_16x16x32_bf16 v[108:111], v[132:135], v[190:193], v[108:111]
	v_mfma_f32_16x16x32_bf16 v[100:103], v[156:159], v[190:193], v[100:103]
	v_mfma_f32_16x16x32_bf16 v[72:75], v[132:135], v[198:201], v[72:75]
	v_mfma_f32_16x16x32_bf16 v[68:71], v[156:159], v[198:201], v[68:71]
	v_mfma_f32_16x16x32_bf16 v[40:43], v[132:135], v[206:209], v[40:43]
	v_mfma_f32_16x16x32_bf16 v[32:35], v[156:159], v[206:209], v[32:35]
	v_mfma_f32_16x16x32_bf16 v[12:15], v[132:135], v[214:217], v[12:15]
	v_mfma_f32_16x16x32_bf16 v[8:11], v[156:159], v[214:217], v[8:11]
	s_setprio 0
	s_setprio 1
	v_mfma_f32_16x16x32_bf16 v[88:91], v[160:163], v[186:189], v[88:91]
	v_mfma_f32_16x16x32_bf16 v[76:79], v[178:181], v[186:189], v[76:79]
	v_mfma_f32_16x16x32_bf16 v[52:55], v[160:163], v[194:197], v[52:55]
	v_mfma_f32_16x16x32_bf16 v[44:47], v[178:181], v[194:197], v[44:47]
	v_mfma_f32_16x16x32_bf16 v[24:27], v[160:163], v[202:205], v[24:27]
	v_mfma_f32_16x16x32_bf16 v[16:19], v[178:181], v[202:205], v[16:19]
	v_mfma_f32_16x16x32_bf16 v[4:7], v[160:163], v[210:213], v[4:7]
	v_mfma_f32_16x16x32_bf16 v[0:3], v[178:181], v[210:213], v[0:3]
	v_mfma_f32_16x16x32_bf16 v[88:91], v[174:177], v[190:193], v[88:91]
	v_mfma_f32_16x16x32_bf16 v[76:79], v[182:185], v[190:193], v[76:79]
	v_mfma_f32_16x16x32_bf16 v[52:55], v[174:177], v[198:201], v[52:55]
	v_mfma_f32_16x16x32_bf16 v[44:47], v[182:185], v[198:201], v[44:47]
	v_mfma_f32_16x16x32_bf16 v[24:27], v[174:177], v[206:209], v[24:27]
	v_mfma_f32_16x16x32_bf16 v[16:19], v[182:185], v[206:209], v[16:19]
	v_mfma_f32_16x16x32_bf16 v[4:7], v[174:177], v[214:217], v[4:7]
	v_mfma_f32_16x16x32_bf16 v[0:3], v[182:185], v[214:217], v[0:3]
	s_setprio 0
	s_barrier
	s_add_i32 s45, 0, 0x18000
	s_add_i32 s68, 0, 0x1c000
	v_add_u32_e32 v156, s45, v168
	v_add_u32_e32 v173, s68, v168
	ds_read_b128 v[128:131], v156
	ds_read_b128 v[132:135], v156 offset:1024
	ds_read_b128 v[152:155], v156 offset:2048
	ds_read_b128 v[156:159], v156 offset:3072
	ds_read_b128 v[160:163], v173
	ds_read_b128 v[174:177], v173 offset:1024
	ds_read_b128 v[178:181], v173 offset:2048
	ds_read_b128 v[182:185], v173 offset:3072
	s_add_u32 s10, s10, 0x40000
	s_addc_u32 s11, s11, 0
	s_mov_b32 m0, s47
	v_lshl_add_u64 v[226:227], s[10:11], 0, v[136:137]
	ds_read_b128 v[186:189], v171 offset:32768
	ds_read_b128 v[190:193], v171 offset:33792
	ds_read_b128 v[194:197], v171 offset:34816
	ds_read_b128 v[198:201], v171 offset:35840
	ds_read_b128 v[202:205], v171 offset:36864
	ds_read_b128 v[206:209], v171 offset:37888
	ds_read_b128 v[210:213], v171 offset:38912
	ds_read_b128 v[214:217], v171 offset:39936
	global_load_lds_dwordx4 v[226:227], off
	v_lshl_add_u64 v[226:227], s[10:11], 0, v[140:141]
	s_mov_b32 m0, s48
	s_nop 0
	global_load_lds_dwordx4 v[226:227], off
	s_waitcnt vmcnt(8)
	s_waitcnt lgkmcnt(0)
	s_barrier
	s_setprio 1
	s_waitcnt lgkmcnt(0)
	v_mfma_f32_16x16x32_bf16 v[56:59], v[128:131], v[186:189], v[56:59]
	v_mfma_f32_16x16x32_bf16 v[64:67], v[152:155], v[186:189], v[64:67]
	v_mfma_f32_16x16x32_bf16 v[84:87], v[128:131], v[194:197], v[84:87]
	v_mfma_f32_16x16x32_bf16 v[92:95], v[152:155], v[194:197], v[92:95]
	v_mfma_f32_16x16x32_bf16 v[112:115], v[128:131], v[202:205], v[112:115]
	v_mfma_f32_16x16x32_bf16 v[116:119], v[152:155], v[202:205], v[116:119]
	v_mfma_f32_16x16x32_bf16 v[120:123], v[128:131], v[210:213], v[120:123]
	v_mfma_f32_16x16x32_bf16 v[124:127], v[152:155], v[210:213], v[124:127]
	v_mfma_f32_16x16x32_bf16 v[56:59], v[132:135], v[190:193], v[56:59]
	v_mfma_f32_16x16x32_bf16 v[64:67], v[156:159], v[190:193], v[64:67]
	v_mfma_f32_16x16x32_bf16 v[84:87], v[132:135], v[198:201], v[84:87]
	v_mfma_f32_16x16x32_bf16 v[92:95], v[156:159], v[198:201], v[92:95]
	v_mfma_f32_16x16x32_bf16 v[112:115], v[132:135], v[206:209], v[112:115]
	v_mfma_f32_16x16x32_bf16 v[116:119], v[156:159], v[206:209], v[116:119]
	v_mfma_f32_16x16x32_bf16 v[120:123], v[132:135], v[214:217], v[120:123]
	v_mfma_f32_16x16x32_bf16 v[124:127], v[156:159], v[214:217], v[124:127]
	s_setprio 0
	s_setprio 1
	v_mfma_f32_16x16x32_bf16 v[20:23], v[160:163], v[186:189], v[20:23]
	v_mfma_f32_16x16x32_bf16 v[28:31], v[178:181], v[186:189], v[28:31]
	v_mfma_f32_16x16x32_bf16 v[36:39], v[160:163], v[194:197], v[36:39]
	v_mfma_f32_16x16x32_bf16 v[48:51], v[178:181], v[194:197], v[48:51]
	v_mfma_f32_16x16x32_bf16 v[60:63], v[160:163], v[202:205], v[60:63]
	v_mfma_f32_16x16x32_bf16 v[80:83], v[178:181], v[202:205], v[80:83]
	v_mfma_f32_16x16x32_bf16 v[96:99], v[160:163], v[210:213], v[96:99]
	v_mfma_f32_16x16x32_bf16 v[104:107], v[178:181], v[210:213], v[104:107]
	v_mfma_f32_16x16x32_bf16 v[20:23], v[174:177], v[190:193], v[20:23]
	v_mfma_f32_16x16x32_bf16 v[28:31], v[182:185], v[190:193], v[28:31]
	v_mfma_f32_16x16x32_bf16 v[36:39], v[174:177], v[198:201], v[36:39]
	v_mfma_f32_16x16x32_bf16 v[48:51], v[182:185], v[198:201], v[48:51]
	v_mfma_f32_16x16x32_bf16 v[60:63], v[174:177], v[206:209], v[60:63]
	v_mfma_f32_16x16x32_bf16 v[80:83], v[182:185], v[206:209], v[80:83]
	v_mfma_f32_16x16x32_bf16 v[96:99], v[174:177], v[214:217], v[96:99]
	v_mfma_f32_16x16x32_bf16 v[104:107], v[182:185], v[214:217], v[104:107]
	s_setprio 0
	s_barrier
; #define PG8_STAGE(bufoff, gbase, voff) do { _Pragma("unroll") for (int _i = 0; _i < 2; ++_i) \
;         __builtin_amdgcn_global_load_lds((const unsigned*)((const char*)(gbase) + (voff)[_i]), (LAS unsigned*)(lds + (bufoff) + ldsw + _i * 8192), 16, 0, 0); } while (0)
; #define PG8_LDA(dst, b, h) do { _Pragma("unroll") for (int m = 0; m < 4; ++m) _Pragma("unroll") for (int k = 0; k < 2; ++k) dst[m][k] = *(const LAS bf16x8*)(lds + PG8_SA(b, h) + aoff + m * 2048 + k * 1024); } while (0)
; #define PG8_MMA(ai, bj, At, Bt) do { __builtin_amdgcn_s_setprio(1); _Pragma("unroll") for (int m = 0; m < 4; ++m) _Pragma("unroll") for (int n = 0; n < 2; ++n) _Pragma("unroll") for (int k = 0; k < 2; ++k) \
;         acc[ai][bj][m][n] = __builtin_amdgcn_mfma_f32_16x16x32_bf16(Bt[n][k], At[m][k], acc[ai][bj][m][n], 0, 0, 0); __builtin_amdgcn_s_setprio(0); } while (0)
; #define PG8_WAIT_V(n) asm volatile("s_waitcnt vmcnt(" #n ")" ::: "memory")
; #define PG8_WAIT_L(n) asm volatile("s_waitcnt lgkmcnt(" #n ")" ::: "memory")
; #define PG8_BAR __builtin_amdgcn_s_barrier()
; #define PG8_SCHED __builtin_amdgcn_sched_barrier(0)
; template <class Epi, class Sched>
; __device__ __forceinline__ void gemm_phase(LAS unsigned char* lds, const Gemm g, const Sched& S, const Epi& E, int wid) {
;     ...
;             PG8_LDA(At, 1, 1); PG8_STAGE(PG8_SB(1, 0), b3, voffB); PG8_STAGE(PG8_SB(1, 1), b3 + hstep, voffB); PG8_STAGE(PG8_SA(1, 0), a3, voffA);
;             PG8_WAIT_V(8); PG8_WAIT_L(0); PG8_BAR; PG8_MMA(1, 0, At, B0); PG8_MMA(1, 1, At, B1); PG8_BAR; PG8_SCHED;
;         }
	s_add_i32 s10, s45, s75
	v_lshl_add_u64 v[218:219], v[218:219], 0, s[24:25]
	s_mov_b32 m0, s10
	ds_read_b128 v[186:189], v171 offset:49152
	ds_read_b128 v[190:193], v171 offset:50176
	ds_read_b128 v[194:197], v171 offset:51200
	ds_read_b128 v[198:201], v171 offset:52224
	ds_read_b128 v[202:205], v171 offset:53248
	ds_read_b128 v[206:209], v171 offset:54272
	ds_read_b128 v[210:213], v171 offset:55296
	ds_read_b128 v[214:217], v171 offset:56320
	global_load_lds_dwordx4 v[218:219], off
	s_add_i32 m0, s10, 0x2000
	s_add_u32 s4, s4, 0x40080
	v_lshl_add_u64 v[218:219], v[220:221], 0, s[24:25]
	s_addc_u32 s5, s5, 0
	s_add_i32 s10, s68, s75
	global_load_lds_dwordx4 v[218:219], off
	v_lshl_add_u64 v[218:219], s[4:5], 0, v[138:139]
	s_mov_b32 m0, s10
	s_nop 0
	global_load_lds_dwordx4 v[218:219], off
	v_lshl_add_u64 v[218:219], s[4:5], 0, v[142:143]
	s_add_i32 m0, s10, 0x2000
	s_nop 0
	global_load_lds_dwordx4 v[218:219], off
	v_lshl_add_u64 v[218:219], v[222:223], 0, s[24:25]
	s_mov_b32 m0, s54
	s_nop 0
	global_load_lds_dwordx4 v[218:219], off
	v_lshl_add_u64 v[218:219], v[224:225], 0, s[24:25]
	s_mov_b32 m0, s55
	s_nop 0
	global_load_lds_dwordx4 v[218:219], off
	s_waitcnt vmcnt(8)
	s_waitcnt lgkmcnt(0)
	s_barrier
	s_setprio 1
	s_waitcnt lgkmcnt(0)
	v_mfma_f32_16x16x32_bf16 v[108:111], v[128:131], v[186:189], v[108:111]
	v_mfma_f32_16x16x32_bf16 v[100:103], v[152:155], v[186:189], v[100:103]
	v_mfma_f32_16x16x32_bf16 v[72:75], v[128:131], v[194:197], v[72:75]
	v_mfma_f32_16x16x32_bf16 v[68:71], v[152:155], v[194:197], v[68:71]
	v_mfma_f32_16x16x32_bf16 v[40:43], v[128:131], v[202:205], v[40:43]
	v_mfma_f32_16x16x32_bf16 v[32:35], v[152:155], v[202:205], v[32:35]
	v_mfma_f32_16x16x32_bf16 v[12:15], v[128:131], v[210:213], v[12:15]
	v_mfma_f32_16x16x32_bf16 v[8:11], v[152:155], v[210:213], v[8:11]
	v_mfma_f32_16x16x32_bf16 v[108:111], v[132:135], v[190:193], v[108:111]
	v_mfma_f32_16x16x32_bf16 v[100:103], v[156:159], v[190:193], v[100:103]
	v_mfma_f32_16x16x32_bf16 v[72:75], v[132:135], v[198:201], v[72:75]
	v_mfma_f32_16x16x32_bf16 v[68:71], v[156:159], v[198:201], v[68:71]
	v_mfma_f32_16x16x32_bf16 v[40:43], v[132:135], v[206:209], v[40:43]
	v_mfma_f32_16x16x32_bf16 v[32:35], v[156:159], v[206:209], v[32:35]
	v_mfma_f32_16x16x32_bf16 v[12:15], v[132:135], v[214:217], v[12:15]
	v_mfma_f32_16x16x32_bf16 v[8:11], v[156:159], v[214:217], v[8:11]
	s_setprio 0
	s_setprio 1
	v_mfma_f32_16x16x32_bf16 v[88:91], v[160:163], v[186:189], v[88:91]
	v_mfma_f32_16x16x32_bf16 v[76:79], v[178:181], v[186:189], v[76:79]
	v_mfma_f32_16x16x32_bf16 v[52:55], v[160:163], v[194:197], v[52:55]
	v_mfma_f32_16x16x32_bf16 v[44:47], v[178:181], v[194:197], v[44:47]
	v_mfma_f32_16x16x32_bf16 v[24:27], v[160:163], v[202:205], v[24:27]
	v_mfma_f32_16x16x32_bf16 v[16:19], v[178:181], v[202:205], v[16:19]
	v_mfma_f32_16x16x32_bf16 v[4:7], v[160:163], v[210:213], v[4:7]
	v_mfma_f32_16x16x32_bf16 v[0:3], v[178:181], v[210:213], v[0:3]
	v_mfma_f32_16x16x32_bf16 v[88:91], v[174:177], v[190:193], v[88:91]
	v_mfma_f32_16x16x32_bf16 v[76:79], v[182:185], v[190:193], v[76:79]
	v_mfma_f32_16x16x32_bf16 v[52:55], v[174:177], v[198:201], v[52:55]
	v_mfma_f32_16x16x32_bf16 v[44:47], v[182:185], v[198:201], v[44:47]
	v_mfma_f32_16x16x32_bf16 v[24:27], v[174:177], v[206:209], v[24:27]
	v_mfma_f32_16x16x32_bf16 v[16:19], v[182:185], v[206:209], v[16:19]
	v_mfma_f32_16x16x32_bf16 v[4:7], v[174:177], v[214:217], v[4:7]
	v_mfma_f32_16x16x32_bf16 v[0:3], v[182:185], v[214:217], v[0:3]
	s_setprio 0
	s_add_i32 s44, s44, 2
	s_add_u32 s6, s6, 0x100
	s_addc_u32 s7, s7, 0
	s_add_u32 s42, s42, 0x100
	s_addc_u32 s43, s43, 0
	s_cmp_gt_u32 s44, 13
	s_barrier
	s_cbranch_scc0 .LBB0_2014
	s_and_b64 vcc, exec, s[26:27]
	s_cbranch_vccz .LBB0_2017
	s_barrier

; #define PG8_STAGE(bufoff, gbase, voff) do { _Pragma("unroll") for (int _i = 0; _i < 2; ++_i) \
;         __builtin_amdgcn_global_load_lds((const unsigned*)((const char*)(gbase) + (voff)[_i]), (LAS unsigned*)(lds + (bufoff) + ldsw + _i * 8192), 16, 0, 0); } while (0)
; #define PG8_LDA(dst, b, h) do { _Pragma("unroll") for (int m = 0; m < 4; ++m) _Pragma("unroll") for (int k = 0; k < 2; ++k) dst[m][k] = *(const LAS bf16x8*)(lds + PG8_SA(b, h) + aoff + m * 2048 + k * 1024); } while (0)
; #define PG8_LDB(dst, b, h) do { _Pragma("unroll") for (int n = 0; n < 2; ++n) _Pragma("unroll") for (int k = 0; k < 2; ++k) dst[n][k] = *(const LAS bf16x8*)(lds + PG8_SB(b, h) + boff + n * 2048 + k * 1024); } while (0)
; #define PG8_MMA(ai, bj, At, Bt) do { __builtin_amdgcn_s_setprio(1); _Pragma("unroll") for (int m = 0; m < 4; ++m) _Pragma("unroll") for (int n = 0; n < 2; ++n) _Pragma("unroll") for (int k = 0; k < 2; ++k) \
;         acc[ai][bj][m][n] = __builtin_amdgcn_mfma_f32_16x16x32_bf16(Bt[n][k], At[m][k], acc[ai][bj][m][n], 0, 0, 0); __builtin_amdgcn_s_setprio(0); } while (0)
; #define PG8_WAIT_V(n) asm volatile("s_waitcnt vmcnt(" #n ")" ::: "memory")
; #define PG8_WAIT_L(n) asm volatile("s_waitcnt lgkmcnt(" #n ")" ::: "memory")
; #define PG8_BAR __builtin_amdgcn_s_barrier()
; #define PG8_SCHED __builtin_amdgcn_sched_barrier(0)
; template <class Epi, class Sched>
; __device__ __forceinline__ void gemm_phase(LAS unsigned char* lds, const Gemm g, const Sched& S, const Epi& E, int wid) {
;     ...
;             PG8_LDB(B0, 0, 0); PG8_LDB(B1, 0, 1); PG8_SCHED; PG8_LDA(At, 0, 0); PG8_STAGE(PG8_SA(1, 1), a1 + hstep, voffA);
;             PG8_WAIT_V(8); PG8_WAIT_L(0); PG8_BAR; PG8_MMA(0, 0, At, B0); PG8_MMA(0, 1, At, B1); PG8_BAR; PG8_SCHED;
;             PG8_LDA(At, 0, 1); PG8_STAGE(PG8_SB(0, 0), b2, voffB); PG8_STAGE(PG8_SB(0, 1), b2 + hstep, voffB); PG8_STAGE(PG8_SA(0, 0), a2, voffA);
;             PG8_WAIT_V(8); PG8_WAIT_L(0); PG8_BAR; PG8_MMA(1, 0, At, B0); PG8_MMA(1, 1, At, B1); PG8_BAR; PG8_SCHED;
.LBB0_2203:
	ds_read_b128 v[152:155], v148
	ds_read_b128 v[156:159], v148 offset:1024
	ds_read_b128 v[160:163], v148 offset:2048
	ds_read_b128 v[168:171], v148 offset:3072
	ds_read_b128 v[172:175], v149
	ds_read_b128 v[176:179], v149 offset:1024
	ds_read_b128 v[180:183], v149 offset:2048
	ds_read_b128 v[184:187], v149 offset:3072
	s_add_u32 s4, s28, 0xfffc0080
	s_addc_u32 s5, s29, -1
	s_cmp_eq_u32 s52, 12
	s_cselect_b32 s31, s21, s5
	s_cselect_b32 s30, s27, s4
	s_cselect_b32 s5, s19, s51
	s_cselect_b32 s4, s49, s50
	v_lshl_add_u64 v[164:165], s[28:29], 0, v[138:139]
	s_add_i32 m0, s35, 0xc000
	ds_read_b128 v[188:191], v150
	ds_read_b128 v[192:195], v150 offset:1024
	ds_read_b128 v[196:199], v150 offset:2048
	ds_read_b128 v[200:203], v150 offset:3072
	ds_read_b128 v[204:207], v150 offset:4096
	ds_read_b128 v[208:211], v150 offset:5120
	ds_read_b128 v[212:215], v150 offset:6144
	ds_read_b128 v[216:219], v150 offset:7168
	global_load_lds_dwordx4 v[164:165], off
	v_lshl_add_u64 v[164:165], s[28:29], 0, v[140:141]
	s_add_i32 m0, s35, 0xe000
	s_nop 0
	global_load_lds_dwordx4 v[164:165], off
	s_waitcnt vmcnt(8)
	s_waitcnt lgkmcnt(0)
	s_barrier
	s_setprio 1
	s_waitcnt lgkmcnt(0)
	v_mfma_f32_16x16x32_bf16 v[124:127], v[152:155], v[188:191], v[124:127]
	v_mfma_f32_16x16x32_bf16 v[116:119], v[160:163], v[188:191], v[116:119]
	v_mfma_f32_16x16x32_bf16 v[108:111], v[152:155], v[196:199], v[108:111]
	v_mfma_f32_16x16x32_bf16 v[100:103], v[160:163], v[196:199], v[100:103]
	v_mfma_f32_16x16x32_bf16 v[92:95], v[152:155], v[204:207], v[92:95]
	v_mfma_f32_16x16x32_bf16 v[84:87], v[160:163], v[204:207], v[84:87]
	v_mfma_f32_16x16x32_bf16 v[76:79], v[152:155], v[212:215], v[76:79]
	v_mfma_f32_16x16x32_bf16 v[68:71], v[160:163], v[212:215], v[68:71]
	v_mfma_f32_16x16x32_bf16 v[124:127], v[156:159], v[192:195], v[124:127]
	v_mfma_f32_16x16x32_bf16 v[116:119], v[168:171], v[192:195], v[116:119]
	v_mfma_f32_16x16x32_bf16 v[108:111], v[156:159], v[200:203], v[108:111]
	v_mfma_f32_16x16x32_bf16 v[100:103], v[168:171], v[200:203], v[100:103]
	v_mfma_f32_16x16x32_bf16 v[92:95], v[156:159], v[208:211], v[92:95]
	v_mfma_f32_16x16x32_bf16 v[84:87], v[168:171], v[208:211], v[84:87]
	v_mfma_f32_16x16x32_bf16 v[76:79], v[156:159], v[216:219], v[76:79]
	v_mfma_f32_16x16x32_bf16 v[68:71], v[168:171], v[216:219], v[68:71]
	s_setprio 0
	s_setprio 1
	v_mfma_f32_16x16x32_bf16 v[120:123], v[172:175], v[188:191], v[120:123]
	v_mfma_f32_16x16x32_bf16 v[112:115], v[180:183], v[188:191], v[112:115]
	v_mfma_f32_16x16x32_bf16 v[104:107], v[172:175], v[196:199], v[104:107]
	v_mfma_f32_16x16x32_bf16 v[96:99], v[180:183], v[196:199], v[96:99]
	v_mfma_f32_16x16x32_bf16 v[88:91], v[172:175], v[204:207], v[88:91]
	v_mfma_f32_16x16x32_bf16 v[80:83], v[180:183], v[204:207], v[80:83]
	v_mfma_f32_16x16x32_bf16 v[72:75], v[172:175], v[212:215], v[72:75]
	v_mfma_f32_16x16x32_bf16 v[64:67], v[180:183], v[212:215], v[64:67]
	v_mfma_f32_16x16x32_bf16 v[120:123], v[176:179], v[192:195], v[120:123]
	v_mfma_f32_16x16x32_bf16 v[112:115], v[184:187], v[192:195], v[112:115]
	v_mfma_f32_16x16x32_bf16 v[104:107], v[176:179], v[200:203], v[104:107]
	v_mfma_f32_16x16x32_bf16 v[96:99], v[184:187], v[200:203], v[96:99]
	v_mfma_f32_16x16x32_bf16 v[88:91], v[176:179], v[208:211], v[88:91]
	v_mfma_f32_16x16x32_bf16 v[80:83], v[184:187], v[208:211], v[80:83]
	v_mfma_f32_16x16x32_bf16 v[72:75], v[176:179], v[216:219], v[72:75]
	v_mfma_f32_16x16x32_bf16 v[64:67], v[184:187], v[216:219], v[64:67]
	s_setprio 0
	s_barrier
	s_add_i32 s53, s44, s75
	v_lshl_add_u64 v[164:165], s[4:5], 0, v[130:131]
	s_mov_b32 m0, s53
	ds_read_b128 v[188:191], v150 offset:16384
	ds_read_b128 v[192:195], v150 offset:17408
	ds_read_b128 v[196:199], v150 offset:18432
	ds_read_b128 v[200:203], v150 offset:19456
	ds_read_b128 v[204:207], v150 offset:20480
	ds_read_b128 v[208:211], v150 offset:21504
	ds_read_b128 v[212:215], v150 offset:22528
	ds_read_b128 v[216:219], v150 offset:23552
	global_load_lds_dwordx4 v[164:165], off
	s_add_i32 m0, s53, 0x2000
	s_add_u32 s54, s4, 0x40000
	v_lshl_add_u64 v[220:221], s[4:5], 0, v[134:135]
	s_addc_u32 s55, s5, 0
	s_add_i32 s53, s45, s75
	global_load_lds_dwordx4 v[220:221], off
	v_lshl_add_u64 v[222:223], s[54:55], 0, v[130:131]
	s_mov_b32 m0, s53
	v_lshl_add_u64 v[224:225], s[30:31], 0, v[132:133]
	global_load_lds_dwordx4 v[222:223], off
	v_lshl_add_u64 v[222:223], s[54:55], 0, v[134:135]
	s_add_i32 m0, s53, 0x2000
	s_nop 0
	global_load_lds_dwordx4 v[222:223], off
	v_lshl_add_u64 v[222:223], s[30:31], 0, v[128:129]
	s_mov_b32 m0, s35
	s_nop 0
	global_load_lds_dwordx4 v[222:223], off
	s_mov_b32 m0, s36
	s_nop 0
	global_load_lds_dwordx4 v[224:225], off
	s_waitcnt vmcnt(8)
	s_waitcnt lgkmcnt(0)
	s_barrier
; #define PG8_STAGE(bufoff, gbase, voff) do { _Pragma("unroll") for (int _i = 0; _i < 2; ++_i) \
;         __builtin_amdgcn_global_load_lds((const unsigned*)((const char*)(gbase) + (voff)[_i]), (LAS unsigned*)(lds + (bufoff) + ldsw + _i * 8192), 16, 0, 0); } while (0)
; #define PG8_LDA(dst, b, h) do { _Pragma("unroll") for (int m = 0; m < 4; ++m) _Pragma("unroll") for (int k = 0; k < 2; ++k) dst[m][k] = *(const LAS bf16x8*)(lds + PG8_SA(b, h) + aoff + m * 2048 + k * 1024); } while (0)
; #define PG8_LDB(dst, b, h) do { _Pragma("unroll") for (int n = 0; n < 2; ++n) _Pragma("unroll") for (int k = 0; k < 2; ++k) dst[n][k] = *(const LAS bf16x8*)(lds + PG8_SB(b, h) + boff + n * 2048 + k * 1024); } while (0)
; #define PG8_MMA(ai, bj, At, Bt) do { __builtin_amdgcn_s_setprio(1); _Pragma("unroll") for (int m = 0; m < 4; ++m) _Pragma("unroll") for (int n = 0; n < 2; ++n) _Pragma("unroll") for (int k = 0; k < 2; ++k) \
;         acc[ai][bj][m][n] = __builtin_amdgcn_mfma_f32_16x16x32_bf16(Bt[n][k], At[m][k], acc[ai][bj][m][n], 0, 0, 0); __builtin_amdgcn_s_setprio(0); } while (0)
; #define PG8_WAIT_V(n) asm volatile("s_waitcnt vmcnt(" #n ")" ::: "memory")
; #define PG8_WAIT_L(n) asm volatile("s_waitcnt lgkmcnt(" #n ")" ::: "memory")
; #define PG8_BAR __builtin_amdgcn_s_barrier()
; #define PG8_SCHED __builtin_amdgcn_sched_barrier(0)
; template <class Epi, class Sched>
; __device__ __forceinline__ void gemm_phase(LAS unsigned char* lds, const Gemm g, const Sched& S, const Epi& E, int wid) {
;     ...
;             PG8_WAIT_V(8); PG8_WAIT_L(0); PG8_BAR; PG8_MMA(1, 0, At, B0); PG8_MMA(1, 1, At, B1); PG8_BAR; PG8_SCHED;
;             PG8_LDB(B0, 1, 0); PG8_LDB(B1, 1, 1); PG8_SCHED; PG8_LDA(At, 1, 0); PG8_STAGE(PG8_SA(0, 1), a2 + hstep, voffA);
;             PG8_WAIT_V(8); PG8_WAIT_L(0); PG8_BAR; PG8_MMA(0, 0, At, B0); PG8_MMA(0, 1, At, B1); PG8_BAR; PG8_SCHED;
	s_setprio 1
	s_waitcnt lgkmcnt(0)
	v_mfma_f32_16x16x32_bf16 v[60:63], v[152:155], v[188:191], v[60:63]
	v_mfma_f32_16x16x32_bf16 v[52:55], v[160:163], v[188:191], v[52:55]
	v_mfma_f32_16x16x32_bf16 v[44:47], v[152:155], v[196:199], v[44:47]
	v_mfma_f32_16x16x32_bf16 v[36:39], v[160:163], v[196:199], v[36:39]
	v_mfma_f32_16x16x32_bf16 v[28:31], v[152:155], v[204:207], v[28:31]
	v_mfma_f32_16x16x32_bf16 v[20:23], v[160:163], v[204:207], v[20:23]
	v_mfma_f32_16x16x32_bf16 v[12:15], v[152:155], v[212:215], v[12:15]
	v_mfma_f32_16x16x32_bf16 v[4:7], v[160:163], v[212:215], v[4:7]
	v_mfma_f32_16x16x32_bf16 v[60:63], v[156:159], v[192:195], v[60:63]
	v_mfma_f32_16x16x32_bf16 v[52:55], v[168:171], v[192:195], v[52:55]
	v_mfma_f32_16x16x32_bf16 v[44:47], v[156:159], v[200:203], v[44:47]
	v_mfma_f32_16x16x32_bf16 v[36:39], v[168:171], v[200:203], v[36:39]
	v_mfma_f32_16x16x32_bf16 v[28:31], v[156:159], v[208:211], v[28:31]
	v_mfma_f32_16x16x32_bf16 v[20:23], v[168:171], v[208:211], v[20:23]
	v_mfma_f32_16x16x32_bf16 v[12:15], v[156:159], v[216:219], v[12:15]
	v_mfma_f32_16x16x32_bf16 v[4:7], v[168:171], v[216:219], v[4:7]
	s_setprio 0
	s_setprio 1
	v_mfma_f32_16x16x32_bf16 v[56:59], v[172:175], v[188:191], v[56:59]
	v_mfma_f32_16x16x32_bf16 v[48:51], v[180:183], v[188:191], v[48:51]
	v_mfma_f32_16x16x32_bf16 v[40:43], v[172:175], v[196:199], v[40:43]
	v_mfma_f32_16x16x32_bf16 v[32:35], v[180:183], v[196:199], v[32:35]
	v_mfma_f32_16x16x32_bf16 v[24:27], v[172:175], v[204:207], v[24:27]
	v_mfma_f32_16x16x32_bf16 v[16:19], v[180:183], v[204:207], v[16:19]
	v_mfma_f32_16x16x32_bf16 v[8:11], v[172:175], v[212:215], v[8:11]
	v_mfma_f32_16x16x32_bf16 v[0:3], v[180:183], v[212:215], v[0:3]
	v_mfma_f32_16x16x32_bf16 v[56:59], v[176:179], v[192:195], v[56:59]
	v_mfma_f32_16x16x32_bf16 v[48:51], v[184:187], v[192:195], v[48:51]
	v_mfma_f32_16x16x32_bf16 v[40:43], v[176:179], v[200:203], v[40:43]
	v_mfma_f32_16x16x32_bf16 v[32:35], v[184:187], v[200:203], v[32:35]
	v_mfma_f32_16x16x32_bf16 v[24:27], v[176:179], v[208:211], v[24:27]
	v_mfma_f32_16x16x32_bf16 v[16:19], v[184:187], v[208:211], v[16:19]
	v_mfma_f32_16x16x32_bf16 v[8:11], v[176:179], v[216:219], v[8:11]
	v_mfma_f32_16x16x32_bf16 v[0:3], v[184:187], v[216:219], v[0:3]
	s_setprio 0
	s_barrier
	s_add_i32 s53, 0, 0x18000
	v_add_u32_e32 v151, s53, v147
	s_add_i32 s54, 0, 0x1c000
	ds_read_b128 v[152:155], v151
	ds_read_b128 v[156:159], v151 offset:1024
	ds_read_b128 v[160:163], v151 offset:2048
	ds_read_b128 v[168:171], v151 offset:3072
	v_add_u32_e32 v151, s54, v147
	ds_read_b128 v[172:175], v151
	ds_read_b128 v[176:179], v151 offset:1024
	ds_read_b128 v[180:183], v151 offset:2048
	ds_read_b128 v[184:187], v151 offset:3072
	s_add_u32 s30, s30, 0x40000
	s_addc_u32 s31, s31, 0
	s_mov_b32 m0, s37
	v_lshl_add_u64 v[226:227], s[30:31], 0, v[128:129]
	ds_read_b128 v[188:191], v150 offset:32768
	ds_read_b128 v[192:195], v150 offset:33792
	ds_read_b128 v[196:199], v150 offset:34816
	ds_read_b128 v[200:203], v150 offset:35840
	ds_read_b128 v[204:207], v150 offset:36864
	ds_read_b128 v[208:211], v150 offset:37888
	ds_read_b128 v[212:215], v150 offset:38912
	ds_read_b128 v[216:219], v150 offset:39936
	global_load_lds_dwordx4 v[226:227], off
	v_lshl_add_u64 v[226:227], s[30:31], 0, v[132:133]
	s_mov_b32 m0, s38
	s_nop 0
	global_load_lds_dwordx4 v[226:227], off
	s_waitcnt vmcnt(8)
	s_waitcnt lgkmcnt(0)
	s_barrier
	s_setprio 1
	s_waitcnt lgkmcnt(0)
	v_mfma_f32_16x16x32_bf16 v[124:127], v[152:155], v[188:191], v[124:127]
	v_mfma_f32_16x16x32_bf16 v[116:119], v[160:163], v[188:191], v[116:119]
	v_mfma_f32_16x16x32_bf16 v[108:111], v[152:155], v[196:199], v[108:111]
	v_mfma_f32_16x16x32_bf16 v[100:103], v[160:163], v[196:199], v[100:103]
	v_mfma_f32_16x16x32_bf16 v[92:95], v[152:155], v[204:207], v[92:95]
	v_mfma_f32_16x16x32_bf16 v[84:87], v[160:163], v[204:207], v[84:87]
	v_mfma_f32_16x16x32_bf16 v[76:79], v[152:155], v[212:215], v[76:79]
	v_mfma_f32_16x16x32_bf16 v[68:71], v[160:163], v[212:215], v[68:71]
	v_mfma_f32_16x16x32_bf16 v[124:127], v[156:159], v[192:195], v[124:127]
	v_mfma_f32_16x16x32_bf16 v[116:119], v[168:171], v[192:195], v[116:119]
	v_mfma_f32_16x16x32_bf16 v[108:111], v[156:159], v[200:203], v[108:111]
	v_mfma_f32_16x16x32_bf16 v[100:103], v[168:171], v[200:203], v[100:103]
	v_mfma_f32_16x16x32_bf16 v[92:95], v[156:159], v[208:211], v[92:95]
	v_mfma_f32_16x16x32_bf16 v[84:87], v[168:171], v[208:211], v[84:87]
	v_mfma_f32_16x16x32_bf16 v[76:79], v[156:159], v[216:219], v[76:79]
	v_mfma_f32_16x16x32_bf16 v[68:71], v[168:171], v[216:219], v[68:71]
	s_setprio 0
	s_setprio 1
	v_mfma_f32_16x16x32_bf16 v[120:123], v[172:175], v[188:191], v[120:123]
	v_mfma_f32_16x16x32_bf16 v[112:115], v[180:183], v[188:191], v[112:115]
	v_mfma_f32_16x16x32_bf16 v[104:107], v[172:175], v[196:199], v[104:107]
	v_mfma_f32_16x16x32_bf16 v[96:99], v[180:183], v[196:199], v[96:99]
	v_mfma_f32_16x16x32_bf16 v[88:91], v[172:175], v[204:207], v[88:91]
	v_mfma_f32_16x16x32_bf16 v[80:83], v[180:183], v[204:207], v[80:83]
	v_mfma_f32_16x16x32_bf16 v[72:75], v[172:175], v[212:215], v[72:75]
	v_mfma_f32_16x16x32_bf16 v[64:67], v[180:183], v[212:215], v[64:67]
	v_mfma_f32_16x16x32_bf16 v[120:123], v[176:179], v[192:195], v[120:123]
	v_mfma_f32_16x16x32_bf16 v[112:115], v[184:187], v[192:195], v[112:115]
	v_mfma_f32_16x16x32_bf16 v[104:107], v[176:179], v[200:203], v[104:107]
	v_mfma_f32_16x16x32_bf16 v[96:99], v[184:187], v[200:203], v[96:99]
	v_mfma_f32_16x16x32_bf16 v[88:91], v[176:179], v[208:211], v[88:91]
	v_mfma_f32_16x16x32_bf16 v[80:83], v[184:187], v[208:211], v[80:83]
	v_mfma_f32_16x16x32_bf16 v[72:75], v[176:179], v[216:219], v[72:75]
	v_mfma_f32_16x16x32_bf16 v[64:67], v[184:187], v[216:219], v[64:67]
	s_setprio 0
	s_barrier
; #define PG8_STAGE(bufoff, gbase, voff) do { _Pragma("unroll") for (int _i = 0; _i < 2; ++_i) \
;         __builtin_amdgcn_global_load_lds((const unsigned*)((const char*)(gbase) + (voff)[_i]), (LAS unsigned*)(lds + (bufoff) + ldsw + _i * 8192), 16, 0, 0); } while (0)
; #define PG8_LDA(dst, b, h) do { _Pragma("unroll") for (int m = 0; m < 4; ++m) _Pragma("unroll") for (int k = 0; k < 2; ++k) dst[m][k] = *(const LAS bf16x8*)(lds + PG8_SA(b, h) + aoff + m * 2048 + k * 1024); } while (0)
; #define PG8_MMA(ai, bj, At, Bt) do { __builtin_amdgcn_s_setprio(1); _Pragma("unroll") for (int m = 0; m < 4; ++m) _Pragma("unroll") for (int n = 0; n < 2; ++n) _Pragma("unroll") for (int k = 0; k < 2; ++k) \
;         acc[ai][bj][m][n] = __builtin_amdgcn_mfma_f32_16x16x32_bf16(Bt[n][k], At[m][k], acc[ai][bj][m][n], 0, 0, 0); __builtin_amdgcn_s_setprio(0); } while (0)
; #define PG8_WAIT_V(n) asm volatile("s_waitcnt vmcnt(" #n ")" ::: "memory")
; #define PG8_WAIT_L(n) asm volatile("s_waitcnt lgkmcnt(" #n ")" ::: "memory")
; #define PG8_BAR __builtin_amdgcn_s_barrier()
; #define PG8_SCHED __builtin_amdgcn_sched_barrier(0)
; template <class Epi, class Sched>
; __device__ __forceinline__ void gemm_phase(LAS unsigned char* lds, const Gemm g, const Sched& S, const Epi& E, int wid) {
;     ...
;             PG8_LDA(At, 1, 1); PG8_STAGE(PG8_SB(1, 0), b3, voffB); PG8_STAGE(PG8_SB(1, 1), b3 + hstep, voffB); PG8_STAGE(PG8_SA(1, 0), a3, voffA);
;             PG8_WAIT_V(8); PG8_WAIT_L(0); PG8_BAR; PG8_MMA(1, 0, At, B0); PG8_MMA(1, 1, At, B1); PG8_BAR; PG8_SCHED;
;         }
	s_add_i32 s30, s53, s75
	v_lshl_add_u64 v[164:165], v[164:165], 0, s[14:15]
	s_mov_b32 m0, s30
	ds_read_b128 v[188:191], v150 offset:49152
	ds_read_b128 v[192:195], v150 offset:50176
	ds_read_b128 v[196:199], v150 offset:51200
	ds_read_b128 v[200:203], v150 offset:52224
	ds_read_b128 v[204:207], v150 offset:53248
	ds_read_b128 v[208:211], v150 offset:54272
	ds_read_b128 v[212:215], v150 offset:55296
	ds_read_b128 v[216:219], v150 offset:56320
	global_load_lds_dwordx4 v[164:165], off
	s_add_i32 m0, s30, 0x2000
	s_add_u32 s4, s4, 0x40080
	v_lshl_add_u64 v[164:165], v[220:221], 0, s[14:15]
	s_addc_u32 s5, s5, 0
	s_add_i32 s30, s54, s75
	global_load_lds_dwordx4 v[164:165], off
	v_lshl_add_u64 v[164:165], s[4:5], 0, v[130:131]
	s_mov_b32 m0, s30
	s_nop 0
	global_load_lds_dwordx4 v[164:165], off
	v_lshl_add_u64 v[164:165], s[4:5], 0, v[134:135]
	s_add_i32 m0, s30, 0x2000
	s_nop 0
	global_load_lds_dwordx4 v[164:165], off
	v_lshl_add_u64 v[164:165], v[222:223], 0, s[14:15]
	s_mov_b32 m0, s39
	s_nop 0
	global_load_lds_dwordx4 v[164:165], off
	v_lshl_add_u64 v[164:165], v[224:225], 0, s[14:15]
	s_mov_b32 m0, s40
	s_nop 0
	global_load_lds_dwordx4 v[164:165], off
	s_waitcnt vmcnt(8)
	s_waitcnt lgkmcnt(0)
	s_barrier
	s_setprio 1
	s_waitcnt lgkmcnt(0)
	v_mfma_f32_16x16x32_bf16 v[60:63], v[152:155], v[188:191], v[60:63]
	v_mfma_f32_16x16x32_bf16 v[52:55], v[160:163], v[188:191], v[52:55]
	v_mfma_f32_16x16x32_bf16 v[44:47], v[152:155], v[196:199], v[44:47]
	v_mfma_f32_16x16x32_bf16 v[36:39], v[160:163], v[196:199], v[36:39]
	v_mfma_f32_16x16x32_bf16 v[28:31], v[152:155], v[204:207], v[28:31]
	v_mfma_f32_16x16x32_bf16 v[20:23], v[160:163], v[204:207], v[20:23]
	v_mfma_f32_16x16x32_bf16 v[12:15], v[152:155], v[212:215], v[12:15]
	v_mfma_f32_16x16x32_bf16 v[4:7], v[160:163], v[212:215], v[4:7]
	v_mfma_f32_16x16x32_bf16 v[60:63], v[156:159], v[192:195], v[60:63]
	v_mfma_f32_16x16x32_bf16 v[52:55], v[168:171], v[192:195], v[52:55]
	v_mfma_f32_16x16x32_bf16 v[44:47], v[156:159], v[200:203], v[44:47]
	v_mfma_f32_16x16x32_bf16 v[36:39], v[168:171], v[200:203], v[36:39]
	v_mfma_f32_16x16x32_bf16 v[28:31], v[156:159], v[208:211], v[28:31]
	v_mfma_f32_16x16x32_bf16 v[20:23], v[168:171], v[208:211], v[20:23]
	v_mfma_f32_16x16x32_bf16 v[12:15], v[156:159], v[216:219], v[12:15]
	v_mfma_f32_16x16x32_bf16 v[4:7], v[168:171], v[216:219], v[4:7]
	s_setprio 0
	s_setprio 1
	v_mfma_f32_16x16x32_bf16 v[56:59], v[172:175], v[188:191], v[56:59]
	v_mfma_f32_16x16x32_bf16 v[48:51], v[180:183], v[188:191], v[48:51]
	v_mfma_f32_16x16x32_bf16 v[40:43], v[172:175], v[196:199], v[40:43]
	v_mfma_f32_16x16x32_bf16 v[32:35], v[180:183], v[196:199], v[32:35]
	v_mfma_f32_16x16x32_bf16 v[24:27], v[172:175], v[204:207], v[24:27]
	v_mfma_f32_16x16x32_bf16 v[16:19], v[180:183], v[204:207], v[16:19]
	v_mfma_f32_16x16x32_bf16 v[8:11], v[172:175], v[212:215], v[8:11]
	v_mfma_f32_16x16x32_bf16 v[0:3], v[180:183], v[212:215], v[0:3]
	v_mfma_f32_16x16x32_bf16 v[56:59], v[176:179], v[192:195], v[56:59]
	v_mfma_f32_16x16x32_bf16 v[48:51], v[184:187], v[192:195], v[48:51]
	v_mfma_f32_16x16x32_bf16 v[40:43], v[176:179], v[200:203], v[40:43]
	v_mfma_f32_16x16x32_bf16 v[32:35], v[184:187], v[200:203], v[32:35]
	v_mfma_f32_16x16x32_bf16 v[24:27], v[176:179], v[208:211], v[24:27]
	v_mfma_f32_16x16x32_bf16 v[16:19], v[184:187], v[208:211], v[16:19]
	v_mfma_f32_16x16x32_bf16 v[8:11], v[176:179], v[216:219], v[8:11]
	v_mfma_f32_16x16x32_bf16 v[0:3], v[184:187], v[216:219], v[0:3]
	s_setprio 0
	s_add_i32 s52, s52, 2
	s_add_u32 s28, s28, 0x100
	s_addc_u32 s29, s29, 0
	s_add_u32 s50, s50, 0x100
	s_addc_u32 s51, s51, 0
	s_cmp_gt_u32 s52, 13
	s_barrier
	s_cbranch_scc0 .LBB0_2203
	s_and_b64 vcc, exec, s[16:17]
	s_cbranch_vccz .LBB0_2206
	s_barrier

; #define PG8_STAGE(bufoff, gbase, voff) do { _Pragma("unroll") for (int _i = 0; _i < 2; ++_i) \
;         __builtin_amdgcn_global_load_lds((const unsigned*)((const char*)(gbase) + (voff)[_i]), (LAS unsigned*)(lds + (bufoff) + ldsw + _i * 8192), 16, 0, 0); } while (0)
; #define PG8_LDA(dst, b, h) do { _Pragma("unroll") for (int m = 0; m < 4; ++m) _Pragma("unroll") for (int k = 0; k < 2; ++k) dst[m][k] = *(const LAS bf16x8*)(lds + PG8_SA(b, h) + aoff + m * 2048 + k * 1024); } while (0)
; #define PG8_LDB(dst, b, h) do { _Pragma("unroll") for (int n = 0; n < 2; ++n) _Pragma("unroll") for (int k = 0; k < 2; ++k) dst[n][k] = *(const LAS bf16x8*)(lds + PG8_SB(b, h) + boff + n * 2048 + k * 1024); } while (0)
; #define PG8_MMA(ai, bj, At, Bt) do { __builtin_amdgcn_s_setprio(1); _Pragma("unroll") for (int m = 0; m < 4; ++m) _Pragma("unroll") for (int n = 0; n < 2; ++n) _Pragma("unroll") for (int k = 0; k < 2; ++k) \
;         acc[ai][bj][m][n] = __builtin_amdgcn_mfma_f32_16x16x32_bf16(Bt[n][k], At[m][k], acc[ai][bj][m][n], 0, 0, 0); __builtin_amdgcn_s_setprio(0); } while (0)
; #define PG8_WAIT_V(n) asm volatile("s_waitcnt vmcnt(" #n ")" ::: "memory")
; #define PG8_WAIT_L(n) asm volatile("s_waitcnt lgkmcnt(" #n ")" ::: "memory")
; #define PG8_BAR __builtin_amdgcn_s_barrier()
; #define PG8_SCHED __builtin_amdgcn_sched_barrier(0)
; template <class Epi, class Sched>
; __device__ __forceinline__ void gemm_phase(LAS unsigned char* lds, const Gemm g, const Sched& S, const Epi& E, int wid) {
;     ...
;             PG8_LDB(B0, 0, 0); PG8_LDB(B1, 0, 1); PG8_SCHED; PG8_LDA(At, 0, 0); PG8_STAGE(PG8_SA(1, 1), a1 + hstep, voffA);
;             PG8_WAIT_V(8); PG8_WAIT_L(0); PG8_BAR; PG8_MMA(0, 0, At, B0); PG8_MMA(0, 1, At, B1); PG8_BAR; PG8_SCHED;
;             PG8_LDA(At, 0, 1); PG8_STAGE(PG8_SB(0, 0), b2, voffB); PG8_STAGE(PG8_SB(0, 1), b2 + hstep, voffB); PG8_STAGE(PG8_SA(0, 0), a2, voffA);
;             PG8_WAIT_V(8); PG8_WAIT_L(0); PG8_BAR; PG8_MMA(1, 0, At, B0); PG8_MMA(1, 1, At, B1); PG8_BAR; PG8_SCHED;
.LBB0_2323:
	ds_read_b128 v[144:147], v163
	ds_read_b128 v[148:151], v163 offset:1024
	ds_read_b128 v[152:155], v163 offset:2048
	ds_read_b128 v[156:159], v163 offset:3072
	ds_read_b128 v[170:173], v164
	ds_read_b128 v[174:177], v164 offset:1024
	ds_read_b128 v[178:181], v164 offset:2048
	ds_read_b128 v[182:185], v164 offset:3072
	s_add_u32 s4, s36, 0x100
	s_addc_u32 s5, s37, 0
	s_cmp_eq_u32 s64, 40
	s_cselect_b32 s39, s27, s5
	s_cselect_b32 s38, s26, s4
	s_cselect_b32 s11, s29, s35
	s_cselect_b32 s10, s28, s31
	v_lshl_add_u64 v[218:219], s[36:37], 0, v[136:137]
	s_add_i32 m0, s41, 0xc000
	ds_read_b128 v[186:189], v165
	ds_read_b128 v[190:193], v165 offset:1024
	ds_read_b128 v[194:197], v165 offset:2048
	ds_read_b128 v[198:201], v165 offset:3072
	ds_read_b128 v[202:205], v165 offset:4096
	ds_read_b128 v[206:209], v165 offset:5120
	ds_read_b128 v[210:213], v165 offset:6144
	ds_read_b128 v[214:217], v165 offset:7168
	global_load_lds_dwordx4 v[218:219], off
	v_lshl_add_u64 v[218:219], s[36:37], 0, v[138:139]
	s_add_i32 m0, s41, 0xe000
	s_nop 0
	global_load_lds_dwordx4 v[218:219], off
	s_waitcnt vmcnt(8)
	s_waitcnt lgkmcnt(0)
	s_barrier
	s_setprio 1
	s_waitcnt lgkmcnt(0)
	v_mfma_f32_16x16x32_bf16 v[124:127], v[144:147], v[186:189], v[124:127]
	v_mfma_f32_16x16x32_bf16 v[120:123], v[152:155], v[186:189], v[120:123]
	v_mfma_f32_16x16x32_bf16 v[108:111], v[144:147], v[194:197], v[108:111]
	v_mfma_f32_16x16x32_bf16 v[104:107], v[152:155], v[194:197], v[104:107]
	v_mfma_f32_16x16x32_bf16 v[92:95], v[144:147], v[202:205], v[92:95]
	v_mfma_f32_16x16x32_bf16 v[88:91], v[152:155], v[202:205], v[88:91]
	v_mfma_f32_16x16x32_bf16 v[76:79], v[144:147], v[210:213], v[76:79]
	v_mfma_f32_16x16x32_bf16 v[72:75], v[152:155], v[210:213], v[72:75]
	v_mfma_f32_16x16x32_bf16 v[124:127], v[148:151], v[190:193], v[124:127]
	v_mfma_f32_16x16x32_bf16 v[120:123], v[156:159], v[190:193], v[120:123]
	v_mfma_f32_16x16x32_bf16 v[108:111], v[148:151], v[198:201], v[108:111]
	v_mfma_f32_16x16x32_bf16 v[104:107], v[156:159], v[198:201], v[104:107]
	v_mfma_f32_16x16x32_bf16 v[92:95], v[148:151], v[206:209], v[92:95]
	v_mfma_f32_16x16x32_bf16 v[88:91], v[156:159], v[206:209], v[88:91]
	v_mfma_f32_16x16x32_bf16 v[76:79], v[148:151], v[214:217], v[76:79]
	v_mfma_f32_16x16x32_bf16 v[72:75], v[156:159], v[214:217], v[72:75]
	s_setprio 0
	s_setprio 1
	v_mfma_f32_16x16x32_bf16 v[116:119], v[170:173], v[186:189], v[116:119]
	v_mfma_f32_16x16x32_bf16 v[112:115], v[178:181], v[186:189], v[112:115]
	v_mfma_f32_16x16x32_bf16 v[100:103], v[170:173], v[194:197], v[100:103]
	v_mfma_f32_16x16x32_bf16 v[96:99], v[178:181], v[194:197], v[96:99]
	v_mfma_f32_16x16x32_bf16 v[84:87], v[170:173], v[202:205], v[84:87]
	v_mfma_f32_16x16x32_bf16 v[80:83], v[178:181], v[202:205], v[80:83]
	v_mfma_f32_16x16x32_bf16 v[68:71], v[170:173], v[210:213], v[68:71]
	v_mfma_f32_16x16x32_bf16 v[64:67], v[178:181], v[210:213], v[64:67]
	v_mfma_f32_16x16x32_bf16 v[116:119], v[174:177], v[190:193], v[116:119]
	v_mfma_f32_16x16x32_bf16 v[112:115], v[182:185], v[190:193], v[112:115]
	v_mfma_f32_16x16x32_bf16 v[100:103], v[174:177], v[198:201], v[100:103]
	v_mfma_f32_16x16x32_bf16 v[96:99], v[182:185], v[198:201], v[96:99]
	v_mfma_f32_16x16x32_bf16 v[84:87], v[174:177], v[206:209], v[84:87]
	v_mfma_f32_16x16x32_bf16 v[80:83], v[182:185], v[206:209], v[80:83]
	v_mfma_f32_16x16x32_bf16 v[68:71], v[174:177], v[214:217], v[68:71]
	v_mfma_f32_16x16x32_bf16 v[64:67], v[182:185], v[214:217], v[64:67]
	s_setprio 0
	s_barrier
	s_add_i32 s36, s56, s75
	v_lshl_add_u64 v[218:219], s[10:11], 0, v[130:131]
	s_mov_b32 m0, s36
	ds_read_b128 v[186:189], v165 offset:16384
	ds_read_b128 v[190:193], v165 offset:17408
	ds_read_b128 v[194:197], v165 offset:18432
	ds_read_b128 v[198:201], v165 offset:19456
	ds_read_b128 v[202:205], v165 offset:20480
	ds_read_b128 v[206:209], v165 offset:21504
	ds_read_b128 v[210:213], v165 offset:22528
	ds_read_b128 v[214:217], v165 offset:23552
	global_load_lds_dwordx4 v[218:219], off
	s_add_i32 m0, s36, 0x2000
	s_add_u32 s36, s10, 0xb0000
	v_lshl_add_u64 v[220:221], s[10:11], 0, v[134:135]
	s_addc_u32 s37, s11, 0
	s_add_i32 s65, s57, s75
	global_load_lds_dwordx4 v[220:221], off
	v_lshl_add_u64 v[222:223], s[36:37], 0, v[130:131]
	s_mov_b32 m0, s65
	v_lshl_add_u64 v[224:225], s[38:39], 0, v[132:133]
	global_load_lds_dwordx4 v[222:223], off
	v_lshl_add_u64 v[222:223], s[36:37], 0, v[134:135]
	s_add_i32 m0, s65, 0x2000
	s_nop 0
	global_load_lds_dwordx4 v[222:223], off
	v_lshl_add_u64 v[222:223], s[38:39], 0, v[128:129]
	s_mov_b32 m0, s41
	s_nop 0
	global_load_lds_dwordx4 v[222:223], off
	s_mov_b32 m0, s42
	s_nop 0
	global_load_lds_dwordx4 v[224:225], off
	s_waitcnt vmcnt(8)
	s_waitcnt lgkmcnt(0)
	s_barrier
; #define PG8_STAGE(bufoff, gbase, voff) do { _Pragma("unroll") for (int _i = 0; _i < 2; ++_i) \
;         __builtin_amdgcn_global_load_lds((const unsigned*)((const char*)(gbase) + (voff)[_i]), (LAS unsigned*)(lds + (bufoff) + ldsw + _i * 8192), 16, 0, 0); } while (0)
; #define PG8_LDA(dst, b, h) do { _Pragma("unroll") for (int m = 0; m < 4; ++m) _Pragma("unroll") for (int k = 0; k < 2; ++k) dst[m][k] = *(const LAS bf16x8*)(lds + PG8_SA(b, h) + aoff + m * 2048 + k * 1024); } while (0)
; #define PG8_LDB(dst, b, h) do { _Pragma("unroll") for (int n = 0; n < 2; ++n) _Pragma("unroll") for (int k = 0; k < 2; ++k) dst[n][k] = *(const LAS bf16x8*)(lds + PG8_SB(b, h) + boff + n * 2048 + k * 1024); } while (0)
; #define PG8_WAIT_V(n) asm volatile("s_waitcnt vmcnt(" #n ")" ::: "memory")
; #define PG8_BAR __builtin_amdgcn_s_barrier()
; template <class Epi, class Sched>
; __device__ __forceinline__ void gemm_phase(LAS unsigned char* lds, const Gemm g, const Sched& S, const Epi& E, int wid) {
;     ...
;         for (int t = 0; t < nt; t += 2) {
;             const bool last = (t == nt - 2);
;             const char* a1 = cA + (size_t)(t + 1) * kstep;
;             const char* a2 = last ? nA : cA + (size_t)(t + 2) * kstep; const char* b2 = last ? nB : cB + (size_t)(t + 2) * kstep;
;             const char* a3 = a2 + kstep; const char* b3 = b2 + kstep;
;             PG8_LDB(B0, 0, 0); PG8_LDB(B1, 0, 1); PG8_SCHED; PG8_LDA(At, 0, 0); PG8_STAGE(PG8_SA(1, 1), a1 + hstep, voffA);
;             PG8_WAIT_V(8); PG8_WAIT_L(0); PG8_BAR; PG8_MMA(0, 0, At, B0); PG8_MMA(0, 1, At, B1); PG8_BAR; PG8_SCHED;
;             PG8_LDA(At, 0, 1); PG8_STAGE(PG8_SB(0, 0), b2, voffB); PG8_STAGE(PG8_SB(0, 1), b2 + hstep, voffB); PG8_STAGE(PG8_SA(0, 0), a2, voffA);
;             PG8_WAIT_V(8); PG8_WAIT_L(0); PG8_BAR; PG8_MMA(1, 0, At, B0); PG8_MMA(1, 1, At, B1); PG8_BAR; PG8_SCHED;
;             PG8_LDB(B0, 1, 0); PG8_LDB(B1, 1, 1); PG8_SCHED; PG8_LDA(At, 1, 0); PG8_STAGE(PG8_SA(0, 1), a2 + hstep, voffA);
;             PG8_WAIT_V(8); PG8_WAIT_L(0); PG8_BAR; PG8_MMA(0, 0, At, B0); PG8_MMA(0, 1, At, B1); PG8_BAR; PG8_SCHED;
;             PG8_LDA(At, 1, 1); PG8_STAGE(PG8_SB(1, 0), b3, voffB); PG8_STAGE(PG8_SB(1, 1), b3 + hstep, voffB); PG8_STAGE(PG8_SA(1, 0), a3, voffA);
;             PG8_WAIT_V(8); PG8_WAIT_L(0); PG8_BAR; PG8_MMA(1, 0, At, B0); PG8_MMA(1, 1, At, B1); PG8_BAR; PG8_SCHED;
	s_setprio 1
	s_waitcnt lgkmcnt(0)
	v_mfma_f32_16x16x32_bf16 v[60:63], v[144:147], v[186:189], v[60:63]
	v_mfma_f32_16x16x32_bf16 v[56:59], v[152:155], v[186:189], v[56:59]
	v_mfma_f32_16x16x32_bf16 v[44:47], v[144:147], v[194:197], v[44:47]
	v_mfma_f32_16x16x32_bf16 v[40:43], v[152:155], v[194:197], v[40:43]
	v_mfma_f32_16x16x32_bf16 v[28:31], v[144:147], v[202:205], v[28:31]
	v_mfma_f32_16x16x32_bf16 v[24:27], v[152:155], v[202:205], v[24:27]
	v_mfma_f32_16x16x32_bf16 v[12:15], v[144:147], v[210:213], v[12:15]
	v_mfma_f32_16x16x32_bf16 v[8:11], v[152:155], v[210:213], v[8:11]
	v_mfma_f32_16x16x32_bf16 v[60:63], v[148:151], v[190:193], v[60:63]
	v_mfma_f32_16x16x32_bf16 v[56:59], v[156:159], v[190:193], v[56:59]
	v_mfma_f32_16x16x32_bf16 v[44:47], v[148:151], v[198:201], v[44:47]
	v_mfma_f32_16x16x32_bf16 v[40:43], v[156:159], v[198:201], v[40:43]
	v_mfma_f32_16x16x32_bf16 v[28:31], v[148:151], v[206:209], v[28:31]
	v_mfma_f32_16x16x32_bf16 v[24:27], v[156:159], v[206:209], v[24:27]
	v_mfma_f32_16x16x32_bf16 v[12:15], v[148:151], v[214:217], v[12:15]
	v_mfma_f32_16x16x32_bf16 v[8:11], v[156:159], v[214:217], v[8:11]
	s_setprio 0
	s_setprio 1
	v_mfma_f32_16x16x32_bf16 v[52:55], v[170:173], v[186:189], v[52:55]
	v_mfma_f32_16x16x32_bf16 v[48:51], v[178:181], v[186:189], v[48:51]
	v_mfma_f32_16x16x32_bf16 v[36:39], v[170:173], v[194:197], v[36:39]
	v_mfma_f32_16x16x32_bf16 v[32:35], v[178:181], v[194:197], v[32:35]
	v_mfma_f32_16x16x32_bf16 v[20:23], v[170:173], v[202:205], v[20:23]
	v_mfma_f32_16x16x32_bf16 v[16:19], v[178:181], v[202:205], v[16:19]
	v_mfma_f32_16x16x32_bf16 v[4:7], v[170:173], v[210:213], v[4:7]
	v_mfma_f32_16x16x32_bf16 v[0:3], v[178:181], v[210:213], v[0:3]
	v_mfma_f32_16x16x32_bf16 v[52:55], v[174:177], v[190:193], v[52:55]
	v_mfma_f32_16x16x32_bf16 v[48:51], v[182:185], v[190:193], v[48:51]
	v_mfma_f32_16x16x32_bf16 v[36:39], v[174:177], v[198:201], v[36:39]
	v_mfma_f32_16x16x32_bf16 v[32:35], v[182:185], v[198:201], v[32:35]
	v_mfma_f32_16x16x32_bf16 v[20:23], v[174:177], v[206:209], v[20:23]
	v_mfma_f32_16x16x32_bf16 v[16:19], v[182:185], v[206:209], v[16:19]
	v_mfma_f32_16x16x32_bf16 v[4:7], v[174:177], v[214:217], v[4:7]
	v_mfma_f32_16x16x32_bf16 v[0:3], v[182:185], v[214:217], v[0:3]
	s_setprio 0
	s_barrier
	s_add_i32 s65, 0, 0x18000
	s_add_i32 s66, 0, 0x1c000
	v_add_u32_e32 v156, s65, v162
	v_add_u32_e32 v169, s66, v162
	ds_read_b128 v[144:147], v156
	ds_read_b128 v[148:151], v156 offset:1024
	ds_read_b128 v[152:155], v156 offset:2048
	ds_read_b128 v[156:159], v156 offset:3072
	ds_read_b128 v[170:173], v169
	ds_read_b128 v[174:177], v169 offset:1024
	ds_read_b128 v[178:181], v169 offset:2048
	ds_read_b128 v[182:185], v169 offset:3072
	s_add_u32 s36, s38, 0xb0000
	s_addc_u32 s37, s39, 0
	s_mov_b32 m0, s43
	v_lshl_add_u64 v[226:227], s[36:37], 0, v[128:129]
	ds_read_b128 v[186:189], v165 offset:32768
	ds_read_b128 v[190:193], v165 offset:33792
	ds_read_b128 v[194:197], v165 offset:34816
	ds_read_b128 v[198:201], v165 offset:35840
	ds_read_b128 v[202:205], v165 offset:36864
	ds_read_b128 v[206:209], v165 offset:37888
	ds_read_b128 v[210:213], v165 offset:38912
	ds_read_b128 v[214:217], v165 offset:39936
	global_load_lds_dwordx4 v[226:227], off
	v_lshl_add_u64 v[226:227], s[36:37], 0, v[132:133]
	s_mov_b32 m0, s44
	s_nop 0
	global_load_lds_dwordx4 v[226:227], off
	s_waitcnt vmcnt(8)
	s_waitcnt lgkmcnt(0)
	s_barrier
	s_setprio 1
	s_waitcnt lgkmcnt(0)
	v_mfma_f32_16x16x32_bf16 v[124:127], v[144:147], v[186:189], v[124:127]
	v_mfma_f32_16x16x32_bf16 v[120:123], v[152:155], v[186:189], v[120:123]
	v_mfma_f32_16x16x32_bf16 v[108:111], v[144:147], v[194:197], v[108:111]
	v_mfma_f32_16x16x32_bf16 v[104:107], v[152:155], v[194:197], v[104:107]
	v_mfma_f32_16x16x32_bf16 v[92:95], v[144:147], v[202:205], v[92:95]
	v_mfma_f32_16x16x32_bf16 v[88:91], v[152:155], v[202:205], v[88:91]
	v_mfma_f32_16x16x32_bf16 v[76:79], v[144:147], v[210:213], v[76:79]
	v_mfma_f32_16x16x32_bf16 v[72:75], v[152:155], v[210:213], v[72:75]
	v_mfma_f32_16x16x32_bf16 v[124:127], v[148:151], v[190:193], v[124:127]
	v_mfma_f32_16x16x32_bf16 v[120:123], v[156:159], v[190:193], v[120:123]
	v_mfma_f32_16x16x32_bf16 v[108:111], v[148:151], v[198:201], v[108:111]
	v_mfma_f32_16x16x32_bf16 v[104:107], v[156:159], v[198:201], v[104:107]
	v_mfma_f32_16x16x32_bf16 v[92:95], v[148:151], v[206:209], v[92:95]
	v_mfma_f32_16x16x32_bf16 v[88:91], v[156:159], v[206:209], v[88:91]
	v_mfma_f32_16x16x32_bf16 v[76:79], v[148:151], v[214:217], v[76:79]
	v_mfma_f32_16x16x32_bf16 v[72:75], v[156:159], v[214:217], v[72:75]
	s_setprio 0
	s_setprio 1
	v_mfma_f32_16x16x32_bf16 v[116:119], v[170:173], v[186:189], v[116:119]
	v_mfma_f32_16x16x32_bf16 v[112:115], v[178:181], v[186:189], v[112:115]
	v_mfma_f32_16x16x32_bf16 v[100:103], v[170:173], v[194:197], v[100:103]
	v_mfma_f32_16x16x32_bf16 v[96:99], v[178:181], v[194:197], v[96:99]
	v_mfma_f32_16x16x32_bf16 v[84:87], v[170:173], v[202:205], v[84:87]
	v_mfma_f32_16x16x32_bf16 v[80:83], v[178:181], v[202:205], v[80:83]
	v_mfma_f32_16x16x32_bf16 v[68:71], v[170:173], v[210:213], v[68:71]
	v_mfma_f32_16x16x32_bf16 v[64:67], v[178:181], v[210:213], v[64:67]
	v_mfma_f32_16x16x32_bf16 v[116:119], v[174:177], v[190:193], v[116:119]
	v_mfma_f32_16x16x32_bf16 v[112:115], v[182:185], v[190:193], v[112:115]
	v_mfma_f32_16x16x32_bf16 v[100:103], v[174:177], v[198:201], v[100:103]
	v_mfma_f32_16x16x32_bf16 v[96:99], v[182:185], v[198:201], v[96:99]
	v_mfma_f32_16x16x32_bf16 v[84:87], v[174:177], v[206:209], v[84:87]
	v_mfma_f32_16x16x32_bf16 v[80:83], v[182:185], v[206:209], v[80:83]
	v_mfma_f32_16x16x32_bf16 v[68:71], v[174:177], v[214:217], v[68:71]
	v_mfma_f32_16x16x32_bf16 v[64:67], v[182:185], v[214:217], v[64:67]
	s_setprio 0
	s_barrier
; #define PG8_STAGE(bufoff, gbase, voff) do { _Pragma("unroll") for (int _i = 0; _i < 2; ++_i) \
;         __builtin_amdgcn_global_load_lds((const unsigned*)((const char*)(gbase) + (voff)[_i]), (LAS unsigned*)(lds + (bufoff) + ldsw + _i * 8192), 16, 0, 0); } while (0)
; #define PG8_LDA(dst, b, h) do { _Pragma("unroll") for (int m = 0; m < 4; ++m) _Pragma("unroll") for (int k = 0; k < 2; ++k) dst[m][k] = *(const LAS bf16x8*)(lds + PG8_SA(b, h) + aoff + m * 2048 + k * 1024); } while (0)
; #define PG8_LDB(dst, b, h) do { _Pragma("unroll") for (int n = 0; n < 2; ++n) _Pragma("unroll") for (int k = 0; k < 2; ++k) dst[n][k] = *(const LAS bf16x8*)(lds + PG8_SB(b, h) + boff + n * 2048 + k * 1024); } while (0)
; #define PG8_WAIT_V(n) asm volatile("s_waitcnt vmcnt(" #n ")" ::: "memory")
; #define PG8_BAR __builtin_amdgcn_s_barrier()
; template <class Epi, class Sched>
; __device__ __forceinline__ void gemm_phase(LAS unsigned char* lds, const Gemm g, const Sched& S, const Epi& E, int wid) {
;     ...
;         for (int t = 0; t < nt; t += 2) {
;             const bool last = (t == nt - 2);
;             const char* a1 = cA + (size_t)(t + 1) * kstep;
;             const char* a2 = last ? nA : cA + (size_t)(t + 2) * kstep; const char* b2 = last ? nB : cB + (size_t)(t + 2) * kstep;
;             const char* a3 = a2 + kstep; const char* b3 = b2 + kstep;
;             PG8_LDB(B0, 0, 0); PG8_LDB(B1, 0, 1); PG8_SCHED; PG8_LDA(At, 0, 0); PG8_STAGE(PG8_SA(1, 1), a1 + hstep, voffA);
;             PG8_WAIT_V(8); PG8_WAIT_L(0); PG8_BAR; PG8_MMA(0, 0, At, B0); PG8_MMA(0, 1, At, B1); PG8_BAR; PG8_SCHED;
;             PG8_LDA(At, 0, 1); PG8_STAGE(PG8_SB(0, 0), b2, voffB); PG8_STAGE(PG8_SB(0, 1), b2 + hstep, voffB); PG8_STAGE(PG8_SA(0, 0), a2, voffA);
;             PG8_WAIT_V(8); PG8_WAIT_L(0); PG8_BAR; PG8_MMA(1, 0, At, B0); PG8_MMA(1, 1, At, B1); PG8_BAR; PG8_SCHED;
;             PG8_LDB(B0, 1, 0); PG8_LDB(B1, 1, 1); PG8_SCHED; PG8_LDA(At, 1, 0); PG8_STAGE(PG8_SA(0, 1), a2 + hstep, voffA);
;             PG8_WAIT_V(8); PG8_WAIT_L(0); PG8_BAR; PG8_MMA(0, 0, At, B0); PG8_MMA(0, 1, At, B1); PG8_BAR; PG8_SCHED;
;             PG8_LDA(At, 1, 1); PG8_STAGE(PG8_SB(1, 0), b3, voffB); PG8_STAGE(PG8_SB(1, 1), b3 + hstep, voffB); PG8_STAGE(PG8_SA(1, 0), a3, voffA);
;             PG8_WAIT_V(8); PG8_WAIT_L(0); PG8_BAR; PG8_MMA(1, 0, At, B0); PG8_MMA(1, 1, At, B1); PG8_BAR; PG8_SCHED;
;         }
	s_add_i32 s36, s65, s75
	v_lshl_add_u64 v[218:219], v[218:219], 0, s[22:23]
	s_mov_b32 m0, s36
	ds_read_b128 v[186:189], v165 offset:49152
	ds_read_b128 v[190:193], v165 offset:50176
	ds_read_b128 v[194:197], v165 offset:51200
	ds_read_b128 v[198:201], v165 offset:52224
	ds_read_b128 v[202:205], v165 offset:53248
	ds_read_b128 v[206:209], v165 offset:54272
	ds_read_b128 v[210:213], v165 offset:55296
	ds_read_b128 v[214:217], v165 offset:56320
	global_load_lds_dwordx4 v[218:219], off
	s_add_i32 m0, s36, 0x2000
	s_add_u32 s10, s10, 0xb0080
	v_lshl_add_u64 v[218:219], v[220:221], 0, s[22:23]
	s_addc_u32 s11, s11, 0
	s_add_i32 s36, s66, s75
	global_load_lds_dwordx4 v[218:219], off
	v_lshl_add_u64 v[218:219], s[10:11], 0, v[130:131]
	s_mov_b32 m0, s36
	s_nop 0
	global_load_lds_dwordx4 v[218:219], off
	v_lshl_add_u64 v[218:219], s[10:11], 0, v[134:135]
	s_add_i32 m0, s36, 0x2000
	s_nop 0
	global_load_lds_dwordx4 v[218:219], off
	v_lshl_add_u64 v[218:219], v[222:223], 0, s[22:23]
	s_mov_b32 m0, s48
	s_nop 0
	global_load_lds_dwordx4 v[218:219], off
	v_lshl_add_u64 v[218:219], v[224:225], 0, s[22:23]
	s_mov_b32 m0, s49
	s_nop 0
	global_load_lds_dwordx4 v[218:219], off
	s_waitcnt vmcnt(8)
	s_waitcnt lgkmcnt(0)
	s_barrier
	s_setprio 1
	s_waitcnt lgkmcnt(0)
	v_mfma_f32_16x16x32_bf16 v[60:63], v[144:147], v[186:189], v[60:63]
	v_mfma_f32_16x16x32_bf16 v[56:59], v[152:155], v[186:189], v[56:59]
	v_mfma_f32_16x16x32_bf16 v[44:47], v[144:147], v[194:197], v[44:47]
	v_mfma_f32_16x16x32_bf16 v[40:43], v[152:155], v[194:197], v[40:43]
	v_mfma_f32_16x16x32_bf16 v[28:31], v[144:147], v[202:205], v[28:31]
	v_mfma_f32_16x16x32_bf16 v[24:27], v[152:155], v[202:205], v[24:27]
	v_mfma_f32_16x16x32_bf16 v[12:15], v[144:147], v[210:213], v[12:15]
	v_mfma_f32_16x16x32_bf16 v[8:11], v[152:155], v[210:213], v[8:11]
	v_mfma_f32_16x16x32_bf16 v[60:63], v[148:151], v[190:193], v[60:63]
	v_mfma_f32_16x16x32_bf16 v[56:59], v[156:159], v[190:193], v[56:59]
	v_mfma_f32_16x16x32_bf16 v[44:47], v[148:151], v[198:201], v[44:47]
	v_mfma_f32_16x16x32_bf16 v[40:43], v[156:159], v[198:201], v[40:43]
	v_mfma_f32_16x16x32_bf16 v[28:31], v[148:151], v[206:209], v[28:31]
	v_mfma_f32_16x16x32_bf16 v[24:27], v[156:159], v[206:209], v[24:27]
	v_mfma_f32_16x16x32_bf16 v[12:15], v[148:151], v[214:217], v[12:15]
	v_mfma_f32_16x16x32_bf16 v[8:11], v[156:159], v[214:217], v[8:11]
	s_setprio 0
	s_setprio 1
	v_mfma_f32_16x16x32_bf16 v[52:55], v[170:173], v[186:189], v[52:55]
	v_mfma_f32_16x16x32_bf16 v[48:51], v[178:181], v[186:189], v[48:51]
	v_mfma_f32_16x16x32_bf16 v[36:39], v[170:173], v[194:197], v[36:39]
	v_mfma_f32_16x16x32_bf16 v[32:35], v[178:181], v[194:197], v[32:35]
	v_mfma_f32_16x16x32_bf16 v[20:23], v[170:173], v[202:205], v[20:23]
	v_mfma_f32_16x16x32_bf16 v[16:19], v[178:181], v[202:205], v[16:19]
	v_mfma_f32_16x16x32_bf16 v[4:7], v[170:173], v[210:213], v[4:7]
	v_mfma_f32_16x16x32_bf16 v[0:3], v[178:181], v[210:213], v[0:3]
	v_mfma_f32_16x16x32_bf16 v[52:55], v[174:177], v[190:193], v[52:55]
	v_mfma_f32_16x16x32_bf16 v[48:51], v[182:185], v[190:193], v[48:51]
	v_mfma_f32_16x16x32_bf16 v[36:39], v[174:177], v[198:201], v[36:39]
	v_mfma_f32_16x16x32_bf16 v[32:35], v[182:185], v[198:201], v[32:35]
	v_mfma_f32_16x16x32_bf16 v[20:23], v[174:177], v[206:209], v[20:23]
	v_mfma_f32_16x16x32_bf16 v[16:19], v[182:185], v[206:209], v[16:19]
	v_mfma_f32_16x16x32_bf16 v[4:7], v[174:177], v[214:217], v[4:7]
	v_mfma_f32_16x16x32_bf16 v[0:3], v[182:185], v[214:217], v[0:3]
	s_setprio 0
	s_add_i32 s64, s64, 2
	s_add_u32 s31, s31, 0x100
	s_addc_u32 s35, s35, 0
	s_cmp_gt_u32 s64, 41
	s_mov_b64 s[36:37], s[4:5]
	s_barrier
	s_cbranch_scc0 .LBB0_2323
	s_and_b64 vcc, exec, s[24:25]
	s_cbranch_vccz .LBB0_2326
	s_barrier
